# v46 plus: MLA V-fragment LDS prefetch, combine-phase gain vector loaded once per loop, gemm_bd A-tile prefetch loads moved into MFMA phase, norm_ple row loads issued together
# speedup vs baseline: 1.0273x; 1.0021x over previous
; #define MFMA32(a, b, c) __builtin_amdgcn_mfma_f32_32x32x16_bf16((a), (b), (c), 0, 0, 0)
; DI void gemm_main_bd(f32x16 (&acc)[4][2], const bf16_t* __restrict__ A, int lda, const bf16_t* __restrict__ Bf, int n0,
;                      int K, char* lds) {
;     ...
;   for (int k = 0; k < nsteps; ++k) {
;     const bf16_t* As = As0 + (k & 1) * (128 * 72);
;     bf16_t* Aw = As0 + ((k + 1) & 1) * (128 * 72);
; #pragma unroll
;     for (int ks = 0; ks < 4; ++ks) { bc[0][ks] = bn[0][ks]; bc[1][ks] = bn[1][ks]; }
;     if (k + 1 < nsteps) {
; #pragma unroll
;       for (int ks = 0; ks < 4; ++ks) {
;         bn[0][ks] = *(const bf16x8*)(Bb0 + (loff + 1024u * (unsigned)(4 * (k + 1) + ks)));
;         bn[1][ks] = *(const bf16x8*)(Bb1 + (loff + 1024u * (unsigned)(4 * (k + 1) + ks)));
;       }
; #pragma unroll
;       for (int i = 0; i < 4; ++i) *(u32x4*)(Aw + (lr + 32 * i) * 72 + lc) = ra[i];
;       if (k + 2 < nsteps) {
; #pragma unroll
;         for (int i = 0; i < 4; ++i) ra[i] = *(const u32x4*)(Ab + (aoff + astep * i + 128u * (unsigned)(k + 2)));
;       }
;     }
;     __builtin_amdgcn_s_setprio(1);
; #pragma unroll
;     for (int ks = 0; ks < 4; ++ks) {
;       bf16x8 af[4];
; #pragma unroll
;       for (int mi = 0; mi < 4; ++mi) af[mi] = *(const bf16x8*)(As + (32 * mi + l31) * 72 + 16 * ks + 8 * h2);
; #pragma unroll
;       for (int mi = 0; mi < 4; ++mi)
; #pragma unroll
;         for (int ni = 0; ni < 2; ++ni) acc[mi][ni] = MFMA32(bc[ni][ks], af[mi], acc[mi][ni]);
;     }
;     __builtin_amdgcn_s_setprio(0);
;     __syncthreads();
;   }
.LBB0_273:
	s_waitcnt vmcnt(4)
	v_mov_b64_e32 v[208:209], v[132:133]
	v_mov_b64_e32 v[206:207], v[130:131]
	v_lshl_add_u64 v[130:131], v[222:223], 0, s[44:45]
	s_mov_b32 s51, 0xb01000
	s_and_b32 s49, 1, s48
	s_add_i32 s48, s48, 1
	v_add_co_u32_e32 v132, vcc, s51, v130
	s_and_b32 s50, 1, s48
	s_nop 0
	v_addc_co_u32_e32 v133, vcc, 0, v131, vcc
	s_mov_b32 s51, 0xb2d000
	s_cmp_eq_u32 s49, 1
	v_add_co_u32_e32 v130, vcc, s51, v130
	s_cselect_b32 s49, 0x4800, 0
	s_cmp_eq_u32 s50, 1
	v_addc_co_u32_e32 v131, vcc, 0, v131, vcc
	s_cselect_b32 s50, 0x4800, 0
	global_load_dwordx4 v[198:201], v[132:133], off
	global_load_dwordx4 v[202:205], v[130:131], off
	global_load_dwordx4 v[194:197], v[132:133], off offset:1024
	global_load_dwordx4 v[190:193], v[130:131], off offset:1024
	global_load_dwordx4 v[182:185], v[132:133], off offset:2048
	global_load_dwordx4 v[186:189], v[130:131], off offset:2048
	global_load_dwordx4 v[178:181], v[132:133], off offset:3072
	s_nop 0
	global_load_dwordx4 v[130:133], v[130:131], off offset:3072
	v_add_u32_e32 v0, s50, v236
	s_waitcnt vmcnt(11)
	ds_write_b128 v0, v[134:137]
	s_waitcnt vmcnt(10)
	ds_write_b128 v0, v[138:141] offset:4608
	s_waitcnt vmcnt(9)
	ds_write_b128 v0, v[142:145] offset:9216
	s_waitcnt vmcnt(8)
	ds_write_b128 v0, v[146:149] offset:13824
	s_setprio 1
	v_add_u32_e32 v0, s49, v234
	ds_read_b128 v[238:241], v0
	ds_read_b128 v[248:251], v0 offset:4608
	s_waitcnt lgkmcnt(1)
	v_mfma_f32_32x32x16_bf16 v[114:129], v[170:173], v[238:241], v[114:129]
	v_mfma_f32_32x32x16_bf16 v[98:113], v[174:177], v[238:241], v[98:113]
	v_add_u32_e32 v245, 0xfff7c000, v237
	global_load_dwordx4 v[134:137], v245, s[34:35]
	ds_read_b128 v[238:241], v0 offset:9216
	s_waitcnt lgkmcnt(1)
	v_mfma_f32_32x32x16_bf16 v[82:97], v[170:173], v[248:251], v[82:97]
	v_mfma_f32_32x32x16_bf16 v[66:81], v[174:177], v[248:251], v[66:81]
	ds_read_b128 v[248:251], v0 offset:13824
	s_waitcnt lgkmcnt(1)
	v_mfma_f32_32x32x16_bf16 v[50:65], v[170:173], v[238:241], v[50:65]
	v_mfma_f32_32x32x16_bf16 v[34:49], v[174:177], v[238:241], v[34:49]
	v_add_u32_e32 v245, 0xfffa8000, v237
	global_load_dwordx4 v[138:141], v245, s[34:35]
	ds_read_b128 v[238:241], v0 offset:32
	s_waitcnt lgkmcnt(1)
	v_mfma_f32_32x32x16_bf16 v[18:33], v[170:173], v[248:251], v[18:33]
	v_mfma_f32_32x32x16_bf16 v[2:17], v[174:177], v[248:251], v[2:17]
	ds_read_b128 v[248:251], v0 offset:4640
	s_waitcnt lgkmcnt(1)
	v_mfma_f32_32x32x16_bf16 v[114:129], v[158:161], v[238:241], v[114:129]
	v_mfma_f32_32x32x16_bf16 v[98:113], v[166:169], v[238:241], v[98:113]
	v_add_u32_e32 v245, 0xfffd4000, v237
	global_load_dwordx4 v[142:145], v245, s[34:35]
	ds_read_b128 v[238:241], v0 offset:9248
	s_waitcnt lgkmcnt(1)
	v_mfma_f32_32x32x16_bf16 v[82:97], v[158:161], v[248:251], v[82:97]
	v_mfma_f32_32x32x16_bf16 v[66:81], v[166:169], v[248:251], v[66:81]
	ds_read_b128 v[248:251], v0 offset:13856
	s_waitcnt lgkmcnt(1)
	v_mfma_f32_32x32x16_bf16 v[50:65], v[158:161], v[238:241], v[50:65]
	v_mfma_f32_32x32x16_bf16 v[34:49], v[166:169], v[238:241], v[34:49]
	global_load_dwordx4 v[146:149], v237, s[34:35]
	ds_read_b128 v[238:241], v0 offset:64
	s_waitcnt lgkmcnt(1)
	v_mfma_f32_32x32x16_bf16 v[18:33], v[158:161], v[248:251], v[18:33]
	v_mfma_f32_32x32x16_bf16 v[2:17], v[166:169], v[248:251], v[2:17]
	ds_read_b128 v[248:251], v0 offset:4672
	s_waitcnt lgkmcnt(1)
	v_mfma_f32_32x32x16_bf16 v[114:129], v[154:157], v[238:241], v[114:129]
	v_mfma_f32_32x32x16_bf16 v[98:113], v[162:165], v[238:241], v[98:113]
	ds_read_b128 v[238:241], v0 offset:9280
	s_waitcnt lgkmcnt(1)
	v_mfma_f32_32x32x16_bf16 v[82:97], v[154:157], v[248:251], v[82:97]
	v_mfma_f32_32x32x16_bf16 v[66:81], v[162:165], v[248:251], v[66:81]
	ds_read_b128 v[248:251], v0 offset:13888
	s_waitcnt lgkmcnt(1)
	v_mfma_f32_32x32x16_bf16 v[50:65], v[154:157], v[238:241], v[50:65]
	v_mfma_f32_32x32x16_bf16 v[34:49], v[162:165], v[238:241], v[34:49]
	ds_read_b128 v[238:241], v0 offset:96
	s_waitcnt lgkmcnt(1)
	v_mfma_f32_32x32x16_bf16 v[18:33], v[154:157], v[248:251], v[18:33]
	v_mfma_f32_32x32x16_bf16 v[2:17], v[162:165], v[248:251], v[2:17]
	ds_read_b128 v[248:251], v0 offset:4704
	s_waitcnt lgkmcnt(1)
	v_mfma_f32_32x32x16_bf16 v[114:129], v[150:153], v[238:241], v[114:129]
	v_mfma_f32_32x32x16_bf16 v[98:113], v[206:209], v[238:241], v[98:113]
	ds_read_b128 v[238:241], v0 offset:9312
	s_waitcnt lgkmcnt(1)
	v_mfma_f32_32x32x16_bf16 v[82:97], v[150:153], v[248:251], v[82:97]
	v_mfma_f32_32x32x16_bf16 v[66:81], v[206:209], v[248:251], v[66:81]
	ds_read_b128 v[248:251], v0 offset:13920
	s_waitcnt lgkmcnt(1)
	v_mfma_f32_32x32x16_bf16 v[50:65], v[150:153], v[238:241], v[50:65]
	v_mfma_f32_32x32x16_bf16 v[34:49], v[206:209], v[238:241], v[34:49]
	s_waitcnt lgkmcnt(0)
	v_mfma_f32_32x32x16_bf16 v[18:33], v[150:153], v[248:251], v[18:33]
	v_mfma_f32_32x32x16_bf16 v[2:17], v[206:209], v[248:251], v[2:17]
	s_setprio 0
	s_add_u32 s44, s44, 0x1000
	s_addc_u32 s45, s45, 0
	v_add_u32_e32 v237, 0x80, v237
	s_cmp_eq_u32 s44, 0x2a000
	s_waitcnt vmcnt(11)
	v_mov_b32_e32 v170, v198
	v_mov_b32_e32 v171, v199
	v_mov_b32_e32 v172, v200
	v_mov_b32_e32 v173, v201
	s_waitcnt vmcnt(9)
	v_mov_b32_e32 v158, v194
	v_mov_b32_e32 v159, v195
	v_mov_b32_e32 v160, v196
	v_mov_b32_e32 v161, v197
	s_waitcnt vmcnt(7)
	v_mov_b32_e32 v154, v182
	v_mov_b32_e32 v155, v183
	v_mov_b32_e32 v156, v184
	v_mov_b32_e32 v157, v185
	s_waitcnt vmcnt(5)
	v_mov_b32_e32 v150, v178
	v_mov_b32_e32 v151, v179
	v_mov_b32_e32 v152, v180
	v_mov_b32_e32 v153, v181
	v_mov_b32_e32 v174, v202
	v_mov_b32_e32 v175, v203
	v_mov_b32_e32 v176, v204
	v_mov_b32_e32 v177, v205
	v_mov_b32_e32 v166, v190
	v_mov_b32_e32 v167, v191
	v_mov_b32_e32 v168, v192
	v_mov_b32_e32 v169, v193
	v_mov_b32_e32 v162, v186
	v_mov_b32_e32 v163, v187
	v_mov_b32_e32 v164, v188
	v_mov_b32_e32 v165, v189
	s_barrier
; #define MFMA32(a, b, c) __builtin_amdgcn_mfma_f32_32x32x16_bf16((a), (b), (c), 0, 0, 0)
; DI void gemm_main_bd(f32x16 (&acc)[4][2], const bf16_t* __restrict__ A, int lda, const bf16_t* __restrict__ Bf, int n0,
;                      int K, char* lds) {
;     ...
;   for (int k = 0; k < nsteps; ++k) {
;     const bf16_t* As = As0 + (k & 1) * (128 * 72);
;     bf16_t* Aw = As0 + ((k + 1) & 1) * (128 * 72);
; #pragma unroll
;     for (int ks = 0; ks < 4; ++ks) { bc[0][ks] = bn[0][ks]; bc[1][ks] = bn[1][ks]; }
;     if (k + 1 < nsteps) {
; #pragma unroll
;       for (int ks = 0; ks < 4; ++ks) {
;         bn[0][ks] = *(const bf16x8*)(Bb0 + (loff + 1024u * (unsigned)(4 * (k + 1) + ks)));
;         bn[1][ks] = *(const bf16x8*)(Bb1 + (loff + 1024u * (unsigned)(4 * (k + 1) + ks)));
;       }
; #pragma unroll
;       for (int i = 0; i < 4; ++i) *(u32x4*)(Aw + (lr + 32 * i) * 72 + lc) = ra[i];
;       if (k + 2 < nsteps) {
; #pragma unroll
;         for (int i = 0; i < 4; ++i) ra[i] = *(const u32x4*)(Ab + (aoff + astep * i + 128u * (unsigned)(k + 2)));
;       }
;     }
;     __builtin_amdgcn_s_setprio(1);
; #pragma unroll
;     for (int ks = 0; ks < 4; ++ks) {
;       bf16x8 af[4];
; #pragma unroll
;       for (int mi = 0; mi < 4; ++mi) af[mi] = *(const bf16x8*)(As + (32 * mi + l31) * 72 + 16 * ks + 8 * h2);
; #pragma unroll
;       for (int mi = 0; mi < 4; ++mi)
; #pragma unroll
;         for (int ni = 0; ni < 2; ++ni) acc[mi][ni] = MFMA32(bc[ni][ks], af[mi], acc[mi][ni]);
;     }
;     __builtin_amdgcn_s_setprio(0);
;     __syncthreads();
;   }
	s_cbranch_scc0 .LBB0_273
	v_or_b32_e32 v150, 0x2b000, v235
	global_load_dwordx4 v[174:177], v150, s[38:39]
	global_load_dwordx4 v[206:209], v150, s[42:43]
	v_or_b32_e32 v150, 0x2b400, v235
	global_load_dwordx4 v[170:173], v150, s[38:39]
	global_load_dwordx4 v[166:169], v150, s[42:43]
	v_or_b32_e32 v150, 0x2b800, v235
	global_load_dwordx4 v[158:161], v150, s[38:39]
	global_load_dwordx4 v[162:165], v150, s[42:43]
	v_or_b32_e32 v150, 0x2bc00, v235
	global_load_dwordx4 v[154:157], v150, s[38:39]
	s_nop 0
	global_load_dwordx4 v[150:153], v150, s[42:43]
	s_waitcnt vmcnt(11)
	ds_write_b128 v236, v[134:137] offset:18432
	s_waitcnt vmcnt(10)
	ds_write_b128 v236, v[138:141] offset:23040
	s_waitcnt vmcnt(9)
	ds_write_b128 v236, v[142:145] offset:27648
	s_waitcnt vmcnt(8)
	ds_write_b128 v236, v[146:149] offset:32256
	s_setprio 1
	ds_read_b128 v[134:137], v234
	s_waitcnt lgkmcnt(0)
	v_mfma_f32_32x32x16_bf16 v[114:129], v[198:201], v[134:137], v[114:129]
	v_mfma_f32_32x32x16_bf16 v[98:113], v[202:205], v[134:137], v[98:113]
	ds_read_b128 v[134:137], v234 offset:4608
	s_waitcnt lgkmcnt(0)
	v_mfma_f32_32x32x16_bf16 v[82:97], v[198:201], v[134:137], v[82:97]
	v_mfma_f32_32x32x16_bf16 v[66:81], v[202:205], v[134:137], v[66:81]
	ds_read_b128 v[134:137], v234 offset:9216
	s_waitcnt lgkmcnt(0)
	v_mfma_f32_32x32x16_bf16 v[50:65], v[198:201], v[134:137], v[50:65]
	v_mfma_f32_32x32x16_bf16 v[34:49], v[202:205], v[134:137], v[34:49]
	ds_read_b128 v[134:137], v234 offset:13824
	s_waitcnt lgkmcnt(0)
	v_mfma_f32_32x32x16_bf16 v[18:33], v[198:201], v[134:137], v[18:33]
	v_mfma_f32_32x32x16_bf16 v[2:17], v[202:205], v[134:137], v[2:17]
	ds_read_b128 v[134:137], v234 offset:32
	s_waitcnt lgkmcnt(0)
	v_mfma_f32_32x32x16_bf16 v[114:129], v[194:197], v[134:137], v[114:129]
	v_mfma_f32_32x32x16_bf16 v[98:113], v[190:193], v[134:137], v[98:113]
	ds_read_b128 v[134:137], v234 offset:4640
	s_waitcnt lgkmcnt(0)
	v_mfma_f32_32x32x16_bf16 v[82:97], v[194:197], v[134:137], v[82:97]
	v_mfma_f32_32x32x16_bf16 v[66:81], v[190:193], v[134:137], v[66:81]
	ds_read_b128 v[134:137], v234 offset:9248
	s_waitcnt lgkmcnt(0)
	v_mfma_f32_32x32x16_bf16 v[50:65], v[194:197], v[134:137], v[50:65]
	v_mfma_f32_32x32x16_bf16 v[34:49], v[190:193], v[134:137], v[34:49]
	ds_read_b128 v[134:137], v234 offset:13856
	s_waitcnt lgkmcnt(0)
	v_mfma_f32_32x32x16_bf16 v[18:33], v[194:197], v[134:137], v[18:33]
	v_mfma_f32_32x32x16_bf16 v[2:17], v[190:193], v[134:137], v[2:17]
	ds_read_b128 v[134:137], v234 offset:64
	s_waitcnt lgkmcnt(0)
	v_mfma_f32_32x32x16_bf16 v[114:129], v[182:185], v[134:137], v[114:129]
	v_mfma_f32_32x32x16_bf16 v[98:113], v[186:189], v[134:137], v[98:113]
	ds_read_b128 v[134:137], v234 offset:4672
	s_waitcnt lgkmcnt(0)
	v_mfma_f32_32x32x16_bf16 v[82:97], v[182:185], v[134:137], v[82:97]
	v_mfma_f32_32x32x16_bf16 v[66:81], v[186:189], v[134:137], v[66:81]
	ds_read_b128 v[134:137], v234 offset:9280
	s_waitcnt lgkmcnt(0)
	v_mfma_f32_32x32x16_bf16 v[50:65], v[182:185], v[134:137], v[50:65]
	v_mfma_f32_32x32x16_bf16 v[34:49], v[186:189], v[134:137], v[34:49]
	ds_read_b128 v[134:137], v234 offset:13888
	s_waitcnt lgkmcnt(0)
	v_mfma_f32_32x32x16_bf16 v[18:33], v[182:185], v[134:137], v[18:33]
	v_mfma_f32_32x32x16_bf16 v[2:17], v[186:189], v[134:137], v[2:17]
	ds_read_b128 v[134:137], v234 offset:96
	s_waitcnt lgkmcnt(0)
	v_mfma_f32_32x32x16_bf16 v[114:129], v[178:181], v[134:137], v[114:129]
	v_mfma_f32_32x32x16_bf16 v[98:113], v[130:133], v[134:137], v[98:113]
	ds_read_b128 v[134:137], v234 offset:4704
	s_waitcnt lgkmcnt(0)
	v_mfma_f32_32x32x16_bf16 v[82:97], v[178:181], v[134:137], v[82:97]
	v_mfma_f32_32x32x16_bf16 v[66:81], v[130:133], v[134:137], v[66:81]
	ds_read_b128 v[134:137], v234 offset:9312
	s_waitcnt lgkmcnt(0)
	v_mfma_f32_32x32x16_bf16 v[50:65], v[178:181], v[134:137], v[50:65]
	v_mfma_f32_32x32x16_bf16 v[34:49], v[130:133], v[134:137], v[34:49]
	ds_read_b128 v[134:137], v234 offset:13920
	s_waitcnt lgkmcnt(0)
	v_mfma_f32_32x32x16_bf16 v[18:33], v[178:181], v[134:137], v[18:33]
	v_mfma_f32_32x32x16_bf16 v[2:17], v[130:133], v[134:137], v[2:17]
	s_setprio 0
	s_and_b32 s28, s28, 0x7fffff00
	s_barrier
	s_setprio 1
	ds_read_b128 v[130:133], v0
	s_waitcnt vmcnt(7) lgkmcnt(0)
	v_mfma_f32_32x32x16_bf16 v[114:129], v[174:177], v[130:133], v[114:129]
	s_waitcnt vmcnt(6)
	v_mfma_f32_32x32x16_bf16 v[98:113], v[206:209], v[130:133], v[98:113]
	ds_read_b128 v[130:133], v0 offset:4608
	s_waitcnt lgkmcnt(0)
	v_mfma_f32_32x32x16_bf16 v[82:97], v[174:177], v[130:133], v[82:97]
	v_mfma_f32_32x32x16_bf16 v[66:81], v[206:209], v[130:133], v[66:81]
	ds_read_b128 v[130:133], v0 offset:9216
	s_waitcnt lgkmcnt(0)
	v_mfma_f32_32x32x16_bf16 v[50:65], v[174:177], v[130:133], v[50:65]
	v_mfma_f32_32x32x16_bf16 v[34:49], v[206:209], v[130:133], v[34:49]
	ds_read_b128 v[130:133], v0 offset:13824
	s_waitcnt lgkmcnt(0)
	v_mfma_f32_32x32x16_bf16 v[18:33], v[174:177], v[130:133], v[18:33]
	v_mfma_f32_32x32x16_bf16 v[2:17], v[206:209], v[130:133], v[2:17]
	ds_read_b128 v[130:133], v0 offset:32
	s_waitcnt vmcnt(5) lgkmcnt(0)
	v_mfma_f32_32x32x16_bf16 v[114:129], v[170:173], v[130:133], v[114:129]
	s_waitcnt vmcnt(4)
	v_mfma_f32_32x32x16_bf16 v[98:113], v[166:169], v[130:133], v[98:113]
	ds_read_b128 v[130:133], v0 offset:4640
	s_waitcnt lgkmcnt(0)
	v_mfma_f32_32x32x16_bf16 v[82:97], v[170:173], v[130:133], v[82:97]
	v_mfma_f32_32x32x16_bf16 v[66:81], v[166:169], v[130:133], v[66:81]
	ds_read_b128 v[130:133], v0 offset:9248
	s_waitcnt lgkmcnt(0)
	v_mfma_f32_32x32x16_bf16 v[50:65], v[170:173], v[130:133], v[50:65]
	v_mfma_f32_32x32x16_bf16 v[34:49], v[166:169], v[130:133], v[34:49]
	ds_read_b128 v[130:133], v0 offset:13856
	s_waitcnt lgkmcnt(0)
; #define MFMA32(a, b, c) __builtin_amdgcn_mfma_f32_32x32x16_bf16((a), (b), (c), 0, 0, 0)
; DI void gemm_main_bd(f32x16 (&acc)[4][2], const bf16_t* __restrict__ A, int lda, const bf16_t* __restrict__ Bf, int n0,
;                      int K, char* lds) {
;     ...
;     for (int ks = 0; ks < 4; ++ks) {
;       bf16x8 af[4];
; #pragma unroll
;       for (int mi = 0; mi < 4; ++mi) af[mi] = *(const bf16x8*)(As + (32 * mi + l31) * 72 + 16 * ks + 8 * h2);
; #pragma unroll
;       for (int mi = 0; mi < 4; ++mi)
; #pragma unroll
;         for (int ni = 0; ni < 2; ++ni) acc[mi][ni] = MFMA32(bc[ni][ks], af[mi], acc[mi][ni]);
;     }
;     __builtin_amdgcn_s_setprio(0);
;     __syncthreads();
;   }
; DI void phase_gemm_resid(const bf16_t* __restrict__ A, int K, const bf16_t* __restrict__ Bf, const float* xsrc, float* x,
;                          float scale, char* lds) {
;     ...
; #pragma unroll
;     for (int mi = 0; mi < 4; ++mi)
; #pragma unroll
;       for (int ni = 0; ni < 2; ++ni) {
;         float4 xs[4];
;         const size_t base = (size_t)(mt * 128 + 32 * mi + l31) * 1024 + nt * 256 + 64 * w + 32 * ni + 4 * h2;
; #pragma unroll
;         for (int g = 0; g < 4; ++g) xs[g] = *(const float4*)(xsrc + base + 8 * g);
; #pragma unroll
;         for (int g = 0; g < 4; ++g) {
;           float4 o;
;           o.x = xs[g].x + scale * a0[mi][ni][4 * g];
;           o.y = xs[g].y + scale * a0[mi][ni][4 * g + 1];
;           o.z = xs[g].z + scale * a0[mi][ni][4 * g + 2];
;           o.w = xs[g].w + scale * a0[mi][ni][4 * g + 3];
;           *(float4*)(x + base + 8 * g) = o;
;         }
;       }
	v_mfma_f32_32x32x16_bf16 v[18:33], v[170:173], v[130:133], v[18:33]
	v_mfma_f32_32x32x16_bf16 v[2:17], v[166:169], v[130:133], v[2:17]
	ds_read_b128 v[130:133], v0 offset:64
	s_waitcnt vmcnt(3) lgkmcnt(0)
	v_mfma_f32_32x32x16_bf16 v[114:129], v[158:161], v[130:133], v[114:129]
	s_waitcnt vmcnt(2)
	v_mfma_f32_32x32x16_bf16 v[98:113], v[162:165], v[130:133], v[98:113]
	ds_read_b128 v[130:133], v0 offset:4672
	s_waitcnt lgkmcnt(0)
	v_mfma_f32_32x32x16_bf16 v[82:97], v[158:161], v[130:133], v[82:97]
	v_mfma_f32_32x32x16_bf16 v[66:81], v[162:165], v[130:133], v[66:81]
	ds_read_b128 v[130:133], v0 offset:9280
	s_waitcnt lgkmcnt(0)
	v_mfma_f32_32x32x16_bf16 v[50:65], v[158:161], v[130:133], v[50:65]
	v_mfma_f32_32x32x16_bf16 v[34:49], v[162:165], v[130:133], v[34:49]
	ds_read_b128 v[130:133], v0 offset:13888
	s_waitcnt lgkmcnt(0)
	v_mfma_f32_32x32x16_bf16 v[18:33], v[158:161], v[130:133], v[18:33]
	v_mfma_f32_32x32x16_bf16 v[2:17], v[162:165], v[130:133], v[2:17]
	ds_read_b128 v[130:133], v0 offset:96
	s_waitcnt vmcnt(1) lgkmcnt(0)
	v_mfma_f32_32x32x16_bf16 v[114:129], v[154:157], v[130:133], v[114:129]
	s_waitcnt vmcnt(0)
	v_mfma_f32_32x32x16_bf16 v[98:113], v[150:153], v[130:133], v[98:113]
	ds_read_b128 v[130:133], v0 offset:4704
	s_waitcnt lgkmcnt(0)
	v_mfma_f32_32x32x16_bf16 v[82:97], v[154:157], v[130:133], v[82:97]
	v_mfma_f32_32x32x16_bf16 v[66:81], v[150:153], v[130:133], v[66:81]
	ds_read_b128 v[130:133], v0 offset:9312
	s_waitcnt lgkmcnt(0)
	v_mfma_f32_32x32x16_bf16 v[50:65], v[154:157], v[130:133], v[50:65]
	v_mfma_f32_32x32x16_bf16 v[34:49], v[150:153], v[130:133], v[34:49]
	ds_read_b128 v[130:133], v0 offset:13920
	s_waitcnt lgkmcnt(0)
	v_mfma_f32_32x32x16_bf16 v[18:33], v[154:157], v[130:133], v[18:33]
	v_mfma_f32_32x32x16_bf16 v[2:17], v[150:153], v[130:133], v[2:17]
	s_setprio 0
	v_lshl_add_u64 v[130:131], v[220:221], 0, s[28:29]
	v_lshl_or_b32 v0, s41, 17, v233
	v_lshl_add_u64 v[132:133], v[130:131], 0, v[0:1]
	v_lshlrev_b64 v[132:133], 2, v[132:133]
	v_lshl_add_u64 v[136:137], s[0:1], 0, v[132:133]
	s_barrier
	v_lshl_add_u64 v[138:139], s[24:25], 0, v[132:133]
	s_add_i32 s40, s40, 1
	s_mul_i32 s28, s40, s66
	s_add_i32 s28, s28, s3
	v_readlane_b32 s34, v243, 23
	s_cmp_ge_u32 s28, s34
	s_mov_b32 s100, 0x20000
	s_mov_b32 s101, 0
	v_lshl_add_u64 v[140:141], v[136:137], 0, s[100:101]
	v_lshl_add_u64 v[142:143], v[140:141], 0, s[100:101]
	v_lshl_add_u64 v[144:145], v[142:143], 0, s[100:101]
	v_lshl_add_u64 v[238:239], v[138:139], 0, s[100:101]
	v_lshl_add_u64 v[240:241], v[238:239], 0, s[100:101]
	v_lshl_add_u64 v[248:249], v[240:241], 0, s[100:101]
	global_load_dwordx4 v[146:149], v[136:137], off
	global_load_dwordx4 v[150:153], v[136:137], off offset:32
	global_load_dwordx4 v[154:157], v[136:137], off offset:64
	global_load_dwordx4 v[158:161], v[136:137], off offset:96
	global_load_dwordx4 v[162:165], v[136:137], off offset:128
	global_load_dwordx4 v[166:169], v[136:137], off offset:160
	global_load_dwordx4 v[170:173], v[136:137], off offset:192
	global_load_dwordx4 v[174:177], v[136:137], off offset:224
	global_load_dwordx4 v[178:181], v[140:141], off
	global_load_dwordx4 v[182:185], v[140:141], off offset:32
	global_load_dwordx4 v[186:189], v[140:141], off offset:64
	global_load_dwordx4 v[190:193], v[140:141], off offset:96
	global_load_dwordx4 v[194:197], v[140:141], off offset:128
	global_load_dwordx4 v[198:201], v[140:141], off offset:160
	global_load_dwordx4 v[202:205], v[140:141], off offset:192
	global_load_dwordx4 v[206:209], v[140:141], off offset:224
	s_waitcnt vmcnt(8)
	v_pk_fma_f32 v[114:115], v[114:115], 0.5, v[146:147] op_sel_hi:[1,0,1]
	v_pk_fma_f32 v[116:117], v[116:117], 0.5, v[148:149] op_sel_hi:[1,0,1]
	v_pk_fma_f32 v[118:119], v[118:119], 0.5, v[150:151] op_sel_hi:[1,0,1]
	v_pk_fma_f32 v[120:121], v[120:121], 0.5, v[152:153] op_sel_hi:[1,0,1]
	v_pk_fma_f32 v[122:123], v[122:123], 0.5, v[154:155] op_sel_hi:[1,0,1]
	v_pk_fma_f32 v[124:125], v[124:125], 0.5, v[156:157] op_sel_hi:[1,0,1]
	v_pk_fma_f32 v[126:127], v[126:127], 0.5, v[158:159] op_sel_hi:[1,0,1]
	v_pk_fma_f32 v[128:129], v[128:129], 0.5, v[160:161] op_sel_hi:[1,0,1]
	v_pk_fma_f32 v[98:99], v[98:99], 0.5, v[162:163] op_sel_hi:[1,0,1]
	v_pk_fma_f32 v[100:101], v[100:101], 0.5, v[164:165] op_sel_hi:[1,0,1]
	v_pk_fma_f32 v[102:103], v[102:103], 0.5, v[166:167] op_sel_hi:[1,0,1]
	v_pk_fma_f32 v[104:105], v[104:105], 0.5, v[168:169] op_sel_hi:[1,0,1]
	v_pk_fma_f32 v[106:107], v[106:107], 0.5, v[170:171] op_sel_hi:[1,0,1]
	v_pk_fma_f32 v[108:109], v[108:109], 0.5, v[172:173] op_sel_hi:[1,0,1]
	v_pk_fma_f32 v[110:111], v[110:111], 0.5, v[174:175] op_sel_hi:[1,0,1]
	v_pk_fma_f32 v[112:113], v[112:113], 0.5, v[176:177] op_sel_hi:[1,0,1]
	global_store_dwordx4 v[138:139], v[114:117], off
	global_store_dwordx4 v[138:139], v[118:121], off offset:32
	global_store_dwordx4 v[138:139], v[122:125], off offset:64
	global_store_dwordx4 v[138:139], v[126:129], off offset:96
	global_store_dwordx4 v[138:139], v[98:101], off offset:128
	global_store_dwordx4 v[138:139], v[102:105], off offset:160
	global_store_dwordx4 v[138:139], v[106:109], off offset:192
	global_store_dwordx4 v[138:139], v[110:113], off offset:224
	global_load_dwordx4 v[146:149], v[142:143], off
	global_load_dwordx4 v[150:153], v[142:143], off offset:32
	global_load_dwordx4 v[154:157], v[142:143], off offset:64
	global_load_dwordx4 v[158:161], v[142:143], off offset:96
	global_load_dwordx4 v[162:165], v[142:143], off offset:128
	global_load_dwordx4 v[166:169], v[142:143], off offset:160
	global_load_dwordx4 v[170:173], v[142:143], off offset:192
	global_load_dwordx4 v[174:177], v[142:143], off offset:224
	s_waitcnt vmcnt(16)
; DI void phase_gemm_resid(const bf16_t* __restrict__ A, int K, const bf16_t* __restrict__ Bf, const float* xsrc, float* x,
;                          float scale, char* lds) {
;     ...
; #pragma unroll
;     for (int mi = 0; mi < 4; ++mi)
; #pragma unroll
;       for (int ni = 0; ni < 2; ++ni) {
;         float4 xs[4];
;         const size_t base = (size_t)(mt * 128 + 32 * mi + l31) * 1024 + nt * 256 + 64 * w + 32 * ni + 4 * h2;
; #pragma unroll
;         for (int g = 0; g < 4; ++g) xs[g] = *(const float4*)(xsrc + base + 8 * g);
; #pragma unroll
;         for (int g = 0; g < 4; ++g) {
;           float4 o;
;           o.x = xs[g].x + scale * a0[mi][ni][4 * g];
;           o.y = xs[g].y + scale * a0[mi][ni][4 * g + 1];
;           o.z = xs[g].z + scale * a0[mi][ni][4 * g + 2];
;           o.w = xs[g].w + scale * a0[mi][ni][4 * g + 3];
;           *(float4*)(x + base + 8 * g) = o;
;         }
;       }
	v_pk_fma_f32 v[82:83], v[82:83], 0.5, v[178:179] op_sel_hi:[1,0,1]
	v_pk_fma_f32 v[84:85], v[84:85], 0.5, v[180:181] op_sel_hi:[1,0,1]
	v_pk_fma_f32 v[86:87], v[86:87], 0.5, v[182:183] op_sel_hi:[1,0,1]
	v_pk_fma_f32 v[88:89], v[88:89], 0.5, v[184:185] op_sel_hi:[1,0,1]
	v_pk_fma_f32 v[90:91], v[90:91], 0.5, v[186:187] op_sel_hi:[1,0,1]
	v_pk_fma_f32 v[92:93], v[92:93], 0.5, v[188:189] op_sel_hi:[1,0,1]
	v_pk_fma_f32 v[94:95], v[94:95], 0.5, v[190:191] op_sel_hi:[1,0,1]
	v_pk_fma_f32 v[96:97], v[96:97], 0.5, v[192:193] op_sel_hi:[1,0,1]
	v_pk_fma_f32 v[66:67], v[66:67], 0.5, v[194:195] op_sel_hi:[1,0,1]
	v_pk_fma_f32 v[68:69], v[68:69], 0.5, v[196:197] op_sel_hi:[1,0,1]
	v_pk_fma_f32 v[70:71], v[70:71], 0.5, v[198:199] op_sel_hi:[1,0,1]
	v_pk_fma_f32 v[72:73], v[72:73], 0.5, v[200:201] op_sel_hi:[1,0,1]
	v_pk_fma_f32 v[74:75], v[74:75], 0.5, v[202:203] op_sel_hi:[1,0,1]
	v_pk_fma_f32 v[76:77], v[76:77], 0.5, v[204:205] op_sel_hi:[1,0,1]
	v_pk_fma_f32 v[78:79], v[78:79], 0.5, v[206:207] op_sel_hi:[1,0,1]
	v_pk_fma_f32 v[80:81], v[80:81], 0.5, v[208:209] op_sel_hi:[1,0,1]
	global_store_dwordx4 v[238:239], v[82:85], off
	global_store_dwordx4 v[238:239], v[86:89], off offset:32
	global_store_dwordx4 v[238:239], v[90:93], off offset:64
	global_store_dwordx4 v[238:239], v[94:97], off offset:96
	global_store_dwordx4 v[238:239], v[66:69], off offset:128
	global_store_dwordx4 v[238:239], v[70:73], off offset:160
	global_store_dwordx4 v[238:239], v[74:77], off offset:192
	global_store_dwordx4 v[238:239], v[78:81], off offset:224
	global_load_dwordx4 v[178:181], v[144:145], off
	global_load_dwordx4 v[182:185], v[144:145], off offset:32
	global_load_dwordx4 v[186:189], v[144:145], off offset:64
	global_load_dwordx4 v[190:193], v[144:145], off offset:96
	global_load_dwordx4 v[194:197], v[144:145], off offset:128
	global_load_dwordx4 v[198:201], v[144:145], off offset:160
	global_load_dwordx4 v[202:205], v[144:145], off offset:192
	global_load_dwordx4 v[206:209], v[144:145], off offset:224
	s_waitcnt vmcnt(16)
	v_pk_fma_f32 v[50:51], v[50:51], 0.5, v[146:147] op_sel_hi:[1,0,1]
	v_pk_fma_f32 v[52:53], v[52:53], 0.5, v[148:149] op_sel_hi:[1,0,1]
	v_pk_fma_f32 v[54:55], v[54:55], 0.5, v[150:151] op_sel_hi:[1,0,1]
	v_pk_fma_f32 v[56:57], v[56:57], 0.5, v[152:153] op_sel_hi:[1,0,1]
	v_pk_fma_f32 v[58:59], v[58:59], 0.5, v[154:155] op_sel_hi:[1,0,1]
	v_pk_fma_f32 v[60:61], v[60:61], 0.5, v[156:157] op_sel_hi:[1,0,1]
	v_pk_fma_f32 v[62:63], v[62:63], 0.5, v[158:159] op_sel_hi:[1,0,1]
	v_pk_fma_f32 v[64:65], v[64:65], 0.5, v[160:161] op_sel_hi:[1,0,1]
	v_pk_fma_f32 v[34:35], v[34:35], 0.5, v[162:163] op_sel_hi:[1,0,1]
	v_pk_fma_f32 v[36:37], v[36:37], 0.5, v[164:165] op_sel_hi:[1,0,1]
	v_pk_fma_f32 v[38:39], v[38:39], 0.5, v[166:167] op_sel_hi:[1,0,1]
	v_pk_fma_f32 v[40:41], v[40:41], 0.5, v[168:169] op_sel_hi:[1,0,1]
	v_pk_fma_f32 v[42:43], v[42:43], 0.5, v[170:171] op_sel_hi:[1,0,1]
	v_pk_fma_f32 v[44:45], v[44:45], 0.5, v[172:173] op_sel_hi:[1,0,1]
	v_pk_fma_f32 v[46:47], v[46:47], 0.5, v[174:175] op_sel_hi:[1,0,1]
	v_pk_fma_f32 v[48:49], v[48:49], 0.5, v[176:177] op_sel_hi:[1,0,1]
	global_store_dwordx4 v[240:241], v[50:53], off
	global_store_dwordx4 v[240:241], v[54:57], off offset:32
	global_store_dwordx4 v[240:241], v[58:61], off offset:64
	global_store_dwordx4 v[240:241], v[62:65], off offset:96
	global_store_dwordx4 v[240:241], v[34:37], off offset:128
	global_store_dwordx4 v[240:241], v[38:41], off offset:160
	global_store_dwordx4 v[240:241], v[42:45], off offset:192
	global_store_dwordx4 v[240:241], v[46:49], off offset:224
	s_waitcnt vmcnt(8)
	v_pk_fma_f32 v[18:19], v[18:19], 0.5, v[178:179] op_sel_hi:[1,0,1]
	v_pk_fma_f32 v[20:21], v[20:21], 0.5, v[180:181] op_sel_hi:[1,0,1]
	v_pk_fma_f32 v[22:23], v[22:23], 0.5, v[182:183] op_sel_hi:[1,0,1]
	v_pk_fma_f32 v[24:25], v[24:25], 0.5, v[184:185] op_sel_hi:[1,0,1]
	v_pk_fma_f32 v[26:27], v[26:27], 0.5, v[186:187] op_sel_hi:[1,0,1]
	v_pk_fma_f32 v[28:29], v[28:29], 0.5, v[188:189] op_sel_hi:[1,0,1]
	v_pk_fma_f32 v[30:31], v[30:31], 0.5, v[190:191] op_sel_hi:[1,0,1]
	v_pk_fma_f32 v[32:33], v[32:33], 0.5, v[192:193] op_sel_hi:[1,0,1]
	v_pk_fma_f32 v[2:3], v[2:3], 0.5, v[194:195] op_sel_hi:[1,0,1]
	v_pk_fma_f32 v[4:5], v[4:5], 0.5, v[196:197] op_sel_hi:[1,0,1]
	v_pk_fma_f32 v[6:7], v[6:7], 0.5, v[198:199] op_sel_hi:[1,0,1]
	v_pk_fma_f32 v[8:9], v[8:9], 0.5, v[200:201] op_sel_hi:[1,0,1]
	v_pk_fma_f32 v[10:11], v[10:11], 0.5, v[202:203] op_sel_hi:[1,0,1]
	v_pk_fma_f32 v[12:13], v[12:13], 0.5, v[204:205] op_sel_hi:[1,0,1]
	v_pk_fma_f32 v[14:15], v[14:15], 0.5, v[206:207] op_sel_hi:[1,0,1]
	v_pk_fma_f32 v[16:17], v[16:17], 0.5, v[208:209] op_sel_hi:[1,0,1]
	global_store_dwordx4 v[248:249], v[18:21], off
	global_store_dwordx4 v[248:249], v[22:25], off offset:32
	global_store_dwordx4 v[248:249], v[26:29], off offset:64
	global_store_dwordx4 v[248:249], v[30:33], off offset:96
	global_store_dwordx4 v[248:249], v[2:5], off offset:128
	global_store_dwordx4 v[248:249], v[6:9], off offset:160
	global_store_dwordx4 v[248:249], v[10:13], off offset:192
	global_store_dwordx4 v[248:249], v[14:17], off offset:224
	s_cbranch_scc0 .LBB0_272

; template <int DK, bool BAND>
; DI void flash_loop(f32x16 (&O)[2], float& m, float& l, const bf16_t* __restrict__ qrow, const bf16_t* __restrict__ kbase,
;                    size_t kstride, const bf16_t* __restrict__ vbase, size_t vstride, int ntiles, int tq, int u0, int L,
;                    char* lds) {
;   const int tid = threadIdx.x + opq(), lane = tid & 63, l31 = lane & 31, h2 = lane >> 5;
;   constexpr int KR = DK + 8, KCH = DK / 8, KN = 64 * KCH / 256;
;   constexpr int STAGE = 64 * KR * 2 + 64 * 72 * 2;
;   bf16x8 qf[DK / 16];
; #pragma unroll
;   for (int ks = 0; ks < DK / 16; ++ks) qf[ks] = *(const bf16x8*)(qrow + 16 * ks + 8 * h2);
;   u32x4 rkA[KN], rvA[2], rkB[KN], rvB[2];
;   auto gload = [&](int kt, u32x4 (&rk)[KN], u32x4 (&rv)[2]) {
; #pragma unroll
;     for (int i = 0; i < KN; ++i) {
;       const int ci = tid + 256 * i, row = ci / KCH, c = ci % KCH;
;       int rr = u0 + 64 * kt + row;
;       if (BAND) rr = min(max(rr, 0), L - 1);
;       rk[i] = *(const u32x4*)((const char*)kbase + ((unsigned)rr * (unsigned)(kstride * 2) + (unsigned)c * 16u));
;     }
; #pragma unroll
;     for (int i = 0; i < 2; ++i) {
;       const int ci = tid + 256 * i, row = ci >> 3, c = ci & 7;
;       int rr = u0 + 64 * kt + row;
;       if (BAND) rr = min(max(rr, 0), L - 1);
;       rv[i] = *(const u32x4*)((const char*)vbase + ((unsigned)rr * (unsigned)(vstride * 2) + (unsigned)c * 16u));
;     }
;   };
;   auto swrite = [&](int st, const u32x4 (&rk)[KN], const u32x4 (&rv)[2]) {
;     bf16_t* Ks = (bf16_t*)(lds + st * STAGE);
; DI void mla_item(CParams& p, int it, int S, char* lds) {
;   const int tid = threadIdx.x + opq(), lane = tid & 63, w = tid >> 6, l31 = lane & 31, h2 = lane >> 5;
;   const int lgq = (S == 2048) ? 4 : 7;
;   const int qb = it & ((1 << lgq) - 1), bh = it >> lgq, h = bh & 3, b = bh >> 2;
;   const int tokbase = b * S, gtok = tokbase + 128 * qb + 32 * w + l31;
;   const bf16_t* Qb = (const bf16_t*)(p.ws + OFF_Q);
;   const bf16_t* Kb = (const bf16_t*)(p.ws + OFF_K);
;   const bf16_t* Vb = (const bf16_t*)(p.ws + OFF_V);
;   bf16_t* Y = (bf16_t*)(p.ws + OFF_N);
;   f32x16 O[2]; zeroO(O);
;   float m = -1e30f, l = 0.f;
;   flash_loop<96, false>(O, m, l, Qb + ((size_t)gtok * 4 + h) * 96, Kb + ((size_t)tokbase * 4 + h) * 96, 384,
;                         Vb + ((size_t)tokbase * 4 + h) * 64, 256, S / 64, 0, 0, 0, lds);
.LBB0_842:
	s_or_b64 exec, exec, s[6:7]
	s_waitcnt lgkmcnt(0)
	s_barrier
	flat_load_dword v0, v[218:219] sc0 sc1
	s_waitcnt vmcnt(0)
	s_mov_b64 s[6:7], -1
	s_waitcnt lgkmcnt(0)
	v_readfirstlane_b32 s8, v0
	s_cmpk_gt_i32 s8, 0x7f
	s_cbranch_scc1 .LBB0_837
	s_ashr_i32 s6, s8, s68
	s_lshl_b32 s6, s6, 3
	s_or_b32 s6, s6, s50
	s_and_b32 s7, s8, s69
	s_lshl_b32 s6, s6, s68
	s_add_i32 s6, s6, s7
	s_ashr_i32 s8, s6, s68
	s_and_b32 s7, s6, s69
	s_and_b32 s6, s8, 3
	s_ashr_i32 s8, s8, 2
	v_mov_b32 v0, 0
	s_lshl_b32 s8, s8, s89
	v_add_u32_e32 v132, v0, v210
	s_lshl_b32 s7, s7, 7
	s_add_i32 s7, s8, s7
	v_ashrrev_i32_e32 v0, 1, v132
	v_and_b32_e32 v0, 0xffffffe0, v0
	v_and_or_b32 v2, v132, 31, s7
	v_add_u32_e32 v130, v2, v0
	v_ashrrev_i32_e32 v131, 31, v130
	v_lshlrev_b64 v[2:3], 2, v[130:131]
	v_or_b32_e32 v0, s6, v2
	v_mov_b64_e32 v[4:5], s[0:1]
	v_mad_u64_u32 v[4:5], s[38:39], v0, s81, v[4:5]
	v_mov_b32 v0, 0
	v_mad_i32_i24 v5, v3, s81, v5
	v_add_u32_e32 v23, v0, v210
	v_bfe_u32 v27, v23, 5, 1
	s_ashr_i32 s9, s8, 31
	v_lshlrev_b32_e32 v0, 4, v27
	s_lshl_b64 s[8:9], s[8:9], 2
	v_lshl_add_u64 v[2:3], v[4:5], 0, v[0:1]
	s_or_b32 s8, s8, s6
	global_load_dwordx4 v[66:69], v[2:3], off
	global_load_dwordx4 v[70:73], v[2:3], off offset:32
	global_load_dwordx4 v[74:77], v[2:3], off offset:64
	global_load_dwordx4 v[78:81], v[2:3], off offset:96
	global_load_dwordx4 v[82:85], v[2:3], off offset:128
	global_load_dwordx4 v[86:89], v[2:3], off offset:160
	v_mul_hi_i32 v2, v23, s17
	s_mul_i32 s7, s9, 0xc0
	s_mul_hi_u32 s28, s8, 0xc0
	v_lshrrev_b32_e32 v3, 31, v2
	v_ashrrev_i32_e32 v2, 1, v2
	s_add_i32 s28, s28, s7
	s_mul_i32 s7, s8, 0xc0
	v_add_u32_e32 v31, v2, v3
	s_add_u32 s38, s45, s7
	v_mul_lo_u32 v2, v31, 12
	s_addc_u32 s39, s46, s28
	s_lshl_b64 s[8:9], s[8:9], 7
	v_sub_u32_e32 v2, v23, v2
	v_add_u32_e32 v18, 0x100, v23
	s_add_u32 s42, s47, s8
	v_lshlrev_b32_e32 v22, 4, v2
	v_mul_hi_i32 v2, v18, s17
	s_addc_u32 s43, s48, s9
	v_mad_u64_u32 v[24:25], s[8:9], v31, s84, v[22:23]
	v_lshrrev_b32_e32 v3, 31, v2
	v_ashrrev_i32_e32 v2, 1, v2
	v_add_u32_e32 v25, v2, v3
	v_mul_lo_u32 v2, v25, 12
	v_sub_u32_e32 v2, v18, v2
	v_add_u32_e32 v10, 0x200, v23
	v_lshlrev_b32_e32 v26, 4, v2
	v_mul_hi_i32 v11, v10, s17
	v_mad_u64_u32 v[28:29], s[8:9], v25, s84, v[26:27]
	v_lshrrev_b32_e32 v12, 31, v11
	v_ashrrev_i32_e32 v11, 1, v11
	v_add_u32_e32 v29, v11, v12
	v_mul_lo_u32 v11, v29, 12
	v_sub_u32_e32 v10, v10, v11
	s_barrier
	global_load_dwordx4 v[2:5], v24, s[38:39]
	global_load_dwordx4 v[6:9], v28, s[38:39]
	v_lshlrev_b32_e32 v30, 4, v10
	v_mad_u64_u32 v[32:33], s[8:9], v29, s84, v[30:31]
	v_lshlrev_b32_e32 v134, 4, v23
	v_ashrrev_i32_e32 v35, 3, v18
	v_ashrrev_i32_e32 v33, 3, v23
	v_and_b32_e32 v135, 0x70, v134
	v_lshlrev_b32_e32 v136, 9, v35
	v_lshlrev_b32_e32 v133, 9, v33
	v_or_b32_e32 v36, v136, v135
	v_add_u32_e32 v37, 0xc000, v24
	v_or_b32_e32 v34, v133, v135
	global_load_dwordx4 v[18:21], v36, s[42:43]
	global_load_dwordx4 v[90:93], v37, s[38:39]
	v_add_u32_e32 v37, 0xc000, v28
	global_load_dwordx4 v[10:13], v32, s[38:39]
	global_load_dwordx4 v[14:17], v34, s[42:43]
	v_add_u32_e32 v38, 0xc000, v32
	global_load_dwordx4 v[94:97], v37, s[38:39]
	global_load_dwordx4 v[98:101], v38, s[38:39]
	v_add_u32_e32 v37, 0x8000, v34
	v_add_u32_e32 v24, 0x18000, v24
	v_add_u32_e32 v38, 0x8000, v36
	global_load_dwordx4 v[106:109], v37, s[42:43]
	global_load_dwordx4 v[114:117], v38, s[42:43]
	v_add_u32_e32 v28, 0x18000, v28
	global_load_dwordx4 v[102:105], v24, s[38:39]
	global_load_dwordx4 v[110:113], v28, s[38:39]
	v_add_u32_e32 v24, 0x18000, v32
	v_add_u32_e32 v28, 0x10000, v34
	global_load_dwordx4 v[118:121], v24, s[38:39]
	global_load_dwordx4 v[122:125], v28, s[42:43]
	v_add_u32_e32 v24, 0x10000, v36
	global_load_dwordx4 v[126:129], v24, s[42:43]
	v_and_b32_e32 v24, 31, v23
	v_bfe_u32 v28, v23, 2, 2
	v_and_b32_e32 v32, 16, v23
	v_lshlrev_b32_e32 v23, 2, v23
	v_lshl_or_b32 v27, v27, 2, v28
	v_and_or_b32 v23, v23, 12, v32
	v_mad_u32_u24 v23, v27, s13, v23
	v_mul_lo_u32 v27, v31, s33
	v_add3_u32 v137, 16, v27, v22
	v_lshl_add_u32 v142, v23, 1, 16
	v_mul_lo_u32 v144, v29, s21
	v_mul_lo_u32 v145, v25, s21
	v_mul_lo_u32 v146, v31, s21
	v_mov_b32_e32 v22, v1
	v_mov_b32_e32 v23, v1
	v_mov_b32_e32 v27, v1
	v_mov_b32_e32 v28, v1
	v_mov_b32_e32 v31, v1
	s_mov_b32 s7, 0
	v_mov_b32_e32 v148, 0
	v_mov_b32_e32 v147, 0xf149f2ca
	s_waitcnt vmcnt(14)
	ds_write_b128 v137, v[2:5]
	v_mul_lo_u32 v2, v25, s33
	v_add3_u32 v138, 16, v2, v26
	v_mul_lo_u32 v2, v29, s33
	v_add3_u32 v139, 16, v2, v30
	v_mul_lo_u32 v2, v33, s12
	v_add3_u32 v140, 16, v2, v135
	v_mul_lo_u32 v2, v35, s12
	v_add3_u32 v141, 16, v2, v135
	v_mul_u32_u24_e32 v2, 0x68, v24
	v_lshlrev_b32_e32 v2, 1, v2
	s_waitcnt vmcnt(13)
	ds_write_b128 v138, v[6:9]
	v_add3_u32 v143, 16, v0, v2
	v_mov_b32_e32 v2, v1
	v_mov_b32_e32 v3, v1
	v_mov_b32_e32 v4, v1
	v_mov_b32_e32 v5, v1
	s_waitcnt vmcnt(10)
	ds_write_b128 v139, v[10:13]
	s_waitcnt vmcnt(9)
	ds_write_b128 v140, v[14:17] offset:13312
	ds_write_b128 v141, v[18:21] offset:13312
	v_mov_b32_e32 v6, v1
	v_mov_b32_e32 v7, v1
	v_mov_b32_e32 v8, v1
	v_mov_b32_e32 v9, v1
	v_mov_b32_e32 v10, v1
	v_mov_b32_e32 v11, v1
	v_mov_b32_e32 v12, v1
	v_mov_b32_e32 v13, v1
	v_mov_b32_e32 v14, v1
	v_mov_b32_e32 v15, v1
	v_mov_b32_e32 v16, v1
	v_mov_b32_e32 v17, v1
	v_mov_b32_e32 v18, v1
	v_mov_b32_e32 v19, v1
	v_mov_b32_e32 v20, v1
	v_mov_b32_e32 v21, v1
	v_mov_b32_e32 v24, v1
	v_mov_b32_e32 v25, v1
	v_mov_b32_e32 v26, v1
	v_mov_b32_e32 v29, v1
	v_mov_b32_e32 v30, v1
	v_mov_b32_e32 v0, v1
	v_mov_b64_e32 v[32:33], v[30:31]
	v_mov_b64_e32 v[30:31], v[28:29]
	v_mov_b64_e32 v[28:29], v[26:27]
	v_mov_b64_e32 v[26:27], v[24:25]
	v_mov_b64_e32 v[24:25], v[22:23]
	v_mov_b64_e32 v[22:23], v[20:21]
	v_mov_b64_e32 v[20:21], v[18:19]
	v_mov_b64_e32 v[18:19], v[16:17]
	v_mov_b64_e32 v[16:17], v[14:15]
	v_mov_b64_e32 v[14:15], v[12:13]
	v_mov_b64_e32 v[12:13], v[10:11]
	v_mov_b64_e32 v[10:11], v[8:9]
	v_mov_b64_e32 v[8:9], v[6:7]
	v_mov_b64_e32 v[6:7], v[4:5]
	v_mov_b64_e32 v[4:5], v[2:3]
	v_mov_b64_e32 v[2:3], v[0:1]
	v_mov_b32_e32 v190, 0
	v_mov_b32_e32 v191, 0
	v_mov_b32_e32 v192, 0
	v_mov_b32_e32 v193, 0
	v_mov_b32_e32 v194, 0
	v_mov_b32_e32 v195, 0
	v_mov_b32_e32 v196, 0
	v_mov_b32_e32 v197, 0
	v_mov_b32_e32 v198, 0
	v_mov_b32_e32 v199, 0
	v_mov_b32_e32 v200, 0
	v_mov_b32_e32 v201, 0
	v_mov_b32_e32 v202, 0
	v_mov_b32_e32 v203, 0
	v_mov_b32_e32 v204, 0
	v_mov_b32_e32 v205, 0
	s_branch .LBB0_845
; #define MFMA32(a, b, c) __builtin_amdgcn_mfma_f32_32x32x16_bf16((a), (b), (c), 0, 0, 0)
; DI float exp2_(float x) { return __builtin_amdgcn_exp2f(x); }
; template <int DK, bool BAND>
; DI void flash_loop(f32x16 (&O)[2], float& m, float& l, const bf16_t* __restrict__ qrow, const bf16_t* __restrict__ kbase,
;                    size_t kstride, const bf16_t* __restrict__ vbase, size_t vstride, int ntiles, int tq, int u0, int L,
;                    char* lds) {
;     ...
;     float ls = 0.f;
; #pragma unroll
;     for (int j = 0; j < 2; ++j)
; #pragma unroll
;       for (int r = 0; r < 16; ++r) { const float pv = exp2_(Sx[j][r] - m); Sx[j][r] = pv; ls += pv; }
;     l += ls;
; #pragma unroll
;     for (int j = 0; j < 2; ++j)
; #pragma unroll
;       for (int s = 0; s < 2; ++s) {
;         const bf16x8 pf = pack8(Sx[j][8 * s], Sx[j][8 * s + 1], Sx[j][8 * s + 2], Sx[j][8 * s + 3], Sx[j][8 * s + 4],
;                                 Sx[j][8 * s + 5], Sx[j][8 * s + 6], Sx[j][8 * s + 7]);
; #pragma unroll
;         for (int t = 0; t < 2; ++t) {
;           const bf16_t* vp = Vs + (32 * j + 16 * s) * 72 + 32 * t + troff;
;           const bf16x8 vf = tr_pair(vp, vp + 8 * 72);
;           O[t] = MFMA32(vf, pf, O[t]);
;         }
;       }
.LBB0_844:
	v_exp_f32_e32 v50, v50
	v_exp_f32_e32 v51, v51
	v_exp_f32_e32 v52, v52
	v_exp_f32_e32 v53, v53
	v_add_f32_e32 v148, 0, v50
	v_exp_f32_e32 v54, v54
	v_add_f32_e32 v148, v51, v148
	v_exp_f32_e32 v55, v55
	v_add_f32_e32 v148, v52, v148
	v_exp_f32_e32 v56, v56
	v_add_f32_e32 v148, v53, v148
	v_exp_f32_e32 v57, v57
	v_add_f32_e32 v148, v54, v148
	v_exp_f32_e32 v58, v58
	v_add_f32_e32 v148, v55, v148
	v_exp_f32_e32 v59, v59
	v_add_f32_e32 v148, v56, v148
	v_exp_f32_e32 v60, v60
	v_add_f32_e32 v148, v57, v148
	v_exp_f32_e32 v61, v61
	v_add_f32_e32 v148, v58, v148
	v_exp_f32_e32 v62, v62
	v_add_f32_e32 v148, v59, v148
	v_exp_f32_e32 v63, v63
	v_add_f32_e32 v148, v60, v148
	v_exp_f32_e32 v64, v64
	v_add_f32_e32 v148, v61, v148
	v_exp_f32_e32 v65, v65
	v_add_f32_e32 v148, v62, v148
	v_exp_f32_e32 v149, v34
	v_add_f32_e32 v148, v63, v148
	v_exp_f32_e32 v150, v35
	v_add_f32_e32 v148, v64, v148
	v_exp_f32_e32 v151, v36
	v_add_f32_e32 v148, v65, v148
	v_exp_f32_e32 v152, v37
	v_add_f32_e32 v34, v149, v148
	v_exp_f32_e32 v153, v38
	v_add_f32_e32 v34, v150, v34
	v_exp_f32_e32 v154, v39
	v_add_f32_e32 v34, v151, v34
	v_exp_f32_e32 v155, v40
	v_add_f32_e32 v34, v152, v34
	v_exp_f32_e32 v156, v41
	v_add_f32_e32 v34, v153, v34
	v_exp_f32_e32 v42, v42
	v_add_f32_e32 v34, v154, v34
	v_exp_f32_e32 v43, v43
	v_add_f32_e32 v34, v155, v34
	v_exp_f32_e32 v44, v44
	v_add_f32_e32 v34, v156, v34
	v_exp_f32_e32 v45, v45
	v_add_f32_e32 v34, v42, v34
	v_exp_f32_e32 v46, v46
	v_add_f32_e32 v34, v43, v34
	v_exp_f32_e32 v47, v47
	v_add_f32_e32 v34, v44, v34
	v_exp_f32_e32 v48, v48
	v_add_f32_e32 v34, v45, v34
	v_exp_f32_e32 v49, v49
	v_add_f32_e32 v34, v46, v34
	v_add_f32_e32 v34, v47, v34
	v_add_f32_e32 v34, v48, v34
	v_add_f32_e32 v34, v49, v34
	v_add_f32_e32 v148, v0, v34
	v_cvt_pk_bf16_f32 v34, v50, v51
	v_cvt_pk_bf16_f32 v35, v52, v53
	v_cvt_pk_bf16_f32 v36, v54, v55
	v_cvt_pk_bf16_f32 v37, v56, v57
	s_add_i32 s7, s7, 2
	v_add_u32_e32 v136, 0x10000, v136
	s_waitcnt lgkmcnt(0)
	v_mfma_f32_32x32x16_bf16 v[2:17], v[158:161], v[34:37], v[2:17]
	v_add_u32_e32 v133, 0x10000, v133
	v_add_u32_e32 v144, 0x18000, v144
	v_add_u32_e32 v145, 0x18000, v145
	v_add_u32_e32 v146, 0x18000, v146
	s_cmp_lt_u32 s7, s88
	s_waitcnt lgkmcnt(0)
	v_mfma_f32_32x32x16_bf16 v[18:33], v[162:165], v[34:37], v[18:33]
	v_cvt_pk_bf16_f32 v34, v58, v59
	v_cvt_pk_bf16_f32 v35, v60, v61
	v_cvt_pk_bf16_f32 v36, v62, v63
	v_cvt_pk_bf16_f32 v37, v64, v65
	s_waitcnt lgkmcnt(0)
	s_nop 0
	v_mfma_f32_32x32x16_bf16 v[2:17], v[166:169], v[34:37], v[2:17]
	s_waitcnt lgkmcnt(0)
	v_mfma_f32_32x32x16_bf16 v[18:33], v[170:173], v[34:37], v[18:33]
	v_cvt_pk_bf16_f32 v34, v149, v150
	v_cvt_pk_bf16_f32 v35, v151, v152
	v_cvt_pk_bf16_f32 v36, v153, v154
	v_cvt_pk_bf16_f32 v37, v155, v156
	s_waitcnt lgkmcnt(0)
	s_nop 0
	v_mfma_f32_32x32x16_bf16 v[2:17], v[174:177], v[34:37], v[2:17]
	s_waitcnt lgkmcnt(0)
	v_mfma_f32_32x32x16_bf16 v[18:33], v[178:181], v[34:37], v[18:33]
	v_cvt_pk_bf16_f32 v34, v42, v43
	v_cvt_pk_bf16_f32 v35, v44, v45
	v_cvt_pk_bf16_f32 v36, v46, v47
	v_cvt_pk_bf16_f32 v37, v48, v49
	s_waitcnt lgkmcnt(0)
	s_nop 0
	v_mfma_f32_32x32x16_bf16 v[2:17], v[182:185], v[34:37], v[2:17]
	s_waitcnt lgkmcnt(0)
	v_mfma_f32_32x32x16_bf16 v[18:33], v[186:189], v[34:37], v[18:33]
	s_cbranch_scc0 .LBB0_836

; #define MFMA32(a, b, c) __builtin_amdgcn_mfma_f32_32x32x16_bf16((a), (b), (c), 0, 0, 0)
; DI float exp2_(float x) { return __builtin_amdgcn_exp2f(x); }
; DI int crow(int r, int h2) { return (r & 3) + 8 * (r >> 2) + 4 * h2; }
; template <int DK, bool BAND>
; DI void flash_loop(f32x16 (&O)[2], float& m, float& l, const bf16_t* __restrict__ qrow, const bf16_t* __restrict__ kbase,
;                    size_t kstride, const bf16_t* __restrict__ vbase, size_t vstride, int ntiles, int tq, int u0, int L,
;                    char* lds) {
;     ...
; #pragma unroll
;     for (int ks = 0; ks < DK / 16; ++ks)
; #pragma unroll
;       for (int j = 0; j < 2; ++j) {
;         const bf16x8 kf = *(const bf16x8*)(Ks + (32 * j + l31) * KR + 16 * ks + 8 * h2);
;         Sx[j] = MFMA32(kf, qf[ks], Sx[j]);
;       }
;     if (BAND) {
; #pragma unroll
;       for (int j = 0; j < 2; ++j)
; #pragma unroll
;         for (int r = 0; r < 16; ++r) {
;           const int u = u0 + 64 * kt + 32 * j + crow(r, h2);
;           const int d = u - tq;
;           const bool valid = (d <= 64) && (d >= -64) && (u >= 0) && (u < L);
;           Sx[j][r] = valid ? Sx[j][r] : -1e30f;
;         }
;     }
;     float mx = Sx[0][0];
; #pragma unroll
;     for (int j = 0; j < 2; ++j)
; #pragma unroll
;       for (int r = 0; r < 16; ++r) mx = fmaxf(mx, Sx[j][r]);
;     mx = xhalf_max(mx);
;     if (__any(mx - m > DEFER_THR)) {
;       const float mn = fmaxf(m, mx);
;       const float alpha = exp2_(m - mn);
;       m = mn;
;       l *= alpha;
; #pragma unroll
;       for (int t = 0; t < 2; ++t)
; #pragma unroll
;         for (int r = 0; r < 16; ++r) O[t][r] *= alpha;
;     }
;     ...
;           const bf16_t* vp = Vs + (32 * j + 16 * s) * 72 + 32 * t + troff;
;           const bf16x8 vf = tr_pair(vp, vp + 8 * 72);
.LBB0_849:
	ds_read_b128 v[34:37], v143
	ds_read_b128 v[150:153], v143 offset:32
	s_waitcnt lgkmcnt(1)
	v_mfma_f32_32x32x16_bf16 v[50:65], v[34:37], v[66:69], v[190:205]
	ds_read_b128 v[34:37], v143 offset:6656
	s_waitcnt lgkmcnt(1)
	v_mfma_f32_32x32x16_bf16 v[50:65], v[150:153], v[70:73], v[50:65]
	ds_read_b128 v[150:153], v143 offset:6688
	s_waitcnt lgkmcnt(1)
	v_mfma_f32_32x32x16_bf16 v[34:49], v[34:37], v[66:69], v[190:205]
	s_waitcnt lgkmcnt(0)
	v_mfma_f32_32x32x16_bf16 v[34:49], v[150:153], v[70:73], v[34:49]
	ds_read_b128 v[150:153], v143 offset:64
	s_waitcnt lgkmcnt(0)
	v_mfma_f32_32x32x16_bf16 v[50:65], v[150:153], v[74:77], v[50:65]
	ds_read_b128 v[150:153], v143 offset:6720
	s_waitcnt lgkmcnt(0)
	v_mfma_f32_32x32x16_bf16 v[34:49], v[150:153], v[74:77], v[34:49]
	ds_read_b128 v[150:153], v143 offset:96
	s_waitcnt lgkmcnt(0)
	v_mfma_f32_32x32x16_bf16 v[50:65], v[150:153], v[78:81], v[50:65]
	ds_read_b128 v[150:153], v143 offset:6752
	s_waitcnt lgkmcnt(0)
	v_mfma_f32_32x32x16_bf16 v[34:49], v[150:153], v[78:81], v[34:49]
	ds_read_b128 v[150:153], v143 offset:128
	s_waitcnt lgkmcnt(0)
	v_mfma_f32_32x32x16_bf16 v[50:65], v[150:153], v[82:85], v[50:65]
	ds_read_b128 v[150:153], v143 offset:6784
	s_waitcnt lgkmcnt(0)
	v_mfma_f32_32x32x16_bf16 v[34:49], v[150:153], v[82:85], v[34:49]
	ds_read_b128 v[150:153], v143 offset:160
	s_waitcnt lgkmcnt(0)
	v_mfma_f32_32x32x16_bf16 v[50:65], v[150:153], v[86:89], v[50:65]
	ds_read_b128 v[150:153], v143 offset:6816
	s_waitcnt lgkmcnt(0)
	v_mfma_f32_32x32x16_bf16 v[34:49], v[150:153], v[86:89], v[34:49]
	ds_read_b64_tr_b16 v[158:159], v142 offset:13312
	ds_read_b64_tr_b16 v[160:161], v142 offset:14464
	ds_read_b64_tr_b16 v[162:163], v142 offset:13376
	ds_read_b64_tr_b16 v[164:165], v142 offset:14528
	ds_read_b64_tr_b16 v[166:167], v142 offset:15616
	ds_read_b64_tr_b16 v[168:169], v142 offset:16768
	ds_read_b64_tr_b16 v[170:171], v142 offset:15680
	ds_read_b64_tr_b16 v[172:173], v142 offset:16832
	ds_read_b64_tr_b16 v[174:175], v142 offset:17920
	ds_read_b64_tr_b16 v[176:177], v142 offset:19072
	ds_read_b64_tr_b16 v[178:179], v142 offset:17984
	ds_read_b64_tr_b16 v[180:181], v142 offset:19136
	ds_read_b64_tr_b16 v[182:183], v142 offset:20224
	ds_read_b64_tr_b16 v[184:185], v142 offset:21376
	v_max_f32_e32 v0, v51, v51
	v_max_f32_e32 v149, v50, v50
	v_max_f32_e32 v0, v149, v0
	v_max3_f32 v0, v0, v52, v53
	v_max3_f32 v0, v0, v54, v55
	v_max3_f32 v0, v0, v56, v57
	v_max3_f32 v0, v0, v58, v59
	v_max3_f32 v0, v0, v60, v61
	v_max3_f32 v0, v0, v62, v63
	v_max3_f32 v0, v0, v64, v65
	v_max3_f32 v0, v0, v34, v35
	v_max3_f32 v0, v0, v36, v37
	v_max3_f32 v0, v0, v38, v39
	v_max3_f32 v0, v0, v40, v41
	v_max3_f32 v0, v0, v42, v43
	v_max3_f32 v0, v0, v44, v45
	v_max3_f32 v0, v0, v46, v47
	v_max3_f32 v0, v0, v48, v49
	v_mov_b32_e32 v149, v0
	s_nop 1
	v_permlane32_swap_b32_e32 v0, v149
	ds_read_b64_tr_b16 v[186:187], v142 offset:20288
	ds_read_b64_tr_b16 v[188:189], v142 offset:21440
	v_max_f32_e32 v149, v149, v149
	v_max_f32_e32 v0, v0, v0
	v_max_f32_e32 v0, v0, v149
	v_sub_f32_e32 v0, v0, v190
	v_sub_f32_e32 v149, v0, v147
	v_cmp_lt_f32_e32 vcc, s22, v149
	s_cbranch_vccz .LBB0_851
	v_max_f32_e32 v0, v0, v0
	v_max_f32_e32 v149, v147, v147
	v_max_f32_e32 v149, v149, v0
	v_sub_f32_e32 v0, v147, v149
	v_exp_f32_e32 v0, v0
	v_mov_b32_e32 v147, v149
	v_mul_f32_e32 v148, v148, v0
	v_pk_mul_f32 v[32:33], v[32:33], v[0:1] op_sel_hi:[1,0]
	v_pk_mul_f32 v[30:31], v[30:31], v[0:1] op_sel_hi:[1,0]
	v_pk_mul_f32 v[28:29], v[28:29], v[0:1] op_sel_hi:[1,0]
	v_pk_mul_f32 v[26:27], v[26:27], v[0:1] op_sel_hi:[1,0]
	v_pk_mul_f32 v[24:25], v[24:25], v[0:1] op_sel_hi:[1,0]
	v_pk_mul_f32 v[22:23], v[22:23], v[0:1] op_sel_hi:[1,0]
	v_pk_mul_f32 v[20:21], v[20:21], v[0:1] op_sel_hi:[1,0]
	v_pk_mul_f32 v[18:19], v[18:19], v[0:1] op_sel_hi:[1,0]
	v_pk_mul_f32 v[16:17], v[16:17], v[0:1] op_sel_hi:[1,0]
	v_pk_mul_f32 v[14:15], v[14:15], v[0:1] op_sel_hi:[1,0]
	v_pk_mul_f32 v[12:13], v[12:13], v[0:1] op_sel_hi:[1,0]
	v_pk_mul_f32 v[10:11], v[10:11], v[0:1] op_sel_hi:[1,0]
	v_pk_mul_f32 v[8:9], v[8:9], v[0:1] op_sel_hi:[1,0]
	v_pk_mul_f32 v[6:7], v[6:7], v[0:1] op_sel_hi:[1,0]
	v_pk_mul_f32 v[4:5], v[4:5], v[0:1] op_sel_hi:[1,0]
	v_pk_mul_f32 v[2:3], v[2:3], v[0:1] op_sel_hi:[1,0]
	v_add_f32_e32 v206, v147, v190
	v_sub_f32_e32 v50, v50, v206
	v_sub_f32_e32 v51, v51, v206
	v_sub_f32_e32 v52, v52, v206
	v_sub_f32_e32 v53, v53, v206
	v_sub_f32_e32 v54, v54, v206
	v_sub_f32_e32 v55, v55, v206
	v_sub_f32_e32 v56, v56, v206
	v_sub_f32_e32 v57, v57, v206
	v_sub_f32_e32 v58, v58, v206
	v_sub_f32_e32 v59, v59, v206
	v_sub_f32_e32 v60, v60, v206
	v_sub_f32_e32 v61, v61, v206
	v_sub_f32_e32 v62, v62, v206
	v_sub_f32_e32 v63, v63, v206
	v_sub_f32_e32 v64, v64, v206
	v_sub_f32_e32 v65, v65, v206
	v_sub_f32_e32 v34, v34, v206
	v_sub_f32_e32 v35, v35, v206
	v_sub_f32_e32 v36, v36, v206
	v_sub_f32_e32 v37, v37, v206
	v_sub_f32_e32 v38, v38, v206
	v_sub_f32_e32 v39, v39, v206
	v_sub_f32_e32 v40, v40, v206
	v_sub_f32_e32 v41, v41, v206
	v_sub_f32_e32 v42, v42, v206
	v_sub_f32_e32 v43, v43, v206
	v_sub_f32_e32 v44, v44, v206
	v_sub_f32_e32 v45, v45, v206
	v_sub_f32_e32 v46, v46, v206
	v_sub_f32_e32 v47, v47, v206
	v_sub_f32_e32 v48, v48, v206
	v_sub_f32_e32 v49, v49, v206
	v_sub_f32_e32 v190, 0, v147
	v_sub_f32_e32 v191, 0, v147
	v_sub_f32_e32 v192, 0, v147
	v_sub_f32_e32 v193, 0, v147
	v_sub_f32_e32 v194, 0, v147
	v_sub_f32_e32 v195, 0, v147
	v_sub_f32_e32 v196, 0, v147
	v_sub_f32_e32 v197, 0, v147
	v_sub_f32_e32 v198, 0, v147
	v_sub_f32_e32 v199, 0, v147
	v_sub_f32_e32 v200, 0, v147
	v_sub_f32_e32 v201, 0, v147
	v_sub_f32_e32 v202, 0, v147
	v_sub_f32_e32 v203, 0, v147
	v_sub_f32_e32 v204, 0, v147
	v_sub_f32_e32 v205, 0, v147
; #define MFMA32(a, b, c) __builtin_amdgcn_mfma_f32_32x32x16_bf16((a), (b), (c), 0, 0, 0)
; DI float exp2_(float x) { return __builtin_amdgcn_exp2f(x); }
; template <int DK, bool BAND>
; DI void flash_loop(f32x16 (&O)[2], float& m, float& l, const bf16_t* __restrict__ qrow, const bf16_t* __restrict__ kbase,
;                    size_t kstride, const bf16_t* __restrict__ vbase, size_t vstride, int ntiles, int tq, int u0, int L,
;                    char* lds) {
;     ...
;     __syncthreads();
;     if (par == 0) {
;       if (kt + 1 < ntiles) swrite((kt + 1) & 1, rkA, rvA);
;       if (kt + 3 < ntiles) gload(kt + 3, rkA, rvA);
;     } else {
;       if (kt + 1 < ntiles) swrite((kt + 1) & 1, rkB, rvB);
;       if (kt + 3 < ntiles) gload(kt + 3, rkB, rvB);
;     }
;     ...
;     float ls = 0.f;
; #pragma unroll
;     for (int j = 0; j < 2; ++j)
; #pragma unroll
;       for (int r = 0; r < 16; ++r) { const float pv = exp2_(Sx[j][r] - m); Sx[j][r] = pv; ls += pv; }
;     l += ls;
; #pragma unroll
;     for (int j = 0; j < 2; ++j)
; #pragma unroll
;       for (int s = 0; s < 2; ++s) {
;         const bf16x8 pf = pack8(Sx[j][8 * s], Sx[j][8 * s + 1], Sx[j][8 * s + 2], Sx[j][8 * s + 3], Sx[j][8 * s + 4],
;                                 Sx[j][8 * s + 5], Sx[j][8 * s + 6], Sx[j][8 * s + 7]);
; #pragma unroll
;         for (int t = 0; t < 2; ++t) {
;           const bf16_t* vp = Vs + (32 * j + 16 * s) * 72 + 32 * t + troff;
;           const bf16x8 vf = tr_pair(vp, vp + 8 * 72);
;           O[t] = MFMA32(vf, pf, O[t]);
;         }
;       }
.LBB0_851:
	v_exp_f32_e32 v0, v50
	v_exp_f32_e32 v50, v51
	v_exp_f32_e32 v51, v52
	v_exp_f32_e32 v52, v53
	v_exp_f32_e32 v53, v54
	v_exp_f32_e32 v54, v55
	v_exp_f32_e32 v55, v56
	v_exp_f32_e32 v56, v57
	v_cvt_pk_bf16_f32 v150, v0, v50
	v_cvt_pk_bf16_f32 v151, v51, v52
	v_cvt_pk_bf16_f32 v152, v53, v54
	v_cvt_pk_bf16_f32 v153, v55, v56
	s_waitcnt lgkmcnt(0)
	v_mfma_f32_32x32x16_bf16 v[2:17], v[158:161], v[150:153], v[2:17]
	v_exp_f32_e32 v57, v58
	v_exp_f32_e32 v58, v59
	v_exp_f32_e32 v59, v60
	v_exp_f32_e32 v60, v61
	v_exp_f32_e32 v61, v62
	v_exp_f32_e32 v62, v63
	v_exp_f32_e32 v63, v64
	v_exp_f32_e32 v64, v65
	s_waitcnt lgkmcnt(0)
	v_mfma_f32_32x32x16_bf16 v[18:33], v[162:165], v[150:153], v[18:33]
	v_cvt_pk_bf16_f32 v150, v57, v58
	v_cvt_pk_bf16_f32 v151, v59, v60
	v_cvt_pk_bf16_f32 v152, v61, v62
	v_cvt_pk_bf16_f32 v153, v63, v64
	s_waitcnt lgkmcnt(0)
	v_mfma_f32_32x32x16_bf16 v[2:17], v[166:169], v[150:153], v[2:17]
	v_exp_f32_e32 v34, v34
	v_exp_f32_e32 v35, v35
	v_exp_f32_e32 v36, v36
	v_exp_f32_e32 v37, v37
	v_exp_f32_e32 v38, v38
	v_exp_f32_e32 v39, v39
	v_exp_f32_e32 v40, v40
	v_exp_f32_e32 v41, v41
	s_waitcnt lgkmcnt(0)
	v_mfma_f32_32x32x16_bf16 v[18:33], v[170:173], v[150:153], v[18:33]
	v_cvt_pk_bf16_f32 v150, v34, v35
	v_cvt_pk_bf16_f32 v151, v36, v37
	v_cvt_pk_bf16_f32 v152, v38, v39
	v_cvt_pk_bf16_f32 v153, v40, v41
	s_waitcnt lgkmcnt(0)
	v_mfma_f32_32x32x16_bf16 v[2:17], v[174:177], v[150:153], v[2:17]
	v_exp_f32_e32 v42, v42
	v_exp_f32_e32 v43, v43
	v_exp_f32_e32 v44, v44
	v_exp_f32_e32 v45, v45
	v_exp_f32_e32 v46, v46
	v_exp_f32_e32 v47, v47
	v_exp_f32_e32 v48, v48
	v_exp_f32_e32 v49, v49
	s_waitcnt lgkmcnt(0)
	v_mfma_f32_32x32x16_bf16 v[18:33], v[178:181], v[150:153], v[18:33]
	v_cvt_pk_bf16_f32 v150, v42, v43
	v_cvt_pk_bf16_f32 v151, v44, v45
	v_cvt_pk_bf16_f32 v152, v46, v47
	v_cvt_pk_bf16_f32 v153, v48, v49
	s_cmp_ge_u32 s7, s40
	s_waitcnt lgkmcnt(0)
	v_mfma_f32_32x32x16_bf16 v[2:17], v[182:185], v[150:153], v[2:17]
	s_waitcnt lgkmcnt(0)
	s_barrier
	v_mfma_f32_32x32x16_bf16 v[18:33], v[186:189], v[150:153], v[18:33]
	s_cbranch_scc1 .LBB0_853
	s_waitcnt vmcnt(4)
	ds_write_b128 v137, v[102:105]
	s_waitcnt vmcnt(3)
	ds_write_b128 v138, v[110:113]
	s_waitcnt vmcnt(2)
	ds_write_b128 v139, v[118:121]
	s_waitcnt vmcnt(1)
	ds_write_b128 v140, v[122:125] offset:13312
	s_waitcnt vmcnt(0)
	ds_write_b128 v141, v[126:129] offset:13312

; #define MFMA32(a, b, c) __builtin_amdgcn_mfma_f32_32x32x16_bf16((a), (b), (c), 0, 0, 0)
; DI float exp2_(float x) { return __builtin_amdgcn_exp2f(x); }
; DI int crow(int r, int h2) { return (r & 3) + 8 * (r >> 2) + 4 * h2; }
; template <int DK, bool BAND>
; DI void flash_loop(f32x16 (&O)[2], float& m, float& l, const bf16_t* __restrict__ qrow, const bf16_t* __restrict__ kbase,
;                    size_t kstride, const bf16_t* __restrict__ vbase, size_t vstride, int ntiles, int tq, int u0, int L,
;                    char* lds) {
;     ...
; #pragma unroll
;     for (int ks = 0; ks < DK / 16; ++ks)
; #pragma unroll
;       for (int j = 0; j < 2; ++j) {
;         const bf16x8 kf = *(const bf16x8*)(Ks + (32 * j + l31) * KR + 16 * ks + 8 * h2);
;         Sx[j] = MFMA32(kf, qf[ks], Sx[j]);
;       }
;     if (BAND) {
; #pragma unroll
;       for (int j = 0; j < 2; ++j)
; #pragma unroll
;         for (int r = 0; r < 16; ++r) {
;           const int u = u0 + 64 * kt + 32 * j + crow(r, h2);
;           const int d = u - tq;
;           const bool valid = (d <= 64) && (d >= -64) && (u >= 0) && (u < L);
;           Sx[j][r] = valid ? Sx[j][r] : -1e30f;
;         }
;     }
;     float mx = Sx[0][0];
; #pragma unroll
;     for (int j = 0; j < 2; ++j)
; #pragma unroll
;       for (int r = 0; r < 16; ++r) mx = fmaxf(mx, Sx[j][r]);
;     mx = xhalf_max(mx);
;     if (__any(mx - m > DEFER_THR)) {
;       const float mn = fmaxf(m, mx);
;       const float alpha = exp2_(m - mn);
;       m = mn;
;       l *= alpha;
; #pragma unroll
;       for (int t = 0; t < 2; ++t)
; #pragma unroll
;         for (int r = 0; r < 16; ++r) O[t][r] *= alpha;
;     }
;     float ls = 0.f;
; #pragma unroll
;     for (int j = 0; j < 2; ++j)
; #pragma unroll
;       for (int r = 0; r < 16; ++r) { const float pv = exp2_(Sx[j][r] - m); Sx[j][r] = pv; ls += pv; }
;     l += ls;
;     ...
;           const bf16_t* vp = Vs + (32 * j + 16 * s) * 72 + 32 * t + troff;
;           const bf16x8 vf = tr_pair(vp, vp + 8 * 72);
.LBB0_855:
	v_add_f32_e32 v0, 0, v0
	v_add_f32_e32 v0, v50, v0
	v_add_f32_e32 v0, v51, v0
	v_add_f32_e32 v0, v52, v0
	v_add_f32_e32 v0, v53, v0
	v_add_f32_e32 v0, v54, v0
	v_add_f32_e32 v0, v55, v0
	v_add_f32_e32 v0, v56, v0
	v_add_f32_e32 v0, v57, v0
	v_add_f32_e32 v0, v58, v0
	v_add_f32_e32 v0, v59, v0
	v_add_f32_e32 v0, v60, v0
	v_add_f32_e32 v0, v61, v0
	v_add_f32_e32 v0, v62, v0
	v_add_f32_e32 v0, v63, v0
	v_add_f32_e32 v0, v64, v0
	v_add_f32_e32 v0, v34, v0
	v_add_f32_e32 v0, v35, v0
	v_add_f32_e32 v0, v36, v0
	v_add_f32_e32 v0, v37, v0
	v_add_f32_e32 v0, v38, v0
	v_add_f32_e32 v0, v39, v0
	v_add_f32_e32 v0, v40, v0
	v_add_f32_e32 v0, v41, v0
	v_add_f32_e32 v0, v42, v0
	v_add_f32_e32 v0, v43, v0
	v_add_f32_e32 v0, v44, v0
	v_add_f32_e32 v0, v45, v0
	v_add_f32_e32 v0, v46, v0
	v_add_f32_e32 v0, v47, v0
	v_add_f32_e32 v0, v48, v0
	v_add_f32_e32 v0, v49, v0
	v_add_f32_e32 v0, v148, v0
	ds_read_b128 v[34:37], v143 offset:22528
	ds_read_b128 v[148:151], v143 offset:22560
	s_waitcnt lgkmcnt(1)
	v_mfma_f32_32x32x16_bf16 v[50:65], v[34:37], v[66:69], v[190:205]
	ds_read_b128 v[34:37], v143 offset:29184
	s_waitcnt lgkmcnt(1)
	v_mfma_f32_32x32x16_bf16 v[50:65], v[148:151], v[70:73], v[50:65]
	ds_read_b128 v[148:151], v143 offset:29216
	s_waitcnt lgkmcnt(1)
	v_mfma_f32_32x32x16_bf16 v[34:49], v[34:37], v[66:69], v[190:205]
	s_waitcnt lgkmcnt(0)
	v_mfma_f32_32x32x16_bf16 v[34:49], v[148:151], v[70:73], v[34:49]
	ds_read_b128 v[148:151], v143 offset:22592
	s_waitcnt lgkmcnt(0)
	v_mfma_f32_32x32x16_bf16 v[50:65], v[148:151], v[74:77], v[50:65]
	ds_read_b128 v[148:151], v143 offset:29248
	s_waitcnt lgkmcnt(0)
	v_mfma_f32_32x32x16_bf16 v[34:49], v[148:151], v[74:77], v[34:49]
	ds_read_b128 v[148:151], v143 offset:22624
	s_waitcnt lgkmcnt(0)
	v_mfma_f32_32x32x16_bf16 v[50:65], v[148:151], v[78:81], v[50:65]
	ds_read_b128 v[148:151], v143 offset:29280
	s_waitcnt lgkmcnt(0)
	v_mfma_f32_32x32x16_bf16 v[34:49], v[148:151], v[78:81], v[34:49]
	ds_read_b128 v[148:151], v143 offset:22656
	s_waitcnt lgkmcnt(0)
	v_mfma_f32_32x32x16_bf16 v[50:65], v[148:151], v[82:85], v[50:65]
	ds_read_b128 v[148:151], v143 offset:29312
	s_waitcnt lgkmcnt(0)
	v_mfma_f32_32x32x16_bf16 v[34:49], v[148:151], v[82:85], v[34:49]
	ds_read_b128 v[148:151], v143 offset:22688
	s_waitcnt lgkmcnt(0)
	v_mfma_f32_32x32x16_bf16 v[50:65], v[148:151], v[86:89], v[50:65]
	ds_read_b128 v[148:151], v143 offset:29344
	s_waitcnt lgkmcnt(0)
	v_mfma_f32_32x32x16_bf16 v[34:49], v[148:151], v[86:89], v[34:49]
	ds_read_b64_tr_b16 v[158:159], v142 offset:35840
	ds_read_b64_tr_b16 v[160:161], v142 offset:36992
	ds_read_b64_tr_b16 v[162:163], v142 offset:35904
	ds_read_b64_tr_b16 v[164:165], v142 offset:37056
	ds_read_b64_tr_b16 v[166:167], v142 offset:38144
	ds_read_b64_tr_b16 v[168:169], v142 offset:39296
	ds_read_b64_tr_b16 v[170:171], v142 offset:38208
	ds_read_b64_tr_b16 v[172:173], v142 offset:39360
	ds_read_b64_tr_b16 v[174:175], v142 offset:40448
	ds_read_b64_tr_b16 v[176:177], v142 offset:41600
	ds_read_b64_tr_b16 v[178:179], v142 offset:40512
	ds_read_b64_tr_b16 v[180:181], v142 offset:41664
	ds_read_b64_tr_b16 v[182:183], v142 offset:42752
	ds_read_b64_tr_b16 v[184:185], v142 offset:43904
	v_max_f32_e32 v148, v51, v51
	v_max_f32_e32 v149, v50, v50
	v_max_f32_e32 v148, v149, v148
	v_max3_f32 v148, v148, v52, v53
	v_max3_f32 v148, v148, v54, v55
	v_max3_f32 v148, v148, v56, v57
	v_max3_f32 v148, v148, v58, v59
	v_max3_f32 v148, v148, v60, v61
	v_max3_f32 v148, v148, v62, v63
	v_max3_f32 v148, v148, v64, v65
	v_max3_f32 v148, v148, v34, v35
	v_max3_f32 v148, v148, v36, v37
	v_max3_f32 v148, v148, v38, v39
	v_max3_f32 v148, v148, v40, v41
	v_max3_f32 v148, v148, v42, v43
	v_max3_f32 v148, v148, v44, v45
	v_max3_f32 v148, v148, v46, v47
	v_max3_f32 v148, v148, v48, v49
	v_mov_b32_e32 v149, v148
	s_nop 1
	v_permlane32_swap_b32_e32 v148, v149
	ds_read_b64_tr_b16 v[186:187], v142 offset:42816
	ds_read_b64_tr_b16 v[188:189], v142 offset:43968
	v_max_f32_e32 v149, v149, v149
	v_max_f32_e32 v148, v148, v148
	v_max_f32_e32 v148, v148, v149
	v_sub_f32_e32 v148, v148, v190
	v_sub_f32_e32 v149, v148, v147
	v_cmp_lt_f32_e32 vcc, s22, v149
	s_cbranch_vccz .LBB0_844
	v_max_f32_e32 v148, v148, v148
	v_max_f32_e32 v149, v147, v147
	v_max_f32_e32 v149, v149, v148
	v_sub_f32_e32 v147, v147, v149
	v_exp_f32_e32 v148, v147
	v_mov_b32_e32 v147, v149
	v_mul_f32_e32 v0, v0, v148
	v_pk_mul_f32 v[32:33], v[32:33], v[148:149] op_sel_hi:[1,0]
	v_pk_mul_f32 v[30:31], v[30:31], v[148:149] op_sel_hi:[1,0]
	v_pk_mul_f32 v[28:29], v[28:29], v[148:149] op_sel_hi:[1,0]
	v_pk_mul_f32 v[26:27], v[26:27], v[148:149] op_sel_hi:[1,0]
	v_pk_mul_f32 v[24:25], v[24:25], v[148:149] op_sel_hi:[1,0]
	v_pk_mul_f32 v[22:23], v[22:23], v[148:149] op_sel_hi:[1,0]
	v_pk_mul_f32 v[20:21], v[20:21], v[148:149] op_sel_hi:[1,0]
	v_pk_mul_f32 v[18:19], v[18:19], v[148:149] op_sel_hi:[1,0]
	v_pk_mul_f32 v[16:17], v[16:17], v[148:149] op_sel_hi:[1,0]
	v_pk_mul_f32 v[14:15], v[14:15], v[148:149] op_sel_hi:[1,0]
	v_pk_mul_f32 v[12:13], v[12:13], v[148:149] op_sel_hi:[1,0]
	v_pk_mul_f32 v[10:11], v[10:11], v[148:149] op_sel_hi:[1,0]
	v_pk_mul_f32 v[8:9], v[8:9], v[148:149] op_sel_hi:[1,0]
	v_pk_mul_f32 v[6:7], v[6:7], v[148:149] op_sel_hi:[1,0]
	v_pk_mul_f32 v[4:5], v[4:5], v[148:149] op_sel_hi:[1,0]
	v_pk_mul_f32 v[2:3], v[2:3], v[148:149] op_sel_hi:[1,0]
	v_add_f32_e32 v206, v147, v190
	v_sub_f32_e32 v50, v50, v206
	v_sub_f32_e32 v51, v51, v206
	v_sub_f32_e32 v52, v52, v206
	v_sub_f32_e32 v53, v53, v206
	v_sub_f32_e32 v54, v54, v206
	v_sub_f32_e32 v55, v55, v206
	v_sub_f32_e32 v56, v56, v206
	v_sub_f32_e32 v57, v57, v206
	v_sub_f32_e32 v58, v58, v206
	v_sub_f32_e32 v59, v59, v206
	v_sub_f32_e32 v60, v60, v206
	v_sub_f32_e32 v61, v61, v206
	v_sub_f32_e32 v62, v62, v206
	v_sub_f32_e32 v63, v63, v206
	v_sub_f32_e32 v64, v64, v206
	v_sub_f32_e32 v65, v65, v206
	v_sub_f32_e32 v34, v34, v206
	v_sub_f32_e32 v35, v35, v206
	v_sub_f32_e32 v36, v36, v206
	v_sub_f32_e32 v37, v37, v206
	v_sub_f32_e32 v38, v38, v206
	v_sub_f32_e32 v39, v39, v206
	v_sub_f32_e32 v40, v40, v206
	v_sub_f32_e32 v41, v41, v206
	v_sub_f32_e32 v42, v42, v206
	v_sub_f32_e32 v43, v43, v206
	v_sub_f32_e32 v44, v44, v206
	v_sub_f32_e32 v45, v45, v206
	v_sub_f32_e32 v46, v46, v206
	v_sub_f32_e32 v47, v47, v206
	v_sub_f32_e32 v48, v48, v206
	v_sub_f32_e32 v49, v49, v206
	v_sub_f32_e32 v190, 0, v147
	v_sub_f32_e32 v191, 0, v147
	v_sub_f32_e32 v192, 0, v147
	v_sub_f32_e32 v193, 0, v147
	v_sub_f32_e32 v194, 0, v147
	v_sub_f32_e32 v195, 0, v147
	v_sub_f32_e32 v196, 0, v147
	v_sub_f32_e32 v197, 0, v147
	v_sub_f32_e32 v198, 0, v147
	v_sub_f32_e32 v199, 0, v147
	v_sub_f32_e32 v200, 0, v147
	v_sub_f32_e32 v201, 0, v147
	v_sub_f32_e32 v202, 0, v147
	v_sub_f32_e32 v203, 0, v147
	v_sub_f32_e32 v204, 0, v147
	v_sub_f32_e32 v205, 0, v147
	s_branch .LBB0_844

; DI unsigned pack2(float a, float b) { f2_t v = {a, b}; return __builtin_bit_cast(unsigned, __builtin_convertvector(v, bf2_t)); }
; DI float exp2_(float x) { return __builtin_amdgcn_exp2f(x); }
; DI int opq() { int z; asm volatile("v_mov_b32 %0, 0" : "=v"(z)); return z; }
; DI void phase_combine(CParams& p, int layer, const float* __restrict__ xg) {
;   const int tidq = threadIdx.x + opq(); const int wave = tidq >> 6, lane = tidq & 63;
;   const bf16_t* PR = (const bf16_t*)(p.ws + OFF_PR);
;   const bf16_t* OD = (const bf16_t*)(p.ws + OFF_OD);
;   const float* LSE = (const float*)(p.ws + OFF_LSE);
;   const bf16_t* OFb = (const bf16_t*)(p.ws + OFF_OF);
;   const bf16_t* OBb = (const bf16_t*)(p.ws + OFF_OB);
;   bf16_t* Y = (bf16_t*)(p.ws + OFF_N);
;   bf16_t* Np = (bf16_t*)(p.ws + OFF_Q);
;   const float* gmix = p.norm_mix + layer * 1024;
;   const float* gdn = p.dn_out_norm + layer * 64;
;   const int head = lane >> 4;
;   for (int r = blockIdx.x * 4 + wave; r < TG; r += gridDim.x * 4) {
;     {
;       float lg[3];
; #pragma unroll
;       for (int g = 0; g < 3; ++g) lg[g] = LSE[((size_t)g * TG + r) * 4 + head];
;       const float mx = fmaxf(lg[0], fmaxf(lg[1], lg[2]));
;       float wg[3], den = 0.f;
; #pragma unroll
;       for (int g = 0; g < 3; ++g) { wg[g] = exp2_(lg[g] - mx); den += wg[g]; }
;       const float id = 1.f / den;
;       float o[4] = {0.f, 0.f, 0.f, 0.f};
; #pragma unroll
;       for (int g = 0; g < 3; ++g) {
;         const u32x2 u = ((const u32x2*)(OD + ((size_t)g * TG + r) * 256))[lane];
;         const float c = wg[g] * id;
;         o[0] += c * __uint_as_float(u.x << 16); o[1] += c * __uint_as_float(u.x & 0xffff0000u);
;         o[2] += c * __uint_as_float(u.y << 16); o[3] += c * __uint_as_float(u.y & 0xffff0000u);
;       }
;       u32x2 ou; ou.x = pack2(o[0], o[1]); ou.y = pack2(o[2], o[3]);
;       ((u32x2*)(Y + (size_t)r * 1024 + 768))[lane] = ou;
.LBB0_905:
	s_or_b64 exec, exec, s[0:1]
	s_mov_b64 s[24:25], s[94:95]
	s_waitcnt lgkmcnt(0)
	s_barrier
	v_mov_b32 v0, 0
	s_mov_b32 s0, 0x8000
	v_add_u32_e32 v2, v0, v210
	v_ashrrev_i32_e32 v0, 6, v2
	v_add_u32_e32 v18, s93, v0
	v_cmp_gt_i32_e32 vcc, s0, v18
	s_and_saveexec_b64 s[0:1], vcc
	s_mov_b32 s38, 0x3a800000
	s_mov_b32 s39, 0x3c800000
	s_movk_i32 s28, 0x7fff
	s_cbranch_execz .LBB0_908
	s_load_dwordx4 s[44:47], s[24:25], 0xf8
	s_load_dwordx2 s[8:9], s[24:25], 0x40
	s_lshl_b64 s[6:7], s[58:59], 2
	v_readlane_b32 s34, v243, 38
	s_load_dwordx2 s[24:25], s[24:25], 0x98
	s_waitcnt lgkmcnt(0)
	s_add_u32 s6, s44, s6
	v_readlane_b32 s35, v243, 39
	s_addc_u32 s7, s45, s7
	s_lshl_b64 s[34:35], s[34:35], 2
	s_add_u32 s8, s8, s34
	s_addc_u32 s9, s9, s35
	s_lshl_b64 s[34:35], s[36:37], 2
	v_lshrrev_b32_e32 v0, 2, v2
	v_and_b32_e32 v4, 63, v2
	s_add_u32 s24, s24, s34
	v_and_b32_e32 v0, 12, v0
	s_addc_u32 s25, s25, s35
	v_lshl_add_u64 v[6:7], s[46:47], 0, v[0:1]
	s_mov_b64 s[34:35], 0x21200000
	v_lshlrev_b32_e32 v0, 3, v4
	v_and_b32_e32 v3, 64, v225
	v_lshl_add_u64 v[20:21], v[6:7], 0, s[34:35]
	v_lshl_add_u64 v[6:7], s[46:47], 0, v[0:1]
	v_xor_b32_e32 v0, 1, v225
	v_add_u32_e32 v3, 64, v3
	v_cmp_lt_i32_e32 vcc, v0, v3
	s_mov_b64 s[34:35], 0x1e200000
	v_lshl_add_u64 v[22:23], v[6:7], 0, s[34:35]
	v_cndmask_b32_e32 v0, v225, v0, vcc
	v_lshlrev_b32_e32 v46, 2, v0
	v_xor_b32_e32 v0, 2, v225
	v_cmp_lt_i32_e32 vcc, v0, v3
	s_mov_b64 s[34:35], 0x21400000
	v_lshl_add_u64 v[24:25], v[6:7], 0, s[34:35]
	v_cndmask_b32_e32 v0, v225, v0, vcc
	v_lshlrev_b32_e32 v47, 2, v0
	v_xor_b32_e32 v0, 4, v225
	v_cmp_lt_i32_e32 vcc, v0, v3
	s_mov_b64 s[34:35], 0x22400000
	v_lshl_add_u64 v[26:27], v[6:7], 0, s[34:35]
	v_cndmask_b32_e32 v0, v225, v0, vcc
	v_lshlrev_b32_e32 v48, 2, v0
	v_xor_b32_e32 v0, 8, v225
	v_cmp_lt_i32_e32 vcc, v0, v3
	s_nop 1
	v_cndmask_b32_e32 v0, v225, v0, vcc
	v_lshlrev_b32_e32 v49, 2, v0
	v_and_b32_e32 v0, 15, v2
	v_lshlrev_b32_e32 v0, 4, v0
	v_lshl_add_u64 v[28:29], s[24:25], 0, v[0:1]
	v_xor_b32_e32 v0, 32, v225
	v_cmp_lt_i32_e32 vcc, v0, v3
	s_nop 1
	v_cndmask_b32_e32 v0, v225, v0, vcc
	v_lshlrev_b32_e32 v50, 2, v0
	v_xor_b32_e32 v0, 16, v225
	v_cmp_lt_i32_e32 vcc, v0, v3
	s_nop 1
	v_cndmask_b32_e32 v0, v225, v0, vcc
	v_lshlrev_b32_e32 v51, 2, v0
	v_lshlrev_b32_e32 v0, 4, v4
	v_lshl_add_u64 v[30:31], s[8:9], 0, v[0:1]
	s_mov_b64 s[8:9], 0x4000000
	v_lshl_add_u64 v[34:35], s[6:7], 0, v[0:1]
	s_mov_b64 s[6:7], 0x1a000000
	v_lshl_add_u64 v[32:33], v[6:7], 0, s[8:9]
	v_lshl_add_u64 v[36:37], v[6:7], 0, s[6:7]
	s_mov_b64 s[6:7], 0
	v_lshlrev_b32_e32 v0, 3, v4
	global_load_dwordx4 v[74:77], v[30:31], off
	global_load_dwordx4 v[78:81], v[30:31], off offset:1024
	global_load_dwordx4 v[82:85], v[30:31], off offset:2048
	global_load_dwordx4 v[86:89], v[30:31], off offset:3072
.LBB0_907:
	v_ashrrev_i32_e32 v19, 31, v18
	v_lshlrev_b64 v[42:43], 9, v[18:19]
	v_lshl_add_u64 v[8:9], v[22:23], 0, v[42:43]
	s_mov_b32 s8, 0x1000000
	v_lshl_add_u64 v[2:3], v[18:19], 4, v[20:21]
	v_add_co_u32_e64 v10, s[44:45], s8, v8
	v_add_co_u32_e32 v4, vcc, 0x80000, v2
	s_nop 0
	v_addc_co_u32_e64 v11, s[44:45], 0, v9, s[44:45]
	s_brev_b32 s8, 64
	v_addc_co_u32_e32 v5, vcc, 0, v3, vcc
	global_load_dwordx2 v[52:53], v[10:11], off
	v_add_co_u32_e64 v10, s[44:45], s8, v8
	v_add_co_u32_e32 v6, vcc, 0x100000, v2
	s_nop 0
	v_addc_co_u32_e64 v11, s[44:45], 0, v9, s[44:45]
	global_load_dwordx2 v[54:55], v[10:11], off
	v_addc_co_u32_e32 v7, vcc, 0, v3, vcc
	global_load_dword v66, v[2:3], off
	global_load_dword v67, v[4:5], off
	global_load_dword v68, v[6:7], off
	global_load_dwordx2 v[56:57], v[8:9], off
	v_lshlrev_b64 v[38:39], 11, v[18:19]
	v_lshlrev_b64 v[4:5], 12, v[18:19]
	v_mov_b64_e32 v[2:3], s[46:47]
	v_mad_i64_i32 v[2:3], s[8:9], v18, s16, v[2:3]
	v_lshl_add_u64 v[2:3], v[2:3], 0, v[0:1]
	s_brev_b32 s8, 16
	v_add_co_u32_e32 v58, vcc, s8, v2
	v_lshl_add_u64 v[4:5], v[34:35], 0, v[4:5]
	s_nop 0
	v_addc_co_u32_e32 v59, vcc, 0, v3, vcc
	global_load_dwordx4 v[14:17], v[4:5], off
	global_load_dwordx4 v[6:9], v[4:5], off offset:1024
	global_load_dwordx4 v[10:13], v[4:5], off offset:2048
	s_nop 0
	global_load_dwordx4 v[2:5], v[4:5], off offset:3072
	s_nop 0
	global_load_dwordx2 v[58:59], v[58:59], off offset:3840
	v_lshl_add_u64 v[40:41], v[32:33], 0, v[38:39]
	v_lshl_add_u64 v[44:45], v[24:25], 0, v[42:43]
	v_lshl_add_u64 v[42:43], v[26:27], 0, v[42:43]
	v_lshl_add_u64 v[38:39], v[36:37], 0, v[38:39]
	v_add_u32_e32 v18, s56, v18
	s_waitcnt vmcnt(10)
	v_lshlrev_b32_e32 v60, 16, v52
	v_and_b32_e32 v61, 0xffff0000, v52
	v_lshlrev_b32_e32 v52, 16, v53
	v_and_b32_e32 v53, 0xffff0000, v53
	s_waitcnt vmcnt(9)
	v_lshlrev_b32_e32 v62, 16, v54
	v_and_b32_e32 v63, 0xffff0000, v54
	s_waitcnt vmcnt(6)
	v_max3_f32 v19, v66, v67, v68
	s_waitcnt vmcnt(5)
	v_lshlrev_b32_e32 v64, 16, v56
	v_and_b32_e32 v65, 0xffff0000, v56
	v_sub_f32_e32 v56, v66, v19
	v_sub_f32_e32 v66, v67, v19
	v_exp_f32_e32 v67, v56
	v_sub_f32_e32 v19, v68, v19
	v_exp_f32_e32 v68, v66
	v_exp_f32_e32 v19, v19
	v_add_f32_e32 v66, 0, v67
	v_lshlrev_b32_e32 v56, 16, v57
	v_add_f32_e32 v66, v68, v66
	v_add_f32_e32 v66, v19, v66
	v_div_scale_f32 v69, s[8:9], v66, v66, 1.0
	v_rcp_f32_e32 v70, v69
	v_div_scale_f32 v71, vcc, 1.0, v66, 1.0
	v_and_b32_e32 v57, 0xffff0000, v57
	v_fma_f32 v72, -v69, v70, 1.0
	v_fmac_f32_e32 v70, v72, v70
	v_mul_f32_e32 v72, v71, v70
	v_fma_f32 v73, -v69, v72, v71
	v_fmac_f32_e32 v72, v73, v70
	v_fma_f32 v69, -v69, v72, v71
	v_div_fmas_f32 v69, v69, v70, v72
	v_div_fixup_f32 v69, v69, v66, 1.0
	v_mul_f32_e32 v66, v67, v69
	v_mul_f32_e32 v68, v68, v69
	v_pk_fma_f32 v[64:65], v[66:67], v[64:65], 0 op_sel_hi:[0,1,0]
	v_pk_fma_f32 v[56:57], v[66:67], v[56:57], 0 op_sel_hi:[0,1,0]
	v_lshlrev_b32_e32 v54, 16, v55
	v_and_b32_e32 v55, 0xffff0000, v55
	v_mul_f32_e32 v70, v19, v69
	v_pk_fma_f32 v[60:61], v[68:69], v[60:61], v[64:65] op_sel_hi:[0,1,1]
	v_pk_fma_f32 v[52:53], v[68:69], v[52:53], v[56:57] op_sel_hi:[0,1,1]
	v_pk_fma_f32 v[56:57], v[70:71], v[62:63], v[60:61] op_sel_hi:[0,1,1]
	v_pk_fma_f32 v[52:53], v[70:71], v[54:55], v[52:53] op_sel_hi:[0,1,1]
	v_cvt_pk_bf16_f32 v54, v56, v57
	v_cvt_pk_bf16_f32 v55, v52, v53
	global_store_dwordx2 v[40:41], v[54:55], off offset:1536
	global_load_dwordx2 v[52:53], v[44:45], off
	s_waitcnt vmcnt(6)
; DI unsigned pack2(float a, float b) { f2_t v = {a, b}; return __builtin_bit_cast(unsigned, __builtin_convertvector(v, bf2_t)); }
; DI float siluf_(float x) { return x * __builtin_amdgcn_rcpf(1.f + __expf(-x)); }
; DI void phase_combine(CParams& p, int layer, const float* __restrict__ xg) {
;     ...
;       const u32x2 uf = ((const u32x2*)(OFb + (size_t)r * 256))[lane];
;       const u32x2 ub = ((const u32x2*)(OBb + (size_t)r * 256))[lane];
;       const u32x2 uz = ((const u32x2*)(PR + (size_t)r * NPR + C_Z))[lane];
;       float o[4], z[4];
;       o[0] = __uint_as_float(uf.x << 16) + __uint_as_float(ub.x << 16);
;       o[1] = __uint_as_float(uf.x & 0xffff0000u) + __uint_as_float(ub.x & 0xffff0000u);
;       o[2] = __uint_as_float(uf.y << 16) + __uint_as_float(ub.y << 16);
;       o[3] = __uint_as_float(uf.y & 0xffff0000u) + __uint_as_float(ub.y & 0xffff0000u);
;       z[0] = __uint_as_float(uz.x << 16); z[1] = __uint_as_float(uz.x & 0xffff0000u);
;       z[2] = __uint_as_float(uz.y << 16); z[3] = __uint_as_float(uz.y & 0xffff0000u);
;       float ss = o[0] * o[0] + o[1] * o[1] + o[2] * o[2] + o[3] * o[3];
;       ss += __shfl_xor(ss, 1); ss += __shfl_xor(ss, 2); ss += __shfl_xor(ss, 4); ss += __shfl_xor(ss, 8);
;       const float rs = rsqrtf(ss * (1.f / 64.f) + EPS);
;       const float4 gg = ((const float4*)gdn)[lane & 15];
;       u32x2 ou;
;       ou.x = pack2(o[0] * rs * gg.x * siluf_(z[0]), o[1] * rs * gg.y * siluf_(z[1]));
;       ou.y = pack2(o[2] * rs * gg.z * siluf_(z[2]), o[3] * rs * gg.w * siluf_(z[3]));
;       ((u32x2*)(Y + (size_t)r * 1024 + 512))[lane] = ou;
;     }
;     {
;       const float4* xr = (const float4*)(xg + (size_t)r * 1024);
;       float4 v[4];
;       float ss = 0.f;
; #pragma unroll
;       for (int i = 0; i < 4; ++i) { v[i] = xr[lane + 64 * i]; ss += v[i].x * v[i].x + v[i].y * v[i].y + v[i].z * v[i].z + v[i].w * v[i].w; }
;       ss = wave_sum(ss);
;       const float rs = rsqrtf(ss * (1.f / 1024.f) + EPS);
; #pragma unroll
;       for (int i = 0; i < 4; ++i) {
;         const float4 gg = ((const float4*)gmix)[lane + 64 * i];
;         u32x2 o; o.x = pack2(v[i].x * rs * gg.x, v[i].y * rs * gg.y); o.y = pack2(v[i].z * rs * gg.z, v[i].w * rs * gg.w);
;         ((u32x2*)(Np + (size_t)r * 1024))[lane + 64 * i] = o;
;       }
;     }
	v_mov_b32_e32 v64, v15
	global_load_dwordx2 v[54:55], v[42:43], off
	s_waitcnt vmcnt(6)
	v_mov_b32_e32 v65, v7
	global_load_dwordx4 v[42:45], v[28:29], off
	s_waitcnt vmcnt(6)
	v_mov_b32_e32 v72, v11
	s_waitcnt vmcnt(5)
	v_mov_b32_e32 v73, v3
	v_mov_b32_e32 v62, v14
	v_mov_b32_e32 v63, v6
	v_mov_b32_e32 v70, v10
	v_mov_b32_e32 v71, v2
	v_pk_mul_f32 v[64:65], v[64:65], v[64:65]
	v_pk_mul_f32 v[72:73], v[72:73], v[72:73]
	v_mov_b32_e32 v56, v16
	v_mov_b32_e32 v57, v8
	v_mov_b32_e32 v66, v12
	v_mov_b32_e32 v67, v4
	v_pk_fma_f32 v[62:63], v[62:63], v[62:63], v[64:65]
	v_pk_fma_f32 v[64:65], v[70:71], v[70:71], v[72:73]
	v_mov_b32_e32 v60, v17
	v_mov_b32_e32 v61, v9
	v_mov_b32_e32 v68, v13
	v_mov_b32_e32 v69, v5
	v_pk_fma_f32 v[56:57], v[56:57], v[56:57], v[62:63]
	v_pk_fma_f32 v[62:63], v[66:67], v[66:67], v[64:65]
	v_pk_fma_f32 v[56:57], v[60:61], v[60:61], v[56:57]
	v_pk_fma_f32 v[60:61], v[68:69], v[68:69], v[62:63]
	v_pk_add_f32 v[56:57], v[56:57], v[56:57] op_sel:[0,1] op_sel_hi:[1,0]
	s_waitcnt vmcnt(2)
	v_lshlrev_b32_e32 v62, 16, v53
	v_and_b32_e32 v63, 0xffff0000, v53
	v_lshlrev_b32_e32 v64, 16, v52
	v_and_b32_e32 v65, 0xffff0000, v52
	s_waitcnt vmcnt(1)
	v_lshlrev_b32_e32 v52, 16, v54
	v_and_b32_e32 v53, 0xffff0000, v54
	v_pk_add_f32 v[52:53], v[64:65], v[52:53]
	v_pk_add_f32 v[56:57], v[56:57], v[60:61]
	v_pk_mul_f32 v[64:65], v[52:53], v[52:53]
	v_lshlrev_b32_e32 v60, 16, v55
	v_mov_b32_e32 v57, v64
	v_mov_b32_e32 v64, v61
	v_pk_add_f32 v[56:57], v[56:57], v[64:65]
	ds_bpermute_b32 v54, v50, v56
	v_and_b32_e32 v61, 0xffff0000, v55
	v_pk_add_f32 v[60:61], v[62:63], v[60:61]
	v_lshlrev_b32_e32 v64, 16, v58
	v_pk_mul_f32 v[62:63], v[60:61], v[60:61]
	v_and_b32_e32 v65, 0xffff0000, v58
	v_mov_b32_e32 v55, v62
	s_waitcnt lgkmcnt(0)
	v_pk_add_f32 v[54:55], v[56:57], v[54:55]
	ds_bpermute_b32 v62, v51, v54
	v_lshlrev_b32_e32 v56, 16, v59
	v_and_b32_e32 v57, 0xffff0000, v59
	v_mul_f32_e32 v19, 0xbfb8aa3b, v64
	v_exp_f32_e32 v19, v19
	s_waitcnt lgkmcnt(0)
	v_pk_add_f32 v[54:55], v[54:55], v[62:63]
	ds_bpermute_b32 v59, v46, v55
	ds_bpermute_b32 v58, v49, v54
	v_mul_f32_e32 v62, 0xbfb8aa3b, v65
	v_exp_f32_e32 v62, v62
	v_mul_f32_e32 v63, 0xbfb8aa3b, v56
	v_mul_f32_e32 v66, 0xbfb8aa3b, v57
	s_waitcnt lgkmcnt(0)
	v_pk_add_f32 v[54:55], v[54:55], v[58:59]
	ds_bpermute_b32 v59, v47, v55
	ds_bpermute_b32 v58, v48, v54
	v_exp_f32_e32 v63, v63
	v_add_f32_e32 v19, 1.0, v19
	v_exp_f32_e32 v66, v66
	v_add_f32_e32 v67, 1.0, v62
	s_waitcnt lgkmcnt(0)
	v_pk_add_f32 v[54:55], v[54:55], v[58:59]
	ds_bpermute_b32 v59, v48, v55
	ds_bpermute_b32 v58, v47, v54
	v_rcp_f32_e32 v62, v19
	v_add_f32_e32 v68, 1.0, v63
	v_rcp_f32_e32 v63, v67
	v_add_f32_e32 v69, 1.0, v66
	s_waitcnt lgkmcnt(0)
	v_pk_add_f32 v[54:55], v[54:55], v[58:59]
	ds_bpermute_b32 v59, v49, v55
	ds_bpermute_b32 v58, v46, v54
	v_rcp_f32_e32 v66, v68
	v_rcp_f32_e32 v67, v69
	s_waitcnt lgkmcnt(0)
	v_pk_add_f32 v[54:55], v[54:55], v[58:59]
	s_nop 0
	v_pk_fma_f32 v[54:55], v[54:55], s[38:39], v[216:217] op_sel_hi:[1,1,0]
	v_pk_mul_f32 v[58:59], v[62:63], v[64:65]
	v_mul_f32_e32 v19, 0x4b800000, v55
	v_cmp_gt_f32_e32 vcc, s15, v55
	v_pk_mul_f32 v[56:57], v[66:67], v[56:57]
	s_nop 0
	v_cndmask_b32_e32 v19, v55, v19, vcc
	v_rsq_f32_e32 v19, v19
	s_nop 0
	v_mul_f32_e32 v55, 0x45800000, v19
	v_cndmask_b32_e32 v62, v19, v55, vcc
	v_pk_mul_f32 v[52:53], v[52:53], v[62:63] op_sel_hi:[1,0]
	v_pk_mul_f32 v[60:61], v[60:61], v[62:63] op_sel_hi:[1,0]
	s_waitcnt vmcnt(0)
	v_pk_mul_f32 v[42:43], v[42:43], v[52:53]
	v_pk_mul_f32 v[44:45], v[44:45], v[60:61]
	v_pk_mul_f32 v[42:43], v[58:59], v[42:43]
	v_pk_mul_f32 v[44:45], v[56:57], v[44:45]
	v_cvt_pk_bf16_f32 v42, v42, v43
	v_cvt_pk_bf16_f32 v43, v44, v45
	global_store_dwordx2 v[40:41], v[42:43], off offset:1024
	v_mul_f32_e32 v19, 0x4b800000, v54
	v_cmp_gt_f32_e32 vcc, s15, v54
	s_nop 1
	v_cndmask_b32_e32 v19, v54, v19, vcc
	v_rsq_f32_e32 v19, v19
	s_nop 0
	v_mul_f32_e32 v44, 0x45800000, v19
	v_cndmask_b32_e32 v44, v19, v44, vcc
	v_pk_mul_f32 v[14:15], v[14:15], v[44:45] op_sel_hi:[1,0]
	v_pk_mul_f32 v[16:17], v[16:17], v[44:45] op_sel_hi:[1,0]
	v_pk_mul_f32 v[6:7], v[6:7], v[44:45] op_sel_hi:[1,0]
	v_pk_mul_f32 v[8:9], v[8:9], v[44:45] op_sel_hi:[1,0]
	v_pk_mul_f32 v[10:11], v[10:11], v[44:45] op_sel_hi:[1,0]
	v_pk_mul_f32 v[12:13], v[12:13], v[44:45] op_sel_hi:[1,0]
	v_pk_mul_f32 v[2:3], v[2:3], v[44:45] op_sel_hi:[1,0]
	v_pk_mul_f32 v[4:5], v[4:5], v[44:45] op_sel_hi:[1,0]
	v_cmp_lt_i32_e32 vcc, s28, v18
	s_or_b64 s[6:7], vcc, s[6:7]
	v_pk_mul_f32 v[14:15], v[74:75], v[14:15]
	v_pk_mul_f32 v[16:17], v[76:77], v[16:17]
	v_cvt_pk_bf16_f32 v14, v14, v15
	v_cvt_pk_bf16_f32 v15, v16, v17
	global_store_dwordx2 v[38:39], v[14:15], off
	v_pk_mul_f32 v[6:7], v[78:79], v[6:7]
	v_pk_mul_f32 v[8:9], v[80:81], v[8:9]
	v_cvt_pk_bf16_f32 v6, v6, v7
	v_cvt_pk_bf16_f32 v7, v8, v9
	global_store_dwordx2 v[38:39], v[6:7], off offset:512
	v_pk_mul_f32 v[6:7], v[82:83], v[10:11]
	v_pk_mul_f32 v[8:9], v[12:13], v[84:85]
	v_cvt_pk_bf16_f32 v6, v6, v7
	v_cvt_pk_bf16_f32 v7, v8, v9
	global_store_dwordx2 v[38:39], v[6:7], off offset:1024
	v_pk_mul_f32 v[2:3], v[2:3], v[86:87]
	v_pk_mul_f32 v[4:5], v[4:5], v[88:89]
	v_cvt_pk_bf16_f32 v2, v2, v3
	v_cvt_pk_bf16_f32 v3, v4, v5
	global_store_dwordx2 v[38:39], v[2:3], off offset:1536
	s_andn2_b64 exec, exec, s[6:7]
	s_cbranch_execnz .LBB0_907

; #define MFMA32(a, b, c) __builtin_amdgcn_mfma_f32_32x32x16_bf16((a), (b), (c), 0, 0, 0)
; DI void gemm_main_bd(f32x16 (&acc)[4][2], const bf16_t* __restrict__ A, int lda, const bf16_t* __restrict__ Bf, int n0,
;                      int K, char* lds) {
;     ...
;   for (int k = 0; k < nsteps; ++k) {
;     const bf16_t* As = As0 + (k & 1) * (128 * 72);
;     bf16_t* Aw = As0 + ((k + 1) & 1) * (128 * 72);
; #pragma unroll
;     for (int ks = 0; ks < 4; ++ks) { bc[0][ks] = bn[0][ks]; bc[1][ks] = bn[1][ks]; }
;     if (k + 1 < nsteps) {
; #pragma unroll
;       for (int ks = 0; ks < 4; ++ks) {
;         bn[0][ks] = *(const bf16x8*)(Bb0 + (loff + 1024u * (unsigned)(4 * (k + 1) + ks)));
;         bn[1][ks] = *(const bf16x8*)(Bb1 + (loff + 1024u * (unsigned)(4 * (k + 1) + ks)));
;       }
; #pragma unroll
;       for (int i = 0; i < 4; ++i) *(u32x4*)(Aw + (lr + 32 * i) * 72 + lc) = ra[i];
;       if (k + 2 < nsteps) {
; #pragma unroll
;         for (int i = 0; i < 4; ++i) ra[i] = *(const u32x4*)(Ab + (aoff + astep * i + 128u * (unsigned)(k + 2)));
;       }
;     }
;     __builtin_amdgcn_s_setprio(1);
; #pragma unroll
;     for (int ks = 0; ks < 4; ++ks) {
;       bf16x8 af[4];
; #pragma unroll
;       for (int mi = 0; mi < 4; ++mi) af[mi] = *(const bf16x8*)(As + (32 * mi + l31) * 72 + 16 * ks + 8 * h2);
; #pragma unroll
;       for (int mi = 0; mi < 4; ++mi)
; #pragma unroll
;         for (int ni = 0; ni < 2; ++ni) acc[mi][ni] = MFMA32(bc[ni][ks], af[mi], acc[mi][ni]);
;     }
;     __builtin_amdgcn_s_setprio(0);
;     __syncthreads();
;   }
.LBB0_1017:
	s_waitcnt vmcnt(4)
	v_mov_b64_e32 v[208:209], v[132:133]
	v_mov_b64_e32 v[206:207], v[130:131]
	v_lshl_add_u64 v[130:131], v[222:223], 0, s[42:43]
	s_mov_b32 s49, 0x23d1000
	s_and_b32 s45, 1, s28
	s_add_i32 s28, s28, 1
	v_add_co_u32_e32 v132, vcc, s49, v130
	s_and_b32 s48, 1, s28
	s_nop 0
	v_addc_co_u32_e32 v133, vcc, 0, v131, vcc
	s_mov_b32 s49, 0x23e1000
	s_cmp_eq_u32 s45, 1
	v_add_co_u32_e32 v130, vcc, s49, v130
	s_cselect_b32 s45, 0x4800, 0
	s_cmp_eq_u32 s48, 1
	v_addc_co_u32_e32 v131, vcc, 0, v131, vcc
	s_cselect_b32 s48, 0x4800, 0
	global_load_dwordx4 v[198:201], v[132:133], off
	global_load_dwordx4 v[202:205], v[130:131], off
	global_load_dwordx4 v[194:197], v[132:133], off offset:1024
	global_load_dwordx4 v[190:193], v[130:131], off offset:1024
	global_load_dwordx4 v[182:185], v[132:133], off offset:2048
	global_load_dwordx4 v[186:189], v[130:131], off offset:2048
	global_load_dwordx4 v[178:181], v[132:133], off offset:3072
	s_nop 0
	global_load_dwordx4 v[130:133], v[130:131], off offset:3072
	v_add_u32_e32 v0, s48, v236
	s_waitcnt vmcnt(11)
	ds_write_b128 v0, v[134:137]
	s_waitcnt vmcnt(10)
	ds_write_b128 v0, v[138:141] offset:4608
	s_waitcnt vmcnt(9)
	ds_write_b128 v0, v[142:145] offset:9216
	s_waitcnt vmcnt(8)
	ds_write_b128 v0, v[146:149] offset:13824
	s_setprio 1
	v_add_u32_e32 v0, s45, v234
	ds_read_b128 v[238:241], v0
	ds_read_b128 v[248:251], v0 offset:4608
	s_waitcnt lgkmcnt(1)
	v_mfma_f32_32x32x16_bf16 v[114:129], v[170:173], v[238:241], v[114:129]
	v_mfma_f32_32x32x16_bf16 v[98:113], v[174:177], v[238:241], v[98:113]
	v_add_u32_e32 v245, 0xfffd0000, v237
	global_load_dwordx4 v[134:137], v245, s[24:25]
	ds_read_b128 v[238:241], v0 offset:9216
	s_waitcnt lgkmcnt(1)
	v_mfma_f32_32x32x16_bf16 v[82:97], v[170:173], v[248:251], v[82:97]
	v_mfma_f32_32x32x16_bf16 v[66:81], v[174:177], v[248:251], v[66:81]
	ds_read_b128 v[248:251], v0 offset:13824
	s_waitcnt lgkmcnt(1)
	v_mfma_f32_32x32x16_bf16 v[50:65], v[170:173], v[238:241], v[50:65]
	v_mfma_f32_32x32x16_bf16 v[34:49], v[174:177], v[238:241], v[34:49]
	v_add_u32_e32 v245, 0xfffe0000, v237
	global_load_dwordx4 v[138:141], v245, s[24:25]
	ds_read_b128 v[238:241], v0 offset:32
	s_waitcnt lgkmcnt(1)
	v_mfma_f32_32x32x16_bf16 v[18:33], v[170:173], v[248:251], v[18:33]
	v_mfma_f32_32x32x16_bf16 v[2:17], v[174:177], v[248:251], v[2:17]
	ds_read_b128 v[248:251], v0 offset:4640
	s_waitcnt lgkmcnt(1)
	v_mfma_f32_32x32x16_bf16 v[114:129], v[158:161], v[238:241], v[114:129]
	v_mfma_f32_32x32x16_bf16 v[98:113], v[166:169], v[238:241], v[98:113]
	v_add_u32_e32 v245, 0xffff0000, v237
	global_load_dwordx4 v[142:145], v245, s[24:25]
	ds_read_b128 v[238:241], v0 offset:9248
	s_waitcnt lgkmcnt(1)
	v_mfma_f32_32x32x16_bf16 v[82:97], v[158:161], v[248:251], v[82:97]
	v_mfma_f32_32x32x16_bf16 v[66:81], v[166:169], v[248:251], v[66:81]
	ds_read_b128 v[248:251], v0 offset:13856
	s_waitcnt lgkmcnt(1)
	v_mfma_f32_32x32x16_bf16 v[50:65], v[158:161], v[238:241], v[50:65]
	v_mfma_f32_32x32x16_bf16 v[34:49], v[166:169], v[238:241], v[34:49]
	global_load_dwordx4 v[146:149], v237, s[24:25]
	ds_read_b128 v[238:241], v0 offset:64
	s_waitcnt lgkmcnt(1)
	v_mfma_f32_32x32x16_bf16 v[18:33], v[158:161], v[248:251], v[18:33]
	v_mfma_f32_32x32x16_bf16 v[2:17], v[166:169], v[248:251], v[2:17]
	ds_read_b128 v[248:251], v0 offset:4672
	s_waitcnt lgkmcnt(1)
	v_mfma_f32_32x32x16_bf16 v[114:129], v[154:157], v[238:241], v[114:129]
	v_mfma_f32_32x32x16_bf16 v[98:113], v[162:165], v[238:241], v[98:113]
	ds_read_b128 v[238:241], v0 offset:9280
	s_waitcnt lgkmcnt(1)
	v_mfma_f32_32x32x16_bf16 v[82:97], v[154:157], v[248:251], v[82:97]
	v_mfma_f32_32x32x16_bf16 v[66:81], v[162:165], v[248:251], v[66:81]
	ds_read_b128 v[248:251], v0 offset:13888
	s_waitcnt lgkmcnt(1)
	v_mfma_f32_32x32x16_bf16 v[50:65], v[154:157], v[238:241], v[50:65]
	v_mfma_f32_32x32x16_bf16 v[34:49], v[162:165], v[238:241], v[34:49]
	ds_read_b128 v[238:241], v0 offset:96
	s_waitcnt lgkmcnt(1)
	v_mfma_f32_32x32x16_bf16 v[18:33], v[154:157], v[248:251], v[18:33]
	v_mfma_f32_32x32x16_bf16 v[2:17], v[162:165], v[248:251], v[2:17]
	ds_read_b128 v[248:251], v0 offset:4704
	s_waitcnt lgkmcnt(1)
	v_mfma_f32_32x32x16_bf16 v[114:129], v[150:153], v[238:241], v[114:129]
	v_mfma_f32_32x32x16_bf16 v[98:113], v[206:209], v[238:241], v[98:113]
	ds_read_b128 v[238:241], v0 offset:9312
	s_waitcnt lgkmcnt(1)
	v_mfma_f32_32x32x16_bf16 v[82:97], v[150:153], v[248:251], v[82:97]
	v_mfma_f32_32x32x16_bf16 v[66:81], v[206:209], v[248:251], v[66:81]
	ds_read_b128 v[248:251], v0 offset:13920
	s_waitcnt lgkmcnt(1)
	v_mfma_f32_32x32x16_bf16 v[50:65], v[150:153], v[238:241], v[50:65]
	v_mfma_f32_32x32x16_bf16 v[34:49], v[206:209], v[238:241], v[34:49]
	s_waitcnt lgkmcnt(0)
	v_mfma_f32_32x32x16_bf16 v[18:33], v[150:153], v[248:251], v[18:33]
	v_mfma_f32_32x32x16_bf16 v[2:17], v[206:209], v[248:251], v[2:17]
	s_setprio 0
	s_add_u32 s42, s42, 0x1000
	s_addc_u32 s43, s43, 0
	v_add_u32_e32 v237, 0x80, v237
	s_cmpk_eq_u32 s42, 0xe000
	s_waitcnt vmcnt(11)
	v_mov_b32_e32 v170, v198
	v_mov_b32_e32 v171, v199
	v_mov_b32_e32 v172, v200
	v_mov_b32_e32 v173, v201
	s_waitcnt vmcnt(9)
	v_mov_b32_e32 v158, v194
	v_mov_b32_e32 v159, v195
	v_mov_b32_e32 v160, v196
	v_mov_b32_e32 v161, v197
	s_waitcnt vmcnt(7)
	v_mov_b32_e32 v154, v182
	v_mov_b32_e32 v155, v183
	v_mov_b32_e32 v156, v184
	v_mov_b32_e32 v157, v185
	s_waitcnt vmcnt(5)
	v_mov_b32_e32 v150, v178
	v_mov_b32_e32 v151, v179
	v_mov_b32_e32 v152, v180
	v_mov_b32_e32 v153, v181
	v_mov_b32_e32 v174, v202
	v_mov_b32_e32 v175, v203
	v_mov_b32_e32 v176, v204
	v_mov_b32_e32 v177, v205
	v_mov_b32_e32 v166, v190
	v_mov_b32_e32 v167, v191
	v_mov_b32_e32 v168, v192
	v_mov_b32_e32 v169, v193
	v_mov_b32_e32 v162, v186
	v_mov_b32_e32 v163, v187
	v_mov_b32_e32 v164, v188
	v_mov_b32_e32 v165, v189
	s_barrier
; #define MFMA32(a, b, c) __builtin_amdgcn_mfma_f32_32x32x16_bf16((a), (b), (c), 0, 0, 0)
; DI void gemm_main_bd(f32x16 (&acc)[4][2], const bf16_t* __restrict__ A, int lda, const bf16_t* __restrict__ Bf, int n0,
;                      int K, char* lds) {
;     ...
;   for (int k = 0; k < nsteps; ++k) {
;     const bf16_t* As = As0 + (k & 1) * (128 * 72);
;     bf16_t* Aw = As0 + ((k + 1) & 1) * (128 * 72);
; #pragma unroll
;     for (int ks = 0; ks < 4; ++ks) { bc[0][ks] = bn[0][ks]; bc[1][ks] = bn[1][ks]; }
;     if (k + 1 < nsteps) {
; #pragma unroll
;       for (int ks = 0; ks < 4; ++ks) {
;         bn[0][ks] = *(const bf16x8*)(Bb0 + (loff + 1024u * (unsigned)(4 * (k + 1) + ks)));
;         bn[1][ks] = *(const bf16x8*)(Bb1 + (loff + 1024u * (unsigned)(4 * (k + 1) + ks)));
;       }
; #pragma unroll
;       for (int i = 0; i < 4; ++i) *(u32x4*)(Aw + (lr + 32 * i) * 72 + lc) = ra[i];
;       if (k + 2 < nsteps) {
; #pragma unroll
;         for (int i = 0; i < 4; ++i) ra[i] = *(const u32x4*)(Ab + (aoff + astep * i + 128u * (unsigned)(k + 2)));
;       }
;     }
;     __builtin_amdgcn_s_setprio(1);
; #pragma unroll
;     for (int ks = 0; ks < 4; ++ks) {
;       bf16x8 af[4];
; #pragma unroll
;       for (int mi = 0; mi < 4; ++mi) af[mi] = *(const bf16x8*)(As + (32 * mi + l31) * 72 + 16 * ks + 8 * h2);
; #pragma unroll
;       for (int mi = 0; mi < 4; ++mi)
; #pragma unroll
;         for (int ni = 0; ni < 2; ++ni) acc[mi][ni] = MFMA32(bc[ni][ks], af[mi], acc[mi][ni]);
;     }
;     __builtin_amdgcn_s_setprio(0);
;     __syncthreads();
;   }
	s_cbranch_scc0 .LBB0_1017
	v_or_b32_e32 v150, 0xf000, v235
	global_load_dwordx4 v[174:177], v150, s[34:35]
	global_load_dwordx4 v[206:209], v150, s[38:39]
	v_or_b32_e32 v150, 0xf400, v235
	global_load_dwordx4 v[170:173], v150, s[34:35]
	global_load_dwordx4 v[166:169], v150, s[38:39]
	v_or_b32_e32 v150, 0xf800, v235
	global_load_dwordx4 v[158:161], v150, s[34:35]
	global_load_dwordx4 v[162:165], v150, s[38:39]
	v_or_b32_e32 v150, 0xfc00, v235
	global_load_dwordx4 v[154:157], v150, s[34:35]
	s_nop 0
	global_load_dwordx4 v[150:153], v150, s[38:39]
	s_waitcnt vmcnt(11)
	ds_write_b128 v236, v[134:137] offset:18432
	s_waitcnt vmcnt(10)
	ds_write_b128 v236, v[138:141] offset:23040
	s_waitcnt vmcnt(9)
	ds_write_b128 v236, v[142:145] offset:27648
	s_waitcnt vmcnt(8)
	ds_write_b128 v236, v[146:149] offset:32256
	s_setprio 1
	ds_read_b128 v[134:137], v234
	s_waitcnt lgkmcnt(0)
	v_mfma_f32_32x32x16_bf16 v[114:129], v[198:201], v[134:137], v[114:129]
	v_mfma_f32_32x32x16_bf16 v[98:113], v[202:205], v[134:137], v[98:113]
	ds_read_b128 v[134:137], v234 offset:4608
	s_waitcnt lgkmcnt(0)
	v_mfma_f32_32x32x16_bf16 v[82:97], v[198:201], v[134:137], v[82:97]
	v_mfma_f32_32x32x16_bf16 v[66:81], v[202:205], v[134:137], v[66:81]
	ds_read_b128 v[134:137], v234 offset:9216
	s_waitcnt lgkmcnt(0)
	v_mfma_f32_32x32x16_bf16 v[50:65], v[198:201], v[134:137], v[50:65]
	v_mfma_f32_32x32x16_bf16 v[34:49], v[202:205], v[134:137], v[34:49]
	ds_read_b128 v[134:137], v234 offset:13824
	s_waitcnt lgkmcnt(0)
	v_mfma_f32_32x32x16_bf16 v[18:33], v[198:201], v[134:137], v[18:33]
	v_mfma_f32_32x32x16_bf16 v[2:17], v[202:205], v[134:137], v[2:17]
	ds_read_b128 v[134:137], v234 offset:32
	s_waitcnt lgkmcnt(0)
	v_mfma_f32_32x32x16_bf16 v[114:129], v[194:197], v[134:137], v[114:129]
	v_mfma_f32_32x32x16_bf16 v[98:113], v[190:193], v[134:137], v[98:113]
	ds_read_b128 v[134:137], v234 offset:4640
	s_waitcnt lgkmcnt(0)
	v_mfma_f32_32x32x16_bf16 v[82:97], v[194:197], v[134:137], v[82:97]
	v_mfma_f32_32x32x16_bf16 v[66:81], v[190:193], v[134:137], v[66:81]
	ds_read_b128 v[134:137], v234 offset:9248
	s_waitcnt lgkmcnt(0)
	v_mfma_f32_32x32x16_bf16 v[50:65], v[194:197], v[134:137], v[50:65]
	v_mfma_f32_32x32x16_bf16 v[34:49], v[190:193], v[134:137], v[34:49]
	ds_read_b128 v[134:137], v234 offset:13856
	s_waitcnt lgkmcnt(0)
	v_mfma_f32_32x32x16_bf16 v[18:33], v[194:197], v[134:137], v[18:33]
	v_mfma_f32_32x32x16_bf16 v[2:17], v[190:193], v[134:137], v[2:17]
	ds_read_b128 v[134:137], v234 offset:64
	s_waitcnt lgkmcnt(0)
	v_mfma_f32_32x32x16_bf16 v[114:129], v[182:185], v[134:137], v[114:129]
	v_mfma_f32_32x32x16_bf16 v[98:113], v[186:189], v[134:137], v[98:113]
	ds_read_b128 v[134:137], v234 offset:4672
	s_waitcnt lgkmcnt(0)
	v_mfma_f32_32x32x16_bf16 v[82:97], v[182:185], v[134:137], v[82:97]
	v_mfma_f32_32x32x16_bf16 v[66:81], v[186:189], v[134:137], v[66:81]
	ds_read_b128 v[134:137], v234 offset:9280
	s_waitcnt lgkmcnt(0)
	v_mfma_f32_32x32x16_bf16 v[50:65], v[182:185], v[134:137], v[50:65]
	v_mfma_f32_32x32x16_bf16 v[34:49], v[186:189], v[134:137], v[34:49]
	ds_read_b128 v[134:137], v234 offset:13888
	s_waitcnt lgkmcnt(0)
	v_mfma_f32_32x32x16_bf16 v[18:33], v[182:185], v[134:137], v[18:33]
	v_mfma_f32_32x32x16_bf16 v[2:17], v[186:189], v[134:137], v[2:17]
	ds_read_b128 v[134:137], v234 offset:96
	s_waitcnt lgkmcnt(0)
	v_mfma_f32_32x32x16_bf16 v[114:129], v[178:181], v[134:137], v[114:129]
	v_mfma_f32_32x32x16_bf16 v[98:113], v[130:133], v[134:137], v[98:113]
	ds_read_b128 v[134:137], v234 offset:4704
	s_waitcnt lgkmcnt(0)
	v_mfma_f32_32x32x16_bf16 v[82:97], v[178:181], v[134:137], v[82:97]
	v_mfma_f32_32x32x16_bf16 v[66:81], v[130:133], v[134:137], v[66:81]
	ds_read_b128 v[134:137], v234 offset:9312
	s_waitcnt lgkmcnt(0)
	v_mfma_f32_32x32x16_bf16 v[50:65], v[178:181], v[134:137], v[50:65]
	v_mfma_f32_32x32x16_bf16 v[34:49], v[130:133], v[134:137], v[34:49]
	ds_read_b128 v[134:137], v234 offset:13920
	s_waitcnt lgkmcnt(0)
	v_mfma_f32_32x32x16_bf16 v[18:33], v[178:181], v[134:137], v[18:33]
	v_mfma_f32_32x32x16_bf16 v[2:17], v[130:133], v[134:137], v[2:17]
	s_setprio 0
	s_barrier
	s_and_b32 s28, s44, 0x7fffff00
	s_setprio 1
	ds_read_b128 v[130:133], v0
	s_waitcnt vmcnt(7) lgkmcnt(0)
	v_mfma_f32_32x32x16_bf16 v[114:129], v[174:177], v[130:133], v[114:129]
	s_waitcnt vmcnt(6)
	v_mfma_f32_32x32x16_bf16 v[98:113], v[206:209], v[130:133], v[98:113]
	ds_read_b128 v[130:133], v0 offset:4608
	s_waitcnt lgkmcnt(0)
	v_mfma_f32_32x32x16_bf16 v[82:97], v[174:177], v[130:133], v[82:97]
	v_mfma_f32_32x32x16_bf16 v[66:81], v[206:209], v[130:133], v[66:81]
	ds_read_b128 v[130:133], v0 offset:9216
	s_waitcnt lgkmcnt(0)
	v_mfma_f32_32x32x16_bf16 v[50:65], v[174:177], v[130:133], v[50:65]
	v_mfma_f32_32x32x16_bf16 v[34:49], v[206:209], v[130:133], v[34:49]
	ds_read_b128 v[130:133], v0 offset:13824
	s_waitcnt lgkmcnt(0)
	v_mfma_f32_32x32x16_bf16 v[18:33], v[174:177], v[130:133], v[18:33]
	v_mfma_f32_32x32x16_bf16 v[2:17], v[206:209], v[130:133], v[2:17]
	ds_read_b128 v[130:133], v0 offset:32
	s_waitcnt vmcnt(5) lgkmcnt(0)
	v_mfma_f32_32x32x16_bf16 v[114:129], v[170:173], v[130:133], v[114:129]
	s_waitcnt vmcnt(4)
	v_mfma_f32_32x32x16_bf16 v[98:113], v[166:169], v[130:133], v[98:113]
	ds_read_b128 v[130:133], v0 offset:4640
	s_waitcnt lgkmcnt(0)
	v_mfma_f32_32x32x16_bf16 v[82:97], v[170:173], v[130:133], v[82:97]
	v_mfma_f32_32x32x16_bf16 v[66:81], v[166:169], v[130:133], v[66:81]
	ds_read_b128 v[130:133], v0 offset:9248
	s_waitcnt lgkmcnt(0)
	v_mfma_f32_32x32x16_bf16 v[50:65], v[170:173], v[130:133], v[50:65]
	v_mfma_f32_32x32x16_bf16 v[34:49], v[166:169], v[130:133], v[34:49]
	ds_read_b128 v[130:133], v0 offset:13856
	s_waitcnt lgkmcnt(0)
; #define MFMA32(a, b, c) __builtin_amdgcn_mfma_f32_32x32x16_bf16((a), (b), (c), 0, 0, 0)
; DI void gemm_main_bd(f32x16 (&acc)[4][2], const bf16_t* __restrict__ A, int lda, const bf16_t* __restrict__ Bf, int n0,
;                      int K, char* lds) {
;     ...
;     for (int ks = 0; ks < 4; ++ks) {
;       bf16x8 af[4];
; #pragma unroll
;       for (int mi = 0; mi < 4; ++mi) af[mi] = *(const bf16x8*)(As + (32 * mi + l31) * 72 + 16 * ks + 8 * h2);
; #pragma unroll
;       for (int mi = 0; mi < 4; ++mi)
; #pragma unroll
;         for (int ni = 0; ni < 2; ++ni) acc[mi][ni] = MFMA32(bc[ni][ks], af[mi], acc[mi][ni]);
;     }
;     __builtin_amdgcn_s_setprio(0);
;     __syncthreads();
;   }
; DI void phase_gemm_resid(const bf16_t* __restrict__ A, int K, const bf16_t* __restrict__ Bf, const float* xsrc, float* x,
;                          float scale, char* lds) {
;     ...
; #pragma unroll
;     for (int mi = 0; mi < 4; ++mi)
; #pragma unroll
;       for (int ni = 0; ni < 2; ++ni) {
;         float4 xs[4];
;         const size_t base = (size_t)(mt * 128 + 32 * mi + l31) * 1024 + nt * 256 + 64 * w + 32 * ni + 4 * h2;
; #pragma unroll
;         for (int g = 0; g < 4; ++g) xs[g] = *(const float4*)(xsrc + base + 8 * g);
; #pragma unroll
;         for (int g = 0; g < 4; ++g) {
;           float4 o;
;           o.x = xs[g].x + scale * a0[mi][ni][4 * g];
;           o.y = xs[g].y + scale * a0[mi][ni][4 * g + 1];
;           o.z = xs[g].z + scale * a0[mi][ni][4 * g + 2];
;           o.w = xs[g].w + scale * a0[mi][ni][4 * g + 3];
;           *(float4*)(x + base + 8 * g) = o;
;         }
;       }
	v_mfma_f32_32x32x16_bf16 v[18:33], v[170:173], v[130:133], v[18:33]
	v_mfma_f32_32x32x16_bf16 v[2:17], v[166:169], v[130:133], v[2:17]
	ds_read_b128 v[130:133], v0 offset:64
	s_waitcnt vmcnt(3) lgkmcnt(0)
	v_mfma_f32_32x32x16_bf16 v[114:129], v[158:161], v[130:133], v[114:129]
	s_waitcnt vmcnt(2)
	v_mfma_f32_32x32x16_bf16 v[98:113], v[162:165], v[130:133], v[98:113]
	ds_read_b128 v[130:133], v0 offset:4672
	s_waitcnt lgkmcnt(0)
	v_mfma_f32_32x32x16_bf16 v[82:97], v[158:161], v[130:133], v[82:97]
	v_mfma_f32_32x32x16_bf16 v[66:81], v[162:165], v[130:133], v[66:81]
	ds_read_b128 v[130:133], v0 offset:9280
	s_waitcnt lgkmcnt(0)
	v_mfma_f32_32x32x16_bf16 v[50:65], v[158:161], v[130:133], v[50:65]
	v_mfma_f32_32x32x16_bf16 v[34:49], v[162:165], v[130:133], v[34:49]
	ds_read_b128 v[130:133], v0 offset:13888
	s_waitcnt lgkmcnt(0)
	v_mfma_f32_32x32x16_bf16 v[18:33], v[158:161], v[130:133], v[18:33]
	v_mfma_f32_32x32x16_bf16 v[2:17], v[162:165], v[130:133], v[2:17]
	ds_read_b128 v[130:133], v0 offset:96
	s_waitcnt vmcnt(1) lgkmcnt(0)
	v_mfma_f32_32x32x16_bf16 v[114:129], v[154:157], v[130:133], v[114:129]
	s_waitcnt vmcnt(0)
	v_mfma_f32_32x32x16_bf16 v[98:113], v[150:153], v[130:133], v[98:113]
	ds_read_b128 v[130:133], v0 offset:4704
	s_waitcnt lgkmcnt(0)
	v_mfma_f32_32x32x16_bf16 v[82:97], v[154:157], v[130:133], v[82:97]
	v_mfma_f32_32x32x16_bf16 v[66:81], v[150:153], v[130:133], v[66:81]
	ds_read_b128 v[130:133], v0 offset:9312
	s_waitcnt lgkmcnt(0)
	v_mfma_f32_32x32x16_bf16 v[50:65], v[154:157], v[130:133], v[50:65]
	v_mfma_f32_32x32x16_bf16 v[34:49], v[150:153], v[130:133], v[34:49]
	ds_read_b128 v[130:133], v0 offset:13920
	s_waitcnt lgkmcnt(0)
	v_mfma_f32_32x32x16_bf16 v[18:33], v[154:157], v[130:133], v[18:33]
	v_mfma_f32_32x32x16_bf16 v[2:17], v[150:153], v[130:133], v[2:17]
	s_setprio 0
	v_lshl_add_u64 v[130:131], v[220:221], 0, s[28:29]
	v_or_b32_e32 v0, s41, v233
	v_lshl_add_u64 v[130:131], v[130:131], 2, s[0:1]
	v_lshlrev_b32_e32 v0, 2, v0
	v_lshl_add_u64 v[130:131], v[130:131], 0, v[0:1]
	s_barrier
	s_mov_b32 s24, 0x40000
	s_add_i32 s40, s40, 1
	v_readlane_b32 s25, v243, 23
	s_mov_b32 s24, 0x60000
	s_mul_i32 s24, s40, s66
	s_add_i32 s24, s24, s3
	s_cmp_ge_u32 s24, s25
	s_mov_b32 s100, 0x20000
	s_mov_b32 s101, 0
	v_lshl_add_u64 v[140:141], v[130:131], 0, s[100:101]
	v_lshl_add_u64 v[142:143], v[140:141], 0, s[100:101]
	v_lshl_add_u64 v[144:145], v[142:143], 0, s[100:101]
	global_load_dwordx4 v[146:149], v[130:131], off
	global_load_dwordx4 v[150:153], v[130:131], off offset:32
	global_load_dwordx4 v[154:157], v[130:131], off offset:64
	global_load_dwordx4 v[158:161], v[130:131], off offset:96
	global_load_dwordx4 v[162:165], v[130:131], off offset:128
	global_load_dwordx4 v[166:169], v[130:131], off offset:160
	global_load_dwordx4 v[170:173], v[130:131], off offset:192
	global_load_dwordx4 v[174:177], v[130:131], off offset:224
	global_load_dwordx4 v[178:181], v[140:141], off
	global_load_dwordx4 v[182:185], v[140:141], off offset:32
	global_load_dwordx4 v[186:189], v[140:141], off offset:64
	global_load_dwordx4 v[190:193], v[140:141], off offset:96
	global_load_dwordx4 v[194:197], v[140:141], off offset:128
	global_load_dwordx4 v[198:201], v[140:141], off offset:160
	global_load_dwordx4 v[202:205], v[140:141], off offset:192
	global_load_dwordx4 v[206:209], v[140:141], off offset:224
	s_waitcnt vmcnt(8)
	v_pk_add_f32 v[114:115], v[114:115], v[146:147]
	v_pk_add_f32 v[116:117], v[116:117], v[148:149]
	v_pk_add_f32 v[118:119], v[118:119], v[150:151]
	v_pk_add_f32 v[120:121], v[120:121], v[152:153]
	v_pk_add_f32 v[122:123], v[122:123], v[154:155]
	v_pk_add_f32 v[124:125], v[124:125], v[156:157]
	v_pk_add_f32 v[126:127], v[126:127], v[158:159]
	v_pk_add_f32 v[128:129], v[128:129], v[160:161]
	v_pk_add_f32 v[98:99], v[98:99], v[162:163]
	v_pk_add_f32 v[100:101], v[100:101], v[164:165]
	v_pk_add_f32 v[102:103], v[102:103], v[166:167]
	v_pk_add_f32 v[104:105], v[104:105], v[168:169]
	v_pk_add_f32 v[106:107], v[106:107], v[170:171]
	v_pk_add_f32 v[108:109], v[108:109], v[172:173]
	v_pk_add_f32 v[110:111], v[110:111], v[174:175]
	v_pk_add_f32 v[112:113], v[112:113], v[176:177]
	global_store_dwordx4 v[130:131], v[114:117], off
	global_store_dwordx4 v[130:131], v[118:121], off offset:32
	global_store_dwordx4 v[130:131], v[122:125], off offset:64
	global_store_dwordx4 v[130:131], v[126:129], off offset:96
	global_store_dwordx4 v[130:131], v[98:101], off offset:128
	global_store_dwordx4 v[130:131], v[102:105], off offset:160
	global_store_dwordx4 v[130:131], v[106:109], off offset:192
	global_store_dwordx4 v[130:131], v[110:113], off offset:224
	global_load_dwordx4 v[146:149], v[142:143], off
	global_load_dwordx4 v[150:153], v[142:143], off offset:32
	global_load_dwordx4 v[154:157], v[142:143], off offset:64
	global_load_dwordx4 v[158:161], v[142:143], off offset:96
	global_load_dwordx4 v[162:165], v[142:143], off offset:128
	global_load_dwordx4 v[166:169], v[142:143], off offset:160
	global_load_dwordx4 v[170:173], v[142:143], off offset:192
	global_load_dwordx4 v[174:177], v[142:143], off offset:224
	s_waitcnt vmcnt(16)
; DI void phase_gemm_resid(const bf16_t* __restrict__ A, int K, const bf16_t* __restrict__ Bf, const float* xsrc, float* x,
;                          float scale, char* lds) {
;     ...
; #pragma unroll
;     for (int mi = 0; mi < 4; ++mi)
; #pragma unroll
;       for (int ni = 0; ni < 2; ++ni) {
;         float4 xs[4];
;         const size_t base = (size_t)(mt * 128 + 32 * mi + l31) * 1024 + nt * 256 + 64 * w + 32 * ni + 4 * h2;
; #pragma unroll
;         for (int g = 0; g < 4; ++g) xs[g] = *(const float4*)(xsrc + base + 8 * g);
; #pragma unroll
;         for (int g = 0; g < 4; ++g) {
;           float4 o;
;           o.x = xs[g].x + scale * a0[mi][ni][4 * g];
;           o.y = xs[g].y + scale * a0[mi][ni][4 * g + 1];
;           o.z = xs[g].z + scale * a0[mi][ni][4 * g + 2];
;           o.w = xs[g].w + scale * a0[mi][ni][4 * g + 3];
;           *(float4*)(x + base + 8 * g) = o;
;         }
;       }
	v_pk_add_f32 v[82:83], v[82:83], v[178:179]
	v_pk_add_f32 v[84:85], v[84:85], v[180:181]
	v_pk_add_f32 v[86:87], v[86:87], v[182:183]
	v_pk_add_f32 v[88:89], v[88:89], v[184:185]
	v_pk_add_f32 v[90:91], v[90:91], v[186:187]
	v_pk_add_f32 v[92:93], v[92:93], v[188:189]
	v_pk_add_f32 v[94:95], v[94:95], v[190:191]
	v_pk_add_f32 v[96:97], v[96:97], v[192:193]
	v_pk_add_f32 v[66:67], v[66:67], v[194:195]
	v_pk_add_f32 v[68:69], v[68:69], v[196:197]
	v_pk_add_f32 v[70:71], v[70:71], v[198:199]
	v_pk_add_f32 v[72:73], v[72:73], v[200:201]
	v_pk_add_f32 v[74:75], v[74:75], v[202:203]
	v_pk_add_f32 v[76:77], v[76:77], v[204:205]
	v_pk_add_f32 v[78:79], v[78:79], v[206:207]
	v_pk_add_f32 v[80:81], v[80:81], v[208:209]
	global_store_dwordx4 v[140:141], v[82:85], off
	global_store_dwordx4 v[140:141], v[86:89], off offset:32
	global_store_dwordx4 v[140:141], v[90:93], off offset:64
	global_store_dwordx4 v[140:141], v[94:97], off offset:96
	global_store_dwordx4 v[140:141], v[66:69], off offset:128
	global_store_dwordx4 v[140:141], v[70:73], off offset:160
	global_store_dwordx4 v[140:141], v[74:77], off offset:192
	global_store_dwordx4 v[140:141], v[78:81], off offset:224
	global_load_dwordx4 v[178:181], v[144:145], off
	global_load_dwordx4 v[182:185], v[144:145], off offset:32
	global_load_dwordx4 v[186:189], v[144:145], off offset:64
	global_load_dwordx4 v[190:193], v[144:145], off offset:96
	global_load_dwordx4 v[194:197], v[144:145], off offset:128
	global_load_dwordx4 v[198:201], v[144:145], off offset:160
	global_load_dwordx4 v[202:205], v[144:145], off offset:192
	global_load_dwordx4 v[206:209], v[144:145], off offset:224
	s_waitcnt vmcnt(16)
	v_pk_add_f32 v[50:51], v[50:51], v[146:147]
	v_pk_add_f32 v[52:53], v[52:53], v[148:149]
	v_pk_add_f32 v[54:55], v[54:55], v[150:151]
	v_pk_add_f32 v[56:57], v[56:57], v[152:153]
	v_pk_add_f32 v[58:59], v[58:59], v[154:155]
	v_pk_add_f32 v[60:61], v[60:61], v[156:157]
	v_pk_add_f32 v[62:63], v[62:63], v[158:159]
	v_pk_add_f32 v[64:65], v[64:65], v[160:161]
	v_pk_add_f32 v[34:35], v[34:35], v[162:163]
	v_pk_add_f32 v[36:37], v[36:37], v[164:165]
	v_pk_add_f32 v[38:39], v[38:39], v[166:167]
	v_pk_add_f32 v[40:41], v[40:41], v[168:169]
	v_pk_add_f32 v[42:43], v[42:43], v[170:171]
	v_pk_add_f32 v[44:45], v[44:45], v[172:173]
	v_pk_add_f32 v[46:47], v[46:47], v[174:175]
	v_pk_add_f32 v[48:49], v[48:49], v[176:177]
	global_store_dwordx4 v[142:143], v[50:53], off
	global_store_dwordx4 v[142:143], v[54:57], off offset:32
	global_store_dwordx4 v[142:143], v[58:61], off offset:64
	global_store_dwordx4 v[142:143], v[62:65], off offset:96
	global_store_dwordx4 v[142:143], v[34:37], off offset:128
	global_store_dwordx4 v[142:143], v[38:41], off offset:160
	global_store_dwordx4 v[142:143], v[42:45], off offset:192
	global_store_dwordx4 v[142:143], v[46:49], off offset:224
	s_waitcnt vmcnt(8)
	v_pk_add_f32 v[18:19], v[18:19], v[178:179]
	v_pk_add_f32 v[20:21], v[20:21], v[180:181]
	v_pk_add_f32 v[22:23], v[22:23], v[182:183]
	v_pk_add_f32 v[24:25], v[24:25], v[184:185]
	v_pk_add_f32 v[26:27], v[26:27], v[186:187]
	v_pk_add_f32 v[28:29], v[28:29], v[188:189]
	v_pk_add_f32 v[30:31], v[30:31], v[190:191]
	v_pk_add_f32 v[32:33], v[32:33], v[192:193]
	v_pk_add_f32 v[2:3], v[2:3], v[194:195]
	v_pk_add_f32 v[4:5], v[4:5], v[196:197]
	v_pk_add_f32 v[6:7], v[6:7], v[198:199]
	v_pk_add_f32 v[8:9], v[8:9], v[200:201]
	v_pk_add_f32 v[10:11], v[10:11], v[202:203]
	v_pk_add_f32 v[12:13], v[12:13], v[204:205]
	v_pk_add_f32 v[14:15], v[14:15], v[206:207]
	v_pk_add_f32 v[16:17], v[16:17], v[208:209]
	global_store_dwordx4 v[144:145], v[18:21], off
	global_store_dwordx4 v[144:145], v[22:25], off offset:32
	global_store_dwordx4 v[144:145], v[26:29], off offset:64
	global_store_dwordx4 v[144:145], v[30:33], off offset:96
	global_store_dwordx4 v[144:145], v[2:5], off offset:128
	global_store_dwordx4 v[144:145], v[6:9], off offset:160
	global_store_dwordx4 v[144:145], v[10:13], off offset:192
	global_store_dwordx4 v[144:145], v[14:17], off offset:224
	s_cbranch_scc0 .LBB0_1016

; #define MFMA32(a, b, c) __builtin_amdgcn_mfma_f32_32x32x16_bf16((a), (b), (c), 0, 0, 0)
; DI void gemm_main_bd(f32x16 (&acc)[4][2], const bf16_t* __restrict__ A, int lda, const bf16_t* __restrict__ Bf, int n0,
;                      int K, char* lds) {
;     ...
;   for (int k = 0; k < nsteps; ++k) {
;     const bf16_t* As = As0 + (k & 1) * (128 * 72);
;     bf16_t* Aw = As0 + ((k + 1) & 1) * (128 * 72);
; #pragma unroll
;     for (int ks = 0; ks < 4; ++ks) { bc[0][ks] = bn[0][ks]; bc[1][ks] = bn[1][ks]; }
;     if (k + 1 < nsteps) {
; #pragma unroll
;       for (int ks = 0; ks < 4; ++ks) {
;         bn[0][ks] = *(const bf16x8*)(Bb0 + (loff + 1024u * (unsigned)(4 * (k + 1) + ks)));
;         bn[1][ks] = *(const bf16x8*)(Bb1 + (loff + 1024u * (unsigned)(4 * (k + 1) + ks)));
;       }
; #pragma unroll
;       for (int i = 0; i < 4; ++i) *(u32x4*)(Aw + (lr + 32 * i) * 72 + lc) = ra[i];
;       if (k + 2 < nsteps) {
; #pragma unroll
;         for (int i = 0; i < 4; ++i) ra[i] = *(const u32x4*)(Ab + (aoff + astep * i + 128u * (unsigned)(k + 2)));
;       }
;     }
;     __builtin_amdgcn_s_setprio(1);
; #pragma unroll
;     for (int ks = 0; ks < 4; ++ks) {
;       bf16x8 af[4];
; #pragma unroll
;       for (int mi = 0; mi < 4; ++mi) af[mi] = *(const bf16x8*)(As + (32 * mi + l31) * 72 + 16 * ks + 8 * h2);
; #pragma unroll
;       for (int mi = 0; mi < 4; ++mi)
; #pragma unroll
;         for (int ni = 0; ni < 2; ++ni) acc[mi][ni] = MFMA32(bc[ni][ks], af[mi], acc[mi][ni]);
;     }
;     __builtin_amdgcn_s_setprio(0);
;     __syncthreads();
;   }
.LBB0_1181:
	s_waitcnt vmcnt(4)
	v_mov_b64_e32 v[208:209], v[132:133]
	v_mov_b64_e32 v[206:207], v[130:131]
	v_lshl_add_u64 v[130:131], v[222:223], 0, s[42:43]
	s_mov_b32 s49, 0x30d1000
	s_and_b32 s45, 1, s44
	s_add_i32 s44, s44, 1
	v_add_co_u32_e32 v132, vcc, s49, v130
	s_and_b32 s48, 1, s44
	s_nop 0
	v_addc_co_u32_e32 v133, vcc, 0, v131, vcc
	s_mov_b32 s49, 0x30fd000
	s_cmp_eq_u32 s45, 1
	v_add_co_u32_e32 v130, vcc, s49, v130
	s_cselect_b32 s45, 0x4800, 0
	s_cmp_eq_u32 s48, 1
	v_addc_co_u32_e32 v131, vcc, 0, v131, vcc
	s_cselect_b32 s48, 0x4800, 0
	global_load_dwordx4 v[198:201], v[132:133], off
	global_load_dwordx4 v[202:205], v[130:131], off
	global_load_dwordx4 v[194:197], v[132:133], off offset:1024
	global_load_dwordx4 v[190:193], v[130:131], off offset:1024
	global_load_dwordx4 v[182:185], v[132:133], off offset:2048
	global_load_dwordx4 v[186:189], v[130:131], off offset:2048
	global_load_dwordx4 v[178:181], v[132:133], off offset:3072
	s_nop 0
	global_load_dwordx4 v[130:133], v[130:131], off offset:3072
	v_add_u32_e32 v0, s48, v236
	s_waitcnt vmcnt(11)
	ds_write_b128 v0, v[134:137]
	s_waitcnt vmcnt(10)
	ds_write_b128 v0, v[138:141] offset:4608
	s_waitcnt vmcnt(9)
	ds_write_b128 v0, v[142:145] offset:9216
	s_waitcnt vmcnt(8)
	ds_write_b128 v0, v[146:149] offset:13824
	s_setprio 1
	v_add_u32_e32 v0, s45, v234
	ds_read_b128 v[238:241], v0
	ds_read_b128 v[248:251], v0 offset:4608
	s_waitcnt lgkmcnt(1)
	v_mfma_f32_32x32x16_bf16 v[114:129], v[170:173], v[238:241], v[114:129]
	v_mfma_f32_32x32x16_bf16 v[98:113], v[174:177], v[238:241], v[98:113]
	v_add_u32_e32 v245, 0xfff7c000, v237
	global_load_dwordx4 v[134:137], v245, s[24:25]
	ds_read_b128 v[238:241], v0 offset:9216
	s_waitcnt lgkmcnt(1)
	v_mfma_f32_32x32x16_bf16 v[82:97], v[170:173], v[248:251], v[82:97]
	v_mfma_f32_32x32x16_bf16 v[66:81], v[174:177], v[248:251], v[66:81]
	ds_read_b128 v[248:251], v0 offset:13824
	s_waitcnt lgkmcnt(1)
	v_mfma_f32_32x32x16_bf16 v[50:65], v[170:173], v[238:241], v[50:65]
	v_mfma_f32_32x32x16_bf16 v[34:49], v[174:177], v[238:241], v[34:49]
	v_add_u32_e32 v245, 0xfffa8000, v237
	global_load_dwordx4 v[138:141], v245, s[24:25]
	ds_read_b128 v[238:241], v0 offset:32
	s_waitcnt lgkmcnt(1)
	v_mfma_f32_32x32x16_bf16 v[18:33], v[170:173], v[248:251], v[18:33]
	v_mfma_f32_32x32x16_bf16 v[2:17], v[174:177], v[248:251], v[2:17]
	ds_read_b128 v[248:251], v0 offset:4640
	s_waitcnt lgkmcnt(1)
	v_mfma_f32_32x32x16_bf16 v[114:129], v[158:161], v[238:241], v[114:129]
	v_mfma_f32_32x32x16_bf16 v[98:113], v[166:169], v[238:241], v[98:113]
	v_add_u32_e32 v245, 0xfffd4000, v237
	global_load_dwordx4 v[142:145], v245, s[24:25]
	ds_read_b128 v[238:241], v0 offset:9248
	s_waitcnt lgkmcnt(1)
	v_mfma_f32_32x32x16_bf16 v[82:97], v[158:161], v[248:251], v[82:97]
	v_mfma_f32_32x32x16_bf16 v[66:81], v[166:169], v[248:251], v[66:81]
	ds_read_b128 v[248:251], v0 offset:13856
	s_waitcnt lgkmcnt(1)
	v_mfma_f32_32x32x16_bf16 v[50:65], v[158:161], v[238:241], v[50:65]
	v_mfma_f32_32x32x16_bf16 v[34:49], v[166:169], v[238:241], v[34:49]
	global_load_dwordx4 v[146:149], v237, s[24:25]
	ds_read_b128 v[238:241], v0 offset:64
	s_waitcnt lgkmcnt(1)
	v_mfma_f32_32x32x16_bf16 v[18:33], v[158:161], v[248:251], v[18:33]
	v_mfma_f32_32x32x16_bf16 v[2:17], v[166:169], v[248:251], v[2:17]
	ds_read_b128 v[248:251], v0 offset:4672
	s_waitcnt lgkmcnt(1)
	v_mfma_f32_32x32x16_bf16 v[114:129], v[154:157], v[238:241], v[114:129]
	v_mfma_f32_32x32x16_bf16 v[98:113], v[162:165], v[238:241], v[98:113]
	ds_read_b128 v[238:241], v0 offset:9280
	s_waitcnt lgkmcnt(1)
	v_mfma_f32_32x32x16_bf16 v[82:97], v[154:157], v[248:251], v[82:97]
	v_mfma_f32_32x32x16_bf16 v[66:81], v[162:165], v[248:251], v[66:81]
	ds_read_b128 v[248:251], v0 offset:13888
	s_waitcnt lgkmcnt(1)
	v_mfma_f32_32x32x16_bf16 v[50:65], v[154:157], v[238:241], v[50:65]
	v_mfma_f32_32x32x16_bf16 v[34:49], v[162:165], v[238:241], v[34:49]
	ds_read_b128 v[238:241], v0 offset:96
	s_waitcnt lgkmcnt(1)
	v_mfma_f32_32x32x16_bf16 v[18:33], v[154:157], v[248:251], v[18:33]
	v_mfma_f32_32x32x16_bf16 v[2:17], v[162:165], v[248:251], v[2:17]
	ds_read_b128 v[248:251], v0 offset:4704
	s_waitcnt lgkmcnt(1)
	v_mfma_f32_32x32x16_bf16 v[114:129], v[150:153], v[238:241], v[114:129]
	v_mfma_f32_32x32x16_bf16 v[98:113], v[206:209], v[238:241], v[98:113]
	ds_read_b128 v[238:241], v0 offset:9312
	s_waitcnt lgkmcnt(1)
	v_mfma_f32_32x32x16_bf16 v[82:97], v[150:153], v[248:251], v[82:97]
	v_mfma_f32_32x32x16_bf16 v[66:81], v[206:209], v[248:251], v[66:81]
	ds_read_b128 v[248:251], v0 offset:13920
	s_waitcnt lgkmcnt(1)
	v_mfma_f32_32x32x16_bf16 v[50:65], v[150:153], v[238:241], v[50:65]
	v_mfma_f32_32x32x16_bf16 v[34:49], v[206:209], v[238:241], v[34:49]
	s_waitcnt lgkmcnt(0)
	v_mfma_f32_32x32x16_bf16 v[18:33], v[150:153], v[248:251], v[18:33]
	v_mfma_f32_32x32x16_bf16 v[2:17], v[206:209], v[248:251], v[2:17]
	s_setprio 0
	s_add_u32 s42, s42, 0x1000
	s_addc_u32 s43, s43, 0
	v_add_u32_e32 v237, 0x80, v237
	s_cmp_eq_u32 s42, 0x2a000
	s_waitcnt vmcnt(11)
	v_mov_b32_e32 v170, v198
	v_mov_b32_e32 v171, v199
	v_mov_b32_e32 v172, v200
	v_mov_b32_e32 v173, v201
	s_waitcnt vmcnt(9)
	v_mov_b32_e32 v158, v194
	v_mov_b32_e32 v159, v195
	v_mov_b32_e32 v160, v196
	v_mov_b32_e32 v161, v197
	s_waitcnt vmcnt(7)
	v_mov_b32_e32 v154, v182
	v_mov_b32_e32 v155, v183
	v_mov_b32_e32 v156, v184
	v_mov_b32_e32 v157, v185
	s_waitcnt vmcnt(5)
	v_mov_b32_e32 v150, v178
	v_mov_b32_e32 v151, v179
	v_mov_b32_e32 v152, v180
	v_mov_b32_e32 v153, v181
	v_mov_b32_e32 v174, v202
	v_mov_b32_e32 v175, v203
	v_mov_b32_e32 v176, v204
	v_mov_b32_e32 v177, v205
	v_mov_b32_e32 v166, v190
	v_mov_b32_e32 v167, v191
	v_mov_b32_e32 v168, v192
	v_mov_b32_e32 v169, v193
	v_mov_b32_e32 v162, v186
	v_mov_b32_e32 v163, v187
	v_mov_b32_e32 v164, v188
	v_mov_b32_e32 v165, v189
	s_barrier
; #define MFMA32(a, b, c) __builtin_amdgcn_mfma_f32_32x32x16_bf16((a), (b), (c), 0, 0, 0)
; DI void gemm_main_bd(f32x16 (&acc)[4][2], const bf16_t* __restrict__ A, int lda, const bf16_t* __restrict__ Bf, int n0,
;                      int K, char* lds) {
;     ...
;   for (int k = 0; k < nsteps; ++k) {
;     const bf16_t* As = As0 + (k & 1) * (128 * 72);
;     bf16_t* Aw = As0 + ((k + 1) & 1) * (128 * 72);
; #pragma unroll
;     for (int ks = 0; ks < 4; ++ks) { bc[0][ks] = bn[0][ks]; bc[1][ks] = bn[1][ks]; }
;     if (k + 1 < nsteps) {
; #pragma unroll
;       for (int ks = 0; ks < 4; ++ks) {
;         bn[0][ks] = *(const bf16x8*)(Bb0 + (loff + 1024u * (unsigned)(4 * (k + 1) + ks)));
;         bn[1][ks] = *(const bf16x8*)(Bb1 + (loff + 1024u * (unsigned)(4 * (k + 1) + ks)));
;       }
; #pragma unroll
;       for (int i = 0; i < 4; ++i) *(u32x4*)(Aw + (lr + 32 * i) * 72 + lc) = ra[i];
;       if (k + 2 < nsteps) {
; #pragma unroll
;         for (int i = 0; i < 4; ++i) ra[i] = *(const u32x4*)(Ab + (aoff + astep * i + 128u * (unsigned)(k + 2)));
;       }
;     }
;     __builtin_amdgcn_s_setprio(1);
; #pragma unroll
;     for (int ks = 0; ks < 4; ++ks) {
;       bf16x8 af[4];
; #pragma unroll
;       for (int mi = 0; mi < 4; ++mi) af[mi] = *(const bf16x8*)(As + (32 * mi + l31) * 72 + 16 * ks + 8 * h2);
; #pragma unroll
;       for (int mi = 0; mi < 4; ++mi)
; #pragma unroll
;         for (int ni = 0; ni < 2; ++ni) acc[mi][ni] = MFMA32(bc[ni][ks], af[mi], acc[mi][ni]);
;     }
;     __builtin_amdgcn_s_setprio(0);
;     __syncthreads();
;   }
	s_cbranch_scc0 .LBB0_1181
	v_or_b32_e32 v150, 0x2b000, v235
	global_load_dwordx4 v[174:177], v150, s[34:35]
	global_load_dwordx4 v[206:209], v150, s[38:39]
	v_or_b32_e32 v150, 0x2b400, v235
	global_load_dwordx4 v[170:173], v150, s[34:35]
	global_load_dwordx4 v[166:169], v150, s[38:39]
	v_or_b32_e32 v150, 0x2b800, v235
	global_load_dwordx4 v[158:161], v150, s[34:35]
	global_load_dwordx4 v[162:165], v150, s[38:39]
	v_or_b32_e32 v150, 0x2bc00, v235
	global_load_dwordx4 v[154:157], v150, s[34:35]
	s_nop 0
	global_load_dwordx4 v[150:153], v150, s[38:39]
	s_waitcnt vmcnt(11)
	ds_write_b128 v236, v[134:137] offset:18432
	s_waitcnt vmcnt(10)
	ds_write_b128 v236, v[138:141] offset:23040
	s_waitcnt vmcnt(9)
	ds_write_b128 v236, v[142:145] offset:27648
	s_waitcnt vmcnt(8)
	ds_write_b128 v236, v[146:149] offset:32256
	s_setprio 1
	ds_read_b128 v[134:137], v234
	s_waitcnt lgkmcnt(0)
	v_mfma_f32_32x32x16_bf16 v[114:129], v[198:201], v[134:137], v[114:129]
	v_mfma_f32_32x32x16_bf16 v[98:113], v[202:205], v[134:137], v[98:113]
	ds_read_b128 v[134:137], v234 offset:4608
	s_waitcnt lgkmcnt(0)
	v_mfma_f32_32x32x16_bf16 v[82:97], v[198:201], v[134:137], v[82:97]
	v_mfma_f32_32x32x16_bf16 v[66:81], v[202:205], v[134:137], v[66:81]
	ds_read_b128 v[134:137], v234 offset:9216
	s_waitcnt lgkmcnt(0)
	v_mfma_f32_32x32x16_bf16 v[50:65], v[198:201], v[134:137], v[50:65]
	v_mfma_f32_32x32x16_bf16 v[34:49], v[202:205], v[134:137], v[34:49]
	ds_read_b128 v[134:137], v234 offset:13824
	s_waitcnt lgkmcnt(0)
	v_mfma_f32_32x32x16_bf16 v[18:33], v[198:201], v[134:137], v[18:33]
	v_mfma_f32_32x32x16_bf16 v[2:17], v[202:205], v[134:137], v[2:17]
	ds_read_b128 v[134:137], v234 offset:32
	s_waitcnt lgkmcnt(0)
	v_mfma_f32_32x32x16_bf16 v[114:129], v[194:197], v[134:137], v[114:129]
	v_mfma_f32_32x32x16_bf16 v[98:113], v[190:193], v[134:137], v[98:113]
	ds_read_b128 v[134:137], v234 offset:4640
	s_waitcnt lgkmcnt(0)
	v_mfma_f32_32x32x16_bf16 v[82:97], v[194:197], v[134:137], v[82:97]
	v_mfma_f32_32x32x16_bf16 v[66:81], v[190:193], v[134:137], v[66:81]
	ds_read_b128 v[134:137], v234 offset:9248
	s_waitcnt lgkmcnt(0)
	v_mfma_f32_32x32x16_bf16 v[50:65], v[194:197], v[134:137], v[50:65]
	v_mfma_f32_32x32x16_bf16 v[34:49], v[190:193], v[134:137], v[34:49]
	ds_read_b128 v[134:137], v234 offset:13856
	s_waitcnt lgkmcnt(0)
	v_mfma_f32_32x32x16_bf16 v[18:33], v[194:197], v[134:137], v[18:33]
	v_mfma_f32_32x32x16_bf16 v[2:17], v[190:193], v[134:137], v[2:17]
	ds_read_b128 v[134:137], v234 offset:64
	s_waitcnt lgkmcnt(0)
	v_mfma_f32_32x32x16_bf16 v[114:129], v[182:185], v[134:137], v[114:129]
	v_mfma_f32_32x32x16_bf16 v[98:113], v[186:189], v[134:137], v[98:113]
	ds_read_b128 v[134:137], v234 offset:4672
	s_waitcnt lgkmcnt(0)
	v_mfma_f32_32x32x16_bf16 v[82:97], v[182:185], v[134:137], v[82:97]
	v_mfma_f32_32x32x16_bf16 v[66:81], v[186:189], v[134:137], v[66:81]
	ds_read_b128 v[134:137], v234 offset:9280
	s_waitcnt lgkmcnt(0)
	v_mfma_f32_32x32x16_bf16 v[50:65], v[182:185], v[134:137], v[50:65]
	v_mfma_f32_32x32x16_bf16 v[34:49], v[186:189], v[134:137], v[34:49]
	ds_read_b128 v[134:137], v234 offset:13888
	s_waitcnt lgkmcnt(0)
	v_mfma_f32_32x32x16_bf16 v[18:33], v[182:185], v[134:137], v[18:33]
	v_mfma_f32_32x32x16_bf16 v[2:17], v[186:189], v[134:137], v[2:17]
	ds_read_b128 v[134:137], v234 offset:96
	s_waitcnt lgkmcnt(0)
	v_mfma_f32_32x32x16_bf16 v[114:129], v[178:181], v[134:137], v[114:129]
	v_mfma_f32_32x32x16_bf16 v[98:113], v[130:133], v[134:137], v[98:113]
	ds_read_b128 v[134:137], v234 offset:4704
	s_waitcnt lgkmcnt(0)
	v_mfma_f32_32x32x16_bf16 v[82:97], v[178:181], v[134:137], v[82:97]
	v_mfma_f32_32x32x16_bf16 v[66:81], v[130:133], v[134:137], v[66:81]
	ds_read_b128 v[134:137], v234 offset:9312
	s_waitcnt lgkmcnt(0)
	v_mfma_f32_32x32x16_bf16 v[50:65], v[178:181], v[134:137], v[50:65]
	v_mfma_f32_32x32x16_bf16 v[34:49], v[130:133], v[134:137], v[34:49]
	ds_read_b128 v[134:137], v234 offset:13920
	s_waitcnt lgkmcnt(0)
	v_mfma_f32_32x32x16_bf16 v[18:33], v[178:181], v[134:137], v[18:33]
	v_mfma_f32_32x32x16_bf16 v[2:17], v[130:133], v[134:137], v[2:17]
	s_setprio 0
	s_barrier
	s_and_b32 s28, s28, 0x7fffff00
	s_setprio 1
	ds_read_b128 v[130:133], v0
	s_waitcnt vmcnt(7) lgkmcnt(0)
	v_mfma_f32_32x32x16_bf16 v[114:129], v[174:177], v[130:133], v[114:129]
	s_waitcnt vmcnt(6)
	v_mfma_f32_32x32x16_bf16 v[98:113], v[206:209], v[130:133], v[98:113]
	ds_read_b128 v[130:133], v0 offset:4608
	s_waitcnt lgkmcnt(0)
	v_mfma_f32_32x32x16_bf16 v[82:97], v[174:177], v[130:133], v[82:97]
	v_mfma_f32_32x32x16_bf16 v[66:81], v[206:209], v[130:133], v[66:81]
	ds_read_b128 v[130:133], v0 offset:9216
	s_waitcnt lgkmcnt(0)
	v_mfma_f32_32x32x16_bf16 v[50:65], v[174:177], v[130:133], v[50:65]
	v_mfma_f32_32x32x16_bf16 v[34:49], v[206:209], v[130:133], v[34:49]
	ds_read_b128 v[130:133], v0 offset:13824
	s_waitcnt lgkmcnt(0)
	v_mfma_f32_32x32x16_bf16 v[18:33], v[174:177], v[130:133], v[18:33]
	v_mfma_f32_32x32x16_bf16 v[2:17], v[206:209], v[130:133], v[2:17]
	ds_read_b128 v[130:133], v0 offset:32
	s_waitcnt vmcnt(5) lgkmcnt(0)
	v_mfma_f32_32x32x16_bf16 v[114:129], v[170:173], v[130:133], v[114:129]
	s_waitcnt vmcnt(4)
	v_mfma_f32_32x32x16_bf16 v[98:113], v[166:169], v[130:133], v[98:113]
	ds_read_b128 v[130:133], v0 offset:4640
	s_waitcnt lgkmcnt(0)
	v_mfma_f32_32x32x16_bf16 v[82:97], v[170:173], v[130:133], v[82:97]
	v_mfma_f32_32x32x16_bf16 v[66:81], v[166:169], v[130:133], v[66:81]
	ds_read_b128 v[130:133], v0 offset:9248
	s_waitcnt lgkmcnt(0)
	v_mfma_f32_32x32x16_bf16 v[50:65], v[170:173], v[130:133], v[50:65]
	v_mfma_f32_32x32x16_bf16 v[34:49], v[166:169], v[130:133], v[34:49]
	ds_read_b128 v[130:133], v0 offset:13856
	s_waitcnt lgkmcnt(0)
; #define MFMA32(a, b, c) __builtin_amdgcn_mfma_f32_32x32x16_bf16((a), (b), (c), 0, 0, 0)
; DI void gemm_main_bd(f32x16 (&acc)[4][2], const bf16_t* __restrict__ A, int lda, const bf16_t* __restrict__ Bf, int n0,
;                      int K, char* lds) {
;     ...
;     for (int ks = 0; ks < 4; ++ks) {
;       bf16x8 af[4];
; #pragma unroll
;       for (int mi = 0; mi < 4; ++mi) af[mi] = *(const bf16x8*)(As + (32 * mi + l31) * 72 + 16 * ks + 8 * h2);
; #pragma unroll
;       for (int mi = 0; mi < 4; ++mi)
; #pragma unroll
;         for (int ni = 0; ni < 2; ++ni) acc[mi][ni] = MFMA32(bc[ni][ks], af[mi], acc[mi][ni]);
;     }
; DI void phase_gemm_resid(const bf16_t* __restrict__ A, int K, const bf16_t* __restrict__ Bf, const float* xsrc, float* x,
;                          float scale, char* lds) {
;     ...
; #pragma unroll
;     for (int mi = 0; mi < 4; ++mi)
; #pragma unroll
;       for (int ni = 0; ni < 2; ++ni) {
;         float4 xs[4];
;         const size_t base = (size_t)(mt * 128 + 32 * mi + l31) * 1024 + nt * 256 + 64 * w + 32 * ni + 4 * h2;
; #pragma unroll
;         for (int g = 0; g < 4; ++g) xs[g] = *(const float4*)(xsrc + base + 8 * g);
; #pragma unroll
;         for (int g = 0; g < 4; ++g) {
;           float4 o;
;           o.x = xs[g].x + scale * a0[mi][ni][4 * g];
;           o.y = xs[g].y + scale * a0[mi][ni][4 * g + 1];
;           o.z = xs[g].z + scale * a0[mi][ni][4 * g + 2];
;           o.w = xs[g].w + scale * a0[mi][ni][4 * g + 3];
;           *(float4*)(x + base + 8 * g) = o;
;         }
;       }
	v_mfma_f32_32x32x16_bf16 v[18:33], v[170:173], v[130:133], v[18:33]
	v_mfma_f32_32x32x16_bf16 v[2:17], v[166:169], v[130:133], v[2:17]
	ds_read_b128 v[130:133], v0 offset:64
	s_waitcnt vmcnt(3) lgkmcnt(0)
	v_mfma_f32_32x32x16_bf16 v[114:129], v[158:161], v[130:133], v[114:129]
	s_waitcnt vmcnt(2)
	v_mfma_f32_32x32x16_bf16 v[98:113], v[162:165], v[130:133], v[98:113]
	ds_read_b128 v[130:133], v0 offset:4672
	s_waitcnt lgkmcnt(0)
	v_mfma_f32_32x32x16_bf16 v[82:97], v[158:161], v[130:133], v[82:97]
	v_mfma_f32_32x32x16_bf16 v[66:81], v[162:165], v[130:133], v[66:81]
	ds_read_b128 v[130:133], v0 offset:9280
	s_waitcnt lgkmcnt(0)
	v_mfma_f32_32x32x16_bf16 v[50:65], v[158:161], v[130:133], v[50:65]
	v_mfma_f32_32x32x16_bf16 v[34:49], v[162:165], v[130:133], v[34:49]
	ds_read_b128 v[130:133], v0 offset:13888
	s_waitcnt lgkmcnt(0)
	v_mfma_f32_32x32x16_bf16 v[18:33], v[158:161], v[130:133], v[18:33]
	v_mfma_f32_32x32x16_bf16 v[2:17], v[162:165], v[130:133], v[2:17]
	ds_read_b128 v[130:133], v0 offset:96
	s_waitcnt vmcnt(1) lgkmcnt(0)
	v_mfma_f32_32x32x16_bf16 v[114:129], v[154:157], v[130:133], v[114:129]
	s_waitcnt vmcnt(0)
	v_mfma_f32_32x32x16_bf16 v[98:113], v[150:153], v[130:133], v[98:113]
	ds_read_b128 v[130:133], v0 offset:4704
	s_waitcnt lgkmcnt(0)
	v_mfma_f32_32x32x16_bf16 v[82:97], v[154:157], v[130:133], v[82:97]
	v_mfma_f32_32x32x16_bf16 v[66:81], v[150:153], v[130:133], v[66:81]
	ds_read_b128 v[130:133], v0 offset:9312
	s_waitcnt lgkmcnt(0)
	v_mfma_f32_32x32x16_bf16 v[50:65], v[154:157], v[130:133], v[50:65]
	v_mfma_f32_32x32x16_bf16 v[34:49], v[150:153], v[130:133], v[34:49]
	ds_read_b128 v[130:133], v0 offset:13920
	s_waitcnt lgkmcnt(0)
	v_mfma_f32_32x32x16_bf16 v[18:33], v[154:157], v[130:133], v[18:33]
	v_mfma_f32_32x32x16_bf16 v[2:17], v[150:153], v[130:133], v[2:17]
	s_setprio 0
	v_lshl_add_u64 v[130:131], v[220:221], 0, s[28:29]
	v_lshl_add_u64 v[130:131], v[130:131], 2, s[0:1]
	v_lshl_or_b32 v0, s41, 19, v233
	v_lshl_add_u64 v[130:131], v[130:131], 0, v[0:1]
	s_barrier
	s_mov_b32 s24, 0x40000
	s_add_i32 s40, s40, 1
	v_readlane_b32 s25, v243, 23
	s_mov_b32 s24, 0x60000
	s_mul_i32 s24, s40, s66
	s_add_i32 s24, s24, s3
	s_cmp_ge_u32 s24, s25
	s_mov_b32 s100, 0x20000
	s_mov_b32 s101, 0
	v_lshl_add_u64 v[140:141], v[130:131], 0, s[100:101]
	v_lshl_add_u64 v[142:143], v[140:141], 0, s[100:101]
	v_lshl_add_u64 v[144:145], v[142:143], 0, s[100:101]
	global_load_dwordx4 v[146:149], v[130:131], off
	global_load_dwordx4 v[150:153], v[130:131], off offset:32
	global_load_dwordx4 v[154:157], v[130:131], off offset:64
	global_load_dwordx4 v[158:161], v[130:131], off offset:96
	global_load_dwordx4 v[162:165], v[130:131], off offset:128
	global_load_dwordx4 v[166:169], v[130:131], off offset:160
	global_load_dwordx4 v[170:173], v[130:131], off offset:192
	global_load_dwordx4 v[174:177], v[130:131], off offset:224
	global_load_dwordx4 v[178:181], v[140:141], off
	global_load_dwordx4 v[182:185], v[140:141], off offset:32
	global_load_dwordx4 v[186:189], v[140:141], off offset:64
	global_load_dwordx4 v[190:193], v[140:141], off offset:96
	global_load_dwordx4 v[194:197], v[140:141], off offset:128
	global_load_dwordx4 v[198:201], v[140:141], off offset:160
	global_load_dwordx4 v[202:205], v[140:141], off offset:192
	global_load_dwordx4 v[206:209], v[140:141], off offset:224
	s_waitcnt vmcnt(8)
	v_pk_fma_f32 v[114:115], v[114:115], 0.5, v[146:147] op_sel_hi:[1,0,1]
	v_pk_fma_f32 v[116:117], v[116:117], 0.5, v[148:149] op_sel_hi:[1,0,1]
	v_pk_fma_f32 v[118:119], v[118:119], 0.5, v[150:151] op_sel_hi:[1,0,1]
	v_pk_fma_f32 v[120:121], v[120:121], 0.5, v[152:153] op_sel_hi:[1,0,1]
	v_pk_fma_f32 v[122:123], v[122:123], 0.5, v[154:155] op_sel_hi:[1,0,1]
	v_pk_fma_f32 v[124:125], v[124:125], 0.5, v[156:157] op_sel_hi:[1,0,1]
	v_pk_fma_f32 v[126:127], v[126:127], 0.5, v[158:159] op_sel_hi:[1,0,1]
	v_pk_fma_f32 v[128:129], v[128:129], 0.5, v[160:161] op_sel_hi:[1,0,1]
	v_pk_fma_f32 v[98:99], v[98:99], 0.5, v[162:163] op_sel_hi:[1,0,1]
	v_pk_fma_f32 v[100:101], v[100:101], 0.5, v[164:165] op_sel_hi:[1,0,1]
	v_pk_fma_f32 v[102:103], v[102:103], 0.5, v[166:167] op_sel_hi:[1,0,1]
	v_pk_fma_f32 v[104:105], v[104:105], 0.5, v[168:169] op_sel_hi:[1,0,1]
	v_pk_fma_f32 v[106:107], v[106:107], 0.5, v[170:171] op_sel_hi:[1,0,1]
	v_pk_fma_f32 v[108:109], v[108:109], 0.5, v[172:173] op_sel_hi:[1,0,1]
	v_pk_fma_f32 v[110:111], v[110:111], 0.5, v[174:175] op_sel_hi:[1,0,1]
	v_pk_fma_f32 v[112:113], v[112:113], 0.5, v[176:177] op_sel_hi:[1,0,1]
	global_store_dwordx4 v[130:131], v[114:117], off
	global_store_dwordx4 v[130:131], v[118:121], off offset:32
	global_store_dwordx4 v[130:131], v[122:125], off offset:64
	global_store_dwordx4 v[130:131], v[126:129], off offset:96
	global_store_dwordx4 v[130:131], v[98:101], off offset:128
	global_store_dwordx4 v[130:131], v[102:105], off offset:160
	global_store_dwordx4 v[130:131], v[106:109], off offset:192
	global_store_dwordx4 v[130:131], v[110:113], off offset:224
	global_load_dwordx4 v[146:149], v[142:143], off
	global_load_dwordx4 v[150:153], v[142:143], off offset:32
	global_load_dwordx4 v[154:157], v[142:143], off offset:64
	global_load_dwordx4 v[158:161], v[142:143], off offset:96
	global_load_dwordx4 v[162:165], v[142:143], off offset:128
	global_load_dwordx4 v[166:169], v[142:143], off offset:160
	global_load_dwordx4 v[170:173], v[142:143], off offset:192
	global_load_dwordx4 v[174:177], v[142:143], off offset:224
	s_waitcnt vmcnt(16)
; DI void phase_gemm_resid(const bf16_t* __restrict__ A, int K, const bf16_t* __restrict__ Bf, const float* xsrc, float* x,
;                          float scale, char* lds) {
;     ...
; #pragma unroll
;     for (int mi = 0; mi < 4; ++mi)
; #pragma unroll
;       for (int ni = 0; ni < 2; ++ni) {
;         float4 xs[4];
;         const size_t base = (size_t)(mt * 128 + 32 * mi + l31) * 1024 + nt * 256 + 64 * w + 32 * ni + 4 * h2;
; #pragma unroll
;         for (int g = 0; g < 4; ++g) xs[g] = *(const float4*)(xsrc + base + 8 * g);
; #pragma unroll
;         for (int g = 0; g < 4; ++g) {
;           float4 o;
;           o.x = xs[g].x + scale * a0[mi][ni][4 * g];
;           o.y = xs[g].y + scale * a0[mi][ni][4 * g + 1];
;           o.z = xs[g].z + scale * a0[mi][ni][4 * g + 2];
;           o.w = xs[g].w + scale * a0[mi][ni][4 * g + 3];
;           *(float4*)(x + base + 8 * g) = o;
;         }
;       }
	v_pk_fma_f32 v[82:83], v[82:83], 0.5, v[178:179] op_sel_hi:[1,0,1]
	v_pk_fma_f32 v[84:85], v[84:85], 0.5, v[180:181] op_sel_hi:[1,0,1]
	v_pk_fma_f32 v[86:87], v[86:87], 0.5, v[182:183] op_sel_hi:[1,0,1]
	v_pk_fma_f32 v[88:89], v[88:89], 0.5, v[184:185] op_sel_hi:[1,0,1]
	v_pk_fma_f32 v[90:91], v[90:91], 0.5, v[186:187] op_sel_hi:[1,0,1]
	v_pk_fma_f32 v[92:93], v[92:93], 0.5, v[188:189] op_sel_hi:[1,0,1]
	v_pk_fma_f32 v[94:95], v[94:95], 0.5, v[190:191] op_sel_hi:[1,0,1]
	v_pk_fma_f32 v[96:97], v[96:97], 0.5, v[192:193] op_sel_hi:[1,0,1]
	v_pk_fma_f32 v[66:67], v[66:67], 0.5, v[194:195] op_sel_hi:[1,0,1]
	v_pk_fma_f32 v[68:69], v[68:69], 0.5, v[196:197] op_sel_hi:[1,0,1]
	v_pk_fma_f32 v[70:71], v[70:71], 0.5, v[198:199] op_sel_hi:[1,0,1]
	v_pk_fma_f32 v[72:73], v[72:73], 0.5, v[200:201] op_sel_hi:[1,0,1]
	v_pk_fma_f32 v[74:75], v[74:75], 0.5, v[202:203] op_sel_hi:[1,0,1]
	v_pk_fma_f32 v[76:77], v[76:77], 0.5, v[204:205] op_sel_hi:[1,0,1]
	v_pk_fma_f32 v[78:79], v[78:79], 0.5, v[206:207] op_sel_hi:[1,0,1]
	v_pk_fma_f32 v[80:81], v[80:81], 0.5, v[208:209] op_sel_hi:[1,0,1]
	global_store_dwordx4 v[140:141], v[82:85], off
	global_store_dwordx4 v[140:141], v[86:89], off offset:32
	global_store_dwordx4 v[140:141], v[90:93], off offset:64
	global_store_dwordx4 v[140:141], v[94:97], off offset:96
	global_store_dwordx4 v[140:141], v[66:69], off offset:128
	global_store_dwordx4 v[140:141], v[70:73], off offset:160
	global_store_dwordx4 v[140:141], v[74:77], off offset:192
	global_store_dwordx4 v[140:141], v[78:81], off offset:224
	global_load_dwordx4 v[178:181], v[144:145], off
	global_load_dwordx4 v[182:185], v[144:145], off offset:32
	global_load_dwordx4 v[186:189], v[144:145], off offset:64
	global_load_dwordx4 v[190:193], v[144:145], off offset:96
	global_load_dwordx4 v[194:197], v[144:145], off offset:128
	global_load_dwordx4 v[198:201], v[144:145], off offset:160
	global_load_dwordx4 v[202:205], v[144:145], off offset:192
	global_load_dwordx4 v[206:209], v[144:145], off offset:224
	s_waitcnt vmcnt(16)
	v_pk_fma_f32 v[50:51], v[50:51], 0.5, v[146:147] op_sel_hi:[1,0,1]
	v_pk_fma_f32 v[52:53], v[52:53], 0.5, v[148:149] op_sel_hi:[1,0,1]
	v_pk_fma_f32 v[54:55], v[54:55], 0.5, v[150:151] op_sel_hi:[1,0,1]
	v_pk_fma_f32 v[56:57], v[56:57], 0.5, v[152:153] op_sel_hi:[1,0,1]
	v_pk_fma_f32 v[58:59], v[58:59], 0.5, v[154:155] op_sel_hi:[1,0,1]
	v_pk_fma_f32 v[60:61], v[60:61], 0.5, v[156:157] op_sel_hi:[1,0,1]
	v_pk_fma_f32 v[62:63], v[62:63], 0.5, v[158:159] op_sel_hi:[1,0,1]
	v_pk_fma_f32 v[64:65], v[64:65], 0.5, v[160:161] op_sel_hi:[1,0,1]
	v_pk_fma_f32 v[34:35], v[34:35], 0.5, v[162:163] op_sel_hi:[1,0,1]
	v_pk_fma_f32 v[36:37], v[36:37], 0.5, v[164:165] op_sel_hi:[1,0,1]
	v_pk_fma_f32 v[38:39], v[38:39], 0.5, v[166:167] op_sel_hi:[1,0,1]
	v_pk_fma_f32 v[40:41], v[40:41], 0.5, v[168:169] op_sel_hi:[1,0,1]
	v_pk_fma_f32 v[42:43], v[42:43], 0.5, v[170:171] op_sel_hi:[1,0,1]
	v_pk_fma_f32 v[44:45], v[44:45], 0.5, v[172:173] op_sel_hi:[1,0,1]
	v_pk_fma_f32 v[46:47], v[46:47], 0.5, v[174:175] op_sel_hi:[1,0,1]
	v_pk_fma_f32 v[48:49], v[48:49], 0.5, v[176:177] op_sel_hi:[1,0,1]
	global_store_dwordx4 v[142:143], v[50:53], off
	global_store_dwordx4 v[142:143], v[54:57], off offset:32
	global_store_dwordx4 v[142:143], v[58:61], off offset:64
	global_store_dwordx4 v[142:143], v[62:65], off offset:96
	global_store_dwordx4 v[142:143], v[34:37], off offset:128
	global_store_dwordx4 v[142:143], v[38:41], off offset:160
	global_store_dwordx4 v[142:143], v[42:45], off offset:192
	global_store_dwordx4 v[142:143], v[46:49], off offset:224
	s_waitcnt vmcnt(8)
	v_pk_fma_f32 v[18:19], v[18:19], 0.5, v[178:179] op_sel_hi:[1,0,1]
	v_pk_fma_f32 v[20:21], v[20:21], 0.5, v[180:181] op_sel_hi:[1,0,1]
	v_pk_fma_f32 v[22:23], v[22:23], 0.5, v[182:183] op_sel_hi:[1,0,1]
	v_pk_fma_f32 v[24:25], v[24:25], 0.5, v[184:185] op_sel_hi:[1,0,1]
	v_pk_fma_f32 v[26:27], v[26:27], 0.5, v[186:187] op_sel_hi:[1,0,1]
	v_pk_fma_f32 v[28:29], v[28:29], 0.5, v[188:189] op_sel_hi:[1,0,1]
	v_pk_fma_f32 v[30:31], v[30:31], 0.5, v[190:191] op_sel_hi:[1,0,1]
	v_pk_fma_f32 v[32:33], v[32:33], 0.5, v[192:193] op_sel_hi:[1,0,1]
	v_pk_fma_f32 v[2:3], v[2:3], 0.5, v[194:195] op_sel_hi:[1,0,1]
	v_pk_fma_f32 v[4:5], v[4:5], 0.5, v[196:197] op_sel_hi:[1,0,1]
	v_pk_fma_f32 v[6:7], v[6:7], 0.5, v[198:199] op_sel_hi:[1,0,1]
	v_pk_fma_f32 v[8:9], v[8:9], 0.5, v[200:201] op_sel_hi:[1,0,1]
	v_pk_fma_f32 v[10:11], v[10:11], 0.5, v[202:203] op_sel_hi:[1,0,1]
	v_pk_fma_f32 v[12:13], v[12:13], 0.5, v[204:205] op_sel_hi:[1,0,1]
	v_pk_fma_f32 v[14:15], v[14:15], 0.5, v[206:207] op_sel_hi:[1,0,1]
	v_pk_fma_f32 v[16:17], v[16:17], 0.5, v[208:209] op_sel_hi:[1,0,1]
	global_store_dwordx4 v[144:145], v[18:21], off
	global_store_dwordx4 v[144:145], v[22:25], off offset:32
	global_store_dwordx4 v[144:145], v[26:29], off offset:64
	global_store_dwordx4 v[144:145], v[30:33], off offset:96
	global_store_dwordx4 v[144:145], v[2:5], off offset:128
	global_store_dwordx4 v[144:145], v[6:9], off offset:160
	global_store_dwordx4 v[144:145], v[10:13], off offset:192
	global_store_dwordx4 v[144:145], v[14:17], off offset:224
	s_cbranch_scc0 .LBB0_1180

; DI unsigned pack2(float a, float b) { f2_t v = {a, b}; return __builtin_bit_cast(unsigned, __builtin_convertvector(v, bf2_t)); }
; DI void phase_norm(const float* __restrict__ x, const float* __restrict__ g, bf16_t* __restrict__ dst,
;                            const float* __restrict__ psrc, bf16_t* __restrict__ pdst) {
;     ...
;   for (int r = blockIdx.x * 4 + wave; r < TG; r += gridDim.x * 4) {
;     const float4* xr = (const float4*)(x + (size_t)r * 1024);
;     float4 v[4];
;     float ss = 0.f;
; #pragma unroll
;     for (int i = 0; i < 4; ++i) { v[i] = xr[lane + 64 * i]; ss += v[i].x * v[i].x + v[i].y * v[i].y + v[i].z * v[i].z + v[i].w * v[i].w; }
;     ss = wave_sum(ss);
;     const float rs = rsqrtf(ss * (1.f / 1024.f) + EPS);
; #pragma unroll
;     for (int i = 0; i < 4; ++i) {
;       const float4 gg = ((const float4*)g)[lane + 64 * i];
;       u32x2 o; o.x = pack2(v[i].x * rs * gg.x, v[i].y * rs * gg.y); o.y = pack2(v[i].z * rs * gg.z, v[i].w * rs * gg.w);
;       ((u32x2*)(dst + (size_t)r * 1024))[lane + 64 * i] = o;
;     }
;     if (psrc) {
;       const float4 pv = ((const float4*)(psrc + (size_t)r * 256))[lane];
;       u32x2 o; o.x = pack2(pv.x, pv.y); o.y = pack2(pv.z, pv.w);
;       ((u32x2*)(pdst + (size_t)r * 256))[lane] = o;
;     }
.LBB0_1234:
	v_ashrrev_i32_e32 v19, 31, v18
	v_lshlrev_b64 v[34:35], 12, v[18:19]
	v_lshl_add_u64 v[46:47], v[24:25], 0, v[34:35]
	v_lshlrev_b64 v[38:39], 11, v[18:19]
	global_load_dwordx4 v[34:37], v[46:47], off
	v_lshl_add_u64 v[50:51], v[26:27], 0, v[38:39]
	global_load_dwordx4 v[38:41], v[46:47], off offset:1024
	global_load_dwordx4 v[90:93], v[46:47], off offset:2048
	global_load_dwordx4 v[94:97], v[46:47], off offset:3072
	s_waitcnt vmcnt(3)
	v_mov_b32_e32 v52, v35
	v_mov_b32_e32 v48, v34
	s_waitcnt vmcnt(2)
	v_mov_b32_e32 v53, v39
	v_mov_b32_e32 v49, v38
	v_pk_mul_f32 v[52:53], v[52:53], v[52:53]
	v_mov_b32_e32 v42, v36
	v_mov_b32_e32 v43, v40
	v_pk_fma_f32 v[48:49], v[48:49], v[48:49], v[52:53]
	v_mov_b32_e32 v44, v37
	v_mov_b32_e32 v45, v41
	v_pk_fma_f32 v[42:43], v[42:43], v[42:43], v[48:49]
	s_nop 0
	v_pk_fma_f32 v[52:53], v[44:45], v[44:45], v[42:43]
	v_add_f32_e32 v0, v52, v53
	s_waitcnt vmcnt(1)
	v_mov_b32_e32 v60, v91
	s_waitcnt vmcnt(0)
	v_mov_b32_e32 v61, v95
	v_mov_b32_e32 v58, v90
	v_mov_b32_e32 v59, v94
	v_pk_mul_f32 v[60:61], v[60:61], v[60:61]
	v_mov_b32_e32 v54, v92
	v_mov_b32_e32 v55, v96
	v_pk_fma_f32 v[58:59], v[58:59], v[58:59], v[60:61]
	v_mov_b32_e32 v56, v93
	v_mov_b32_e32 v57, v97
	v_pk_fma_f32 v[54:55], v[54:55], v[54:55], v[58:59]
	s_nop 0
	v_pk_fma_f32 v[54:55], v[56:57], v[56:57], v[54:55]
	s_nop 0
	v_add_f32_e32 v0, v0, v54
	v_add_f32_e32 v0, v0, v55
	ds_bpermute_b32 v52, v28, v0
	s_waitcnt lgkmcnt(0)
	v_add_f32_e32 v0, v0, v52
	ds_bpermute_b32 v52, v29, v0
	s_waitcnt lgkmcnt(0)
	v_add_f32_e32 v0, v0, v52
	ds_bpermute_b32 v52, v30, v0
	s_waitcnt lgkmcnt(0)
	v_add_f32_e32 v0, v0, v52
	ds_bpermute_b32 v52, v31, v0
	s_waitcnt lgkmcnt(0)
	v_add_f32_e32 v0, v0, v52
	ds_bpermute_b32 v52, v32, v0
	s_waitcnt lgkmcnt(0)
	v_add_f32_e32 v0, v0, v52
	ds_bpermute_b32 v52, v33, v0
	s_waitcnt lgkmcnt(0)
	v_add_f32_e32 v0, v0, v52
	v_fmamk_f32 v0, v0, 0x3a800000, v216
	v_cmp_gt_f32_e32 vcc, s15, v0
	v_mul_f32_e32 v52, 0x4b800000, v0
	s_nop 0
	v_cndmask_b32_e32 v0, v0, v52, vcc
	v_rsq_f32_e32 v0, v0
	s_nop 0
	v_mul_f32_e32 v52, 0x45800000, v0
	v_cndmask_b32_e32 v0, v0, v52, vcc
	v_pk_mul_f32 v[34:35], v[34:35], v[0:1] op_sel_hi:[1,0]
	v_pk_mul_f32 v[36:37], v[36:37], v[0:1] op_sel_hi:[1,0]
	v_pk_mul_f32 v[34:35], v[2:3], v[34:35]
	v_pk_mul_f32 v[36:37], v[4:5], v[36:37]
	v_cvt_pk_bf16_f32 v34, v34, v35
	v_cvt_pk_bf16_f32 v35, v36, v37
	global_store_dwordx2 v[50:51], v[34:35], off
	v_pk_mul_f32 v[34:35], v[38:39], v[0:1] op_sel_hi:[1,0]
	v_pk_mul_f32 v[36:37], v[40:41], v[0:1] op_sel_hi:[1,0]
	v_pk_mul_f32 v[34:35], v[6:7], v[34:35]
	v_pk_mul_f32 v[36:37], v[8:9], v[36:37]
	v_cvt_pk_bf16_f32 v34, v34, v35
	v_cvt_pk_bf16_f32 v35, v36, v37
	global_store_dwordx2 v[50:51], v[34:35], off offset:512
	v_pk_mul_f32 v[34:35], v[90:91], v[0:1] op_sel_hi:[1,0]
	v_pk_mul_f32 v[36:37], v[92:93], v[0:1] op_sel_hi:[1,0]
	v_pk_mul_f32 v[34:35], v[10:11], v[34:35]
	v_pk_mul_f32 v[36:37], v[12:13], v[36:37]
	v_cvt_pk_bf16_f32 v34, v34, v35
	v_cvt_pk_bf16_f32 v35, v36, v37
	global_store_dwordx2 v[50:51], v[34:35], off offset:1024
	v_pk_mul_f32 v[34:35], v[94:95], v[0:1] op_sel_hi:[1,0]
	v_pk_mul_f32 v[36:37], v[96:97], v[0:1] op_sel_hi:[1,0]
	v_pk_mul_f32 v[34:35], v[14:15], v[34:35]
	v_pk_mul_f32 v[36:37], v[16:17], v[36:37]
	v_cvt_pk_bf16_f32 v34, v34, v35
	v_cvt_pk_bf16_f32 v35, v36, v37
	s_andn2_b64 vcc, exec, s[24:25]
	global_store_dwordx2 v[50:51], v[34:35], off offset:1536
	s_cbranch_vccnz .LBB0_1233
	v_lshlrev_b64 v[34:35], 10, v[18:19]
	v_lshl_add_u64 v[34:35], v[20:21], 0, v[34:35]
	global_load_dwordx4 v[34:37], v[34:35], off
	s_waitcnt vmcnt(0)
	v_cvt_pk_bf16_f32 v34, v34, v35
	v_cvt_pk_bf16_f32 v35, v36, v37
	v_lshlrev_b64 v[36:37], 9, v[18:19]
	v_lshl_add_u64 v[36:37], v[22:23], 0, v[36:37]
	global_store_dwordx2 v[36:37], v[34:35], off
	s_branch .LBB0_1233
